# s_setprio 1/0 flips around MFMA runs in all GEMM K-loops (on top of v19)
# speedup vs baseline: 1.0365x; 1.0011x over previous
.LBB0_121:
	v_lshl_add_u32 v83, s24, 14, v80
	v_add_u32_e32 v90, 0x1000, v83
	v_readfirstlane_b32 s26, v83
	s_waitcnt vmcnt(4) lgkmcnt(0)
	s_barrier
	v_add_u32_e32 v89, 0x2000, v83
	s_mov_b32 m0, s26
	v_readfirstlane_b32 s26, v90
	v_lshl_add_u64 v[74:75], v[70:71], 0, s[10:11]
	v_add_u32_e32 v88, 0x3000, v83
	global_load_lds_dwordx4 v[68:69], off
	s_mov_b32 m0, s26
	v_readfirstlane_b32 s26, v89
	v_lshl_add_u64 v[84:85], v[74:75], 0, s[36:37]
	global_load_lds_dwordx4 v[66:67], off
	s_mov_b32 m0, s26
	v_readfirstlane_b32 s26, v88
	global_load_lds_dwordx4 v[84:85], off
	s_mov_b32 m0, s26
	s_lshl_b32 s26, s25, 14
	v_lshl_add_u64 v[86:87], v[74:75], 0, s[40:41]
	s_add_i32 s26, s26, 0
	global_load_lds_dwordx4 v[86:87], off
	v_add3_u32 v83, s26, v82, v0
	ds_read_b128 v[84:87], v83 offset:8192
	ds_read_b128 v[88:91], v83 offset:9216
	ds_read_b128 v[92:95], v83 offset:10240
	ds_read_b128 v[96:99], v83 offset:11264
	v_add3_u32 v83, s26, v81, v0
	s_add_i32 s26, s25, 1
	ds_read_b128 v[100:103], v83
	ds_read_b128 v[104:107], v83 offset:1024
	ds_read_b128 v[108:111], v83 offset:2048
	ds_read_b128 v[112:115], v83 offset:3072
	s_cmp_lg_u32 s25, 2
	s_cselect_b32 s25, s26, 0
	s_add_i32 s26, s24, 1
	s_cmp_lg_u32 s24, 2
	s_cselect_b32 s24, s26, 0
	v_lshl_add_u32 v83, s24, 14, v80
	s_waitcnt lgkmcnt(0)
	s_setprio 1
	v_mfma_f32_16x16x32_bf16 v[62:65], v[84:87], v[100:103], v[62:65]
	v_readfirstlane_b32 s26, v83
	v_lshl_add_u64 v[78:79], v[68:69], 0, 64
	s_setprio 0
	s_waitcnt vmcnt(4) lgkmcnt(0)
	s_setprio 1
	v_mfma_f32_16x16x32_bf16 v[46:49], v[84:87], v[104:107], v[46:49]
	s_setprio 0
	s_barrier
	s_mov_b32 m0, s26
	s_setprio 1
	v_mfma_f32_16x16x32_bf16 v[30:33], v[84:87], v[108:111], v[30:33]
	v_lshl_add_u64 v[76:77], v[66:67], 0, 64
	global_load_lds_dwordx4 v[78:79], off
	v_mfma_f32_16x16x32_bf16 v[14:17], v[84:87], v[112:115], v[14:17]
	v_add_u32_e32 v86, 0x1000, v83
	v_add_u32_e32 v85, 0x2000, v83
	v_readfirstlane_b32 s26, v86
	v_add_u32_e32 v84, 0x3000, v83
	s_mov_b32 m0, s26
	v_readfirstlane_b32 s26, v85
	v_lshl_add_u64 v[72:73], v[74:75], 0, s[58:59]
	v_lshl_add_u64 v[74:75], v[74:75], 0, s[82:83]
	global_load_lds_dwordx4 v[76:77], off
	s_mov_b32 m0, s26
	v_readfirstlane_b32 s26, v84
	global_load_lds_dwordx4 v[74:75], off
	s_mov_b32 m0, s26
	s_lshl_b32 s26, s25, 14
	global_load_lds_dwordx4 v[72:73], off
	s_add_i32 s26, s26, 0
	v_add3_u32 v83, s26, v82, v0
	v_mfma_f32_16x16x32_bf16 v[58:61], v[88:91], v[100:103], v[58:61]
	v_lshl_add_u64 v[68:69], v[68:69], 0, s[78:79]
	v_lshl_add_u64 v[66:67], v[66:67], 0, s[78:79]
	v_mfma_f32_16x16x32_bf16 v[42:45], v[88:91], v[104:107], v[42:45]
	v_mfma_f32_16x16x32_bf16 v[26:29], v[88:91], v[108:111], v[26:29]
	v_mfma_f32_16x16x32_bf16 v[10:13], v[88:91], v[112:115], v[10:13]
	s_setprio 0
	ds_read_b128 v[72:75], v83 offset:8192
	ds_read_b128 v[76:79], v83 offset:9216
	ds_read_b128 v[84:87], v83 offset:10240
	ds_read_b128 v[88:91], v83 offset:11264
	v_add3_u32 v83, s26, v81, v0
	s_add_i32 s26, s25, 1
	s_setprio 1
	v_mfma_f32_16x16x32_bf16 v[54:57], v[92:95], v[100:103], v[54:57]
	s_cmp_lg_u32 s25, 2
	s_cselect_b32 s25, s26, 0
	s_add_i32 s26, s24, 1
	v_mfma_f32_16x16x32_bf16 v[50:53], v[96:99], v[100:103], v[50:53]
	s_cmp_lg_u32 s24, 2
	s_cselect_b32 s24, s26, 0
	s_add_u32 s10, s10, 0x80
	v_mfma_f32_16x16x32_bf16 v[38:41], v[92:95], v[104:107], v[38:41]
	s_addc_u32 s11, s11, 0
	s_cmpk_eq_i32 s10, 0x1580
	v_mfma_f32_16x16x32_bf16 v[34:37], v[96:99], v[104:107], v[34:37]
	v_mfma_f32_16x16x32_bf16 v[22:25], v[92:95], v[108:111], v[22:25]
	v_mfma_f32_16x16x32_bf16 v[18:21], v[96:99], v[108:111], v[18:21]
	v_mfma_f32_16x16x32_bf16 v[6:9], v[92:95], v[112:115], v[6:9]
	v_mfma_f32_16x16x32_bf16 v[2:5], v[96:99], v[112:115], v[2:5]
	s_setprio 0
	ds_read_b128 v[92:95], v83
	ds_read_b128 v[96:99], v83 offset:1024
	ds_read_b128 v[100:103], v83 offset:2048
	ds_read_b128 v[104:107], v83 offset:3072
	s_waitcnt lgkmcnt(0)
	s_setprio 1
	v_mfma_f32_16x16x32_bf16 v[62:65], v[72:75], v[92:95], v[62:65]
	v_mfma_f32_16x16x32_bf16 v[58:61], v[76:79], v[92:95], v[58:61]
	v_mfma_f32_16x16x32_bf16 v[54:57], v[84:87], v[92:95], v[54:57]
	v_mfma_f32_16x16x32_bf16 v[50:53], v[88:91], v[92:95], v[50:53]
	v_mfma_f32_16x16x32_bf16 v[46:49], v[72:75], v[96:99], v[46:49]
	v_mfma_f32_16x16x32_bf16 v[42:45], v[76:79], v[96:99], v[42:45]
	v_mfma_f32_16x16x32_bf16 v[38:41], v[84:87], v[96:99], v[38:41]
	v_mfma_f32_16x16x32_bf16 v[34:37], v[88:91], v[96:99], v[34:37]
	v_mfma_f32_16x16x32_bf16 v[30:33], v[72:75], v[100:103], v[30:33]
	v_mfma_f32_16x16x32_bf16 v[26:29], v[76:79], v[100:103], v[26:29]
	v_mfma_f32_16x16x32_bf16 v[22:25], v[84:87], v[100:103], v[22:25]
	v_mfma_f32_16x16x32_bf16 v[18:21], v[88:91], v[100:103], v[18:21]
	v_mfma_f32_16x16x32_bf16 v[14:17], v[72:75], v[104:107], v[14:17]
	v_mfma_f32_16x16x32_bf16 v[10:13], v[76:79], v[104:107], v[10:13]
	v_mfma_f32_16x16x32_bf16 v[6:9], v[84:87], v[104:107], v[6:9]
	v_mfma_f32_16x16x32_bf16 v[2:5], v[88:91], v[104:107], v[2:5]
	s_setprio 0
	s_cbranch_scc0 .LBB0_121
	s_waitcnt vmcnt(4) lgkmcnt(0)
	s_barrier
	v_add3_u32 v98, 0, v82, v0
	v_add3_u32 v0, 0, v81, v0
	ds_read_b128 v[66:69], v98 offset:40960
	ds_read_b128 v[70:73], v98 offset:41984
	ds_read_b128 v[74:77], v98 offset:43008
	ds_read_b128 v[82:85], v98 offset:44032
	ds_read_b128 v[78:81], v0 offset:32768
	ds_read_b128 v[86:89], v0 offset:33792
	ds_read_b128 v[90:93], v0 offset:34816
	ds_read_b128 v[94:97], v0 offset:35840
	s_waitcnt vmcnt(0) lgkmcnt(0)
	s_barrier
	s_waitcnt lgkmcnt(0)
	v_mfma_f32_16x16x32_bf16 v[62:65], v[66:69], v[78:81], v[62:65]
	s_lshl_b64 s[10:11], s[2:3], 11
	s_add_u32 s2, s19, s10
	s_addc_u32 s11, s20, s11
	v_mfma_f32_16x16x32_bf16 v[58:61], v[70:73], v[78:81], v[58:61]
	s_lshl_b32 s10, s13, 1
	s_add_u32 s10, s2, s10
	s_mov_b32 s2, 0xfffffc0
	v_mfma_f32_16x16x32_bf16 v[54:57], v[74:77], v[78:81], v[54:57]
	s_addc_u32 s11, s11, 0
	s_mov_b64 s[24:25], 0x3000
	v_mfma_f32_16x16x32_bf16 v[50:53], v[82:85], v[78:81], v[50:53]
	v_mfma_f32_16x16x32_bf16 v[46:49], v[66:69], v[86:89], v[46:49]
	v_mfma_f32_16x16x32_bf16 v[42:45], v[70:73], v[86:89], v[42:45]
	v_mfma_f32_16x16x32_bf16 v[38:41], v[74:77], v[86:89], v[38:41]
	v_mfma_f32_16x16x32_bf16 v[34:37], v[82:85], v[86:89], v[34:37]
	v_mfma_f32_16x16x32_bf16 v[30:33], v[66:69], v[90:93], v[30:33]
	v_mfma_f32_16x16x32_bf16 v[26:29], v[70:73], v[90:93], v[26:29]
	v_mfma_f32_16x16x32_bf16 v[22:25], v[74:77], v[90:93], v[22:25]
	v_mfma_f32_16x16x32_bf16 v[18:21], v[82:85], v[90:93], v[18:21]
	v_mfma_f32_16x16x32_bf16 v[14:17], v[66:69], v[94:97], v[14:17]
	v_mfma_f32_16x16x32_bf16 v[10:13], v[70:73], v[94:97], v[10:13]
	v_mfma_f32_16x16x32_bf16 v[6:9], v[74:77], v[94:97], v[6:9]
	v_mfma_f32_16x16x32_bf16 v[2:5], v[82:85], v[94:97], v[2:5]
	ds_read_b128 v[66:69], v98 offset:8192
	ds_read_b128 v[70:73], v98 offset:9216
	ds_read_b128 v[74:77], v98 offset:10240
	ds_read_b128 v[78:81], v98 offset:11264
	ds_read_b128 v[82:85], v0
	ds_read_b128 v[86:89], v0 offset:1024
	ds_read_b128 v[90:93], v0 offset:2048
	ds_read_b128 v[94:97], v0 offset:3072
	s_waitcnt vmcnt(0) lgkmcnt(0)
	s_barrier
	v_mfma_f32_16x16x32_bf16 v[62:65], v[66:69], v[82:85], v[62:65]
	v_mfma_f32_16x16x32_bf16 v[58:61], v[70:73], v[82:85], v[58:61]
	v_mfma_f32_16x16x32_bf16 v[54:57], v[74:77], v[82:85], v[54:57]
	s_nop 5
	v_cvt_pk_bf16_f32 v62, v62, v63
	v_cvt_pk_bf16_f32 v63, v64, v65
	v_cvt_pk_bf16_f32 v58, v58, v59
	v_mfma_f32_16x16x32_bf16 v[50:53], v[78:81], v[82:85], v[50:53]
	v_cvt_pk_bf16_f32 v59, v60, v61
	v_cvt_pk_bf16_f32 v54, v54, v55
	v_cvt_pk_bf16_f32 v55, v56, v57
	v_mfma_f32_16x16x32_bf16 v[46:49], v[66:69], v[86:89], v[46:49]
	v_mfma_f32_16x16x32_bf16 v[30:33], v[66:69], v[90:93], v[30:33]
	s_nop 2
	v_cvt_pk_bf16_f32 v50, v50, v51
	v_cvt_pk_bf16_f32 v51, v52, v53
	s_nop 1
	v_cvt_pk_bf16_f32 v46, v46, v47
	v_mfma_f32_16x16x32_bf16 v[14:17], v[66:69], v[94:97], v[14:17]
	v_mov_b32_e32 v66, v196
	v_cvt_pk_bf16_f32 v47, v48, v49
	v_mfma_f32_16x16x32_bf16 v[42:45], v[70:73], v[86:89], v[42:45]
	v_and_b32_e32 v67, 15, v66
	v_lshrrev_b32_e32 v68, 1, v66
	v_and_b32_e32 v0, 64, v66
	v_mfma_f32_16x16x32_bf16 v[26:29], v[70:73], v[90:93], v[26:29]
	v_and_or_b32 v69, v68, s2, v67
	v_lshl_add_u32 v0, v0, 1, 0
	v_and_b32_e32 v68, 24, v68
	v_mfma_f32_16x16x32_bf16 v[10:13], v[70:73], v[94:97], v[10:13]
	v_mul_lo_u32 v69, v69, s30
	v_add3_u32 v0, v0, v68, v69
	ds_write2_b64 v0, v[62:63], v[58:59] offset1:4
	v_mfma_f32_16x16x32_bf16 v[6:9], v[74:77], v[94:97], v[6:9]
	ds_write2_b64 v0, v[54:55], v[50:51] offset0:8 offset1:12
	v_cvt_pk_bf16_f32 v42, v42, v43
	v_cvt_pk_bf16_f32 v43, v44, v45
	v_mfma_f32_16x16x32_bf16 v[2:5], v[78:81], v[94:97], v[2:5]
	v_add_u32_e32 v44, 0x1000, v0
	v_cvt_pk_bf16_f32 v26, v26, v27
	v_cvt_pk_bf16_f32 v27, v28, v29
	v_mfma_f32_16x16x32_bf16 v[38:41], v[74:77], v[86:89], v[38:41]
	v_add_u32_e32 v28, 0x2000, v0
	v_cvt_pk_bf16_f32 v14, v14, v15
	v_cvt_pk_bf16_f32 v15, v16, v17
	v_mfma_f32_16x16x32_bf16 v[34:37], v[78:81], v[86:89], v[34:37]
	v_cvt_pk_bf16_f32 v10, v10, v11
	v_cvt_pk_bf16_f32 v11, v12, v13
	v_add_u32_e32 v0, 0x3000, v0
	v_mfma_f32_16x16x32_bf16 v[22:25], v[74:77], v[90:93], v[22:25]
	v_cvt_pk_bf16_f32 v6, v6, v7
	v_cvt_pk_bf16_f32 v7, v8, v9
	v_cvt_pk_bf16_f32 v2, v2, v3
	v_mfma_f32_16x16x32_bf16 v[18:21], v[78:81], v[90:93], v[18:21]
	v_cvt_pk_bf16_f32 v3, v4, v5
	ds_write2_b64 v0, v[14:15], v[10:11] offset0:96 offset1:100
	ds_write2_b64 v0, v[6:7], v[2:3] offset0:104 offset1:108
	v_lshlrev_b32_e32 v0, 4, v67
	v_ashrrev_i32_e32 v2, 4, v66
	v_lshl_add_u64 v[6:7], s[10:11], 0, v[0:1]
	v_add_u32_e32 v0, 0, v0
	v_ashrrev_i32_e32 v3, 31, v2
	v_cvt_pk_bf16_f32 v38, v38, v39
	v_cvt_pk_bf16_f32 v39, v40, v41
	v_cvt_pk_bf16_f32 v34, v34, v35
	v_cvt_pk_bf16_f32 v35, v36, v37
	v_cvt_pk_bf16_f32 v30, v30, v31
	v_cvt_pk_bf16_f32 v31, v32, v33
	v_cvt_pk_bf16_f32 v22, v22, v23
	v_cvt_pk_bf16_f32 v23, v24, v25
	v_cvt_pk_bf16_f32 v18, v18, v19
	v_cvt_pk_bf16_f32 v19, v20, v21
	v_mad_u64_u32 v[4:5], s[10:11], v2, s30, v[0:1]
	v_lshlrev_b64 v[2:3], 11, v[2:3]
	ds_write2_b64 v44, v[46:47], v[42:43] offset0:32 offset1:36
	ds_write2_b64 v44, v[38:39], v[34:35] offset0:40 offset1:44
	ds_write2_b64 v28, v[30:31], v[26:27] offset0:64 offset1:68
	ds_write2_b64 v28, v[22:23], v[18:19] offset0:72 offset1:76
	s_waitcnt lgkmcnt(0)
	s_barrier
	v_lshl_add_u64 v[8:9], v[6:7], 0, v[2:3]
	ds_read_b128 v[2:5], v4
	s_waitcnt lgkmcnt(0)
	global_store_dwordx4 v[8:9], v[2:5], off
	s_nop 1
	v_add_u32_e32 v2, 0x100, v66
	v_ashrrev_i32_e32 v2, 4, v2
	v_ashrrev_i32_e32 v3, 31, v2
	v_mad_u64_u32 v[4:5], s[10:11], v2, s30, v[0:1]
	v_lshlrev_b64 v[2:3], 11, v[2:3]
	v_lshl_add_u64 v[8:9], v[6:7], 0, v[2:3]
	ds_read_b128 v[2:5], v4
	s_waitcnt lgkmcnt(0)
	global_store_dwordx4 v[8:9], v[2:5], off
	s_nop 1
	v_add_u32_e32 v2, 0x200, v66
	v_ashrrev_i32_e32 v2, 4, v2
	v_ashrrev_i32_e32 v3, 31, v2
	v_mad_u64_u32 v[4:5], s[10:11], v2, s30, v[0:1]
	v_lshlrev_b64 v[2:3], 11, v[2:3]
	v_lshl_add_u64 v[8:9], v[6:7], 0, v[2:3]
	ds_read_b128 v[2:5], v4
	s_waitcnt lgkmcnt(0)
	global_store_dwordx4 v[8:9], v[2:5], off
	s_nop 1
	v_add_u32_e32 v2, 0x300, v66
	v_ashrrev_i32_e32 v2, 4, v2
	v_ashrrev_i32_e32 v3, 31, v2
	v_mad_u64_u32 v[4:5], s[10:11], v2, s30, v[0:1]
	v_lshlrev_b64 v[2:3], 11, v[2:3]
	v_lshl_add_u64 v[8:9], v[6:7], 0, v[2:3]
	ds_read_b128 v[2:5], v4
	s_waitcnt lgkmcnt(0)
	global_store_dwordx4 v[8:9], v[2:5], off
	s_nop 1
	v_add_u32_e32 v2, 0x400, v66
	v_ashrrev_i32_e32 v2, 4, v2
	v_ashrrev_i32_e32 v3, 31, v2
	v_mad_u64_u32 v[4:5], s[10:11], v2, s30, v[0:1]
	v_lshlrev_b64 v[2:3], 11, v[2:3]
	v_lshl_add_u64 v[8:9], v[6:7], 0, v[2:3]
	ds_read_b128 v[2:5], v4
	s_waitcnt lgkmcnt(0)
	global_store_dwordx4 v[8:9], v[2:5], off
	s_nop 1
	v_add_u32_e32 v2, 0x500, v66
	v_ashrrev_i32_e32 v2, 4, v2
	v_ashrrev_i32_e32 v3, 31, v2
	v_mad_u64_u32 v[4:5], s[10:11], v2, s30, v[0:1]
	v_lshlrev_b64 v[2:3], 11, v[2:3]
	v_lshl_add_u64 v[8:9], v[6:7], 0, v[2:3]
	ds_read_b128 v[2:5], v4
	s_waitcnt lgkmcnt(0)
	global_store_dwordx4 v[8:9], v[2:5], off
	s_nop 1
	v_add_u32_e32 v2, 0x600, v66
	v_ashrrev_i32_e32 v2, 4, v2
	v_ashrrev_i32_e32 v3, 31, v2
	v_mad_u64_u32 v[4:5], s[10:11], v2, s30, v[0:1]
	v_lshlrev_b64 v[2:3], 11, v[2:3]
	v_lshl_add_u64 v[8:9], v[6:7], 0, v[2:3]
	ds_read_b128 v[2:5], v4
	s_waitcnt lgkmcnt(0)
	global_store_dwordx4 v[8:9], v[2:5], off
	s_nop 1
	v_add_u32_e32 v2, 0x700, v66
	v_ashrrev_i32_e32 v2, 4, v2
	v_ashrrev_i32_e32 v3, 31, v2
	v_mad_u64_u32 v[4:5], s[10:11], v2, s30, v[0:1]
	v_lshlrev_b64 v[2:3], 11, v[2:3]
	v_lshl_add_u64 v[6:7], v[6:7], 0, v[2:3]
	ds_read_b128 v[2:5], v4
	s_mov_b64 s[10:11], 0
	s_waitcnt lgkmcnt(0)
	global_store_dwordx4 v[6:7], v[2:5], off
	s_barrier

.LBB0_125:
	s_mul_i32 s26, s25, 0x6000
	v_add_u32_e32 v144, s26, v156
	v_add_u32_e32 v132, 0x1000, v144
	v_readfirstlane_b32 s26, v144
	s_waitcnt vmcnt(6) lgkmcnt(0)
	s_barrier
	s_mov_b32 m0, s26
	v_readfirstlane_b32 s26, v132
	v_add_u32_e32 v134, 0x2000, v144
	global_load_lds_dwordx4 v[148:149], off
	s_mov_b32 m0, s26
	v_readfirstlane_b32 s26, v134
	v_add_u32_e32 v136, 0x3000, v144
	global_load_lds_dwordx4 v[150:151], off
	s_mov_b32 m0, s26
	v_readfirstlane_b32 s26, v136
	v_add_u32_e32 v145, 0x4000, v144
	v_lshl_add_u64 v[138:139], v[154:155], 0, s[12:13]
	global_load_lds_dwordx4 v[152:153], off
	s_mov_b32 m0, s26
	v_readfirstlane_b32 s26, v145
	v_lshl_add_u64 v[142:143], v[138:139], 0, s[36:37]
	global_load_lds_dwordx4 v[146:147], off
	s_mov_b32 m0, s26
	v_lshl_add_u64 v[140:141], v[138:139], 0, s[40:41]
	global_load_lds_dwordx4 v[142:143], off
	v_add_u32_e32 v142, 0x5000, v144
	v_lshl_add_u64 v[130:131], v[148:149], 0, 64
	v_readfirstlane_b32 s26, v142
	s_mov_b32 m0, s26
	s_mul_i32 s26, s2, 0x6000
	s_add_i32 s26, s26, 0
	global_load_lds_dwordx4 v[140:141], off
	v_add3_u32 v159, s26, v157, v0
	ds_read_b128 v[142:145], v159 offset:16384
	ds_read_b128 v[160:163], v159 offset:17408
	ds_read_b128 v[164:167], v159 offset:18432
	ds_read_b128 v[168:171], v159 offset:19456
	v_add3_u32 v159, s26, v158, v0
	ds_read_b128 v[172:175], v159
	ds_read_b128 v[176:179], v159 offset:1024
	ds_read_b128 v[180:183], v159 offset:2048
	ds_read_b128 v[184:187], v159 offset:3072
	s_add_i32 s26, s2, 1
	s_waitcnt lgkmcnt(0)
	s_setprio 1
	v_mfma_f32_16x16x32_bf16 v[126:129], v[142:145], v[172:175], v[126:129]
	s_cmp_lg_u32 s2, 2
	s_cselect_b32 s2, s26, 0
	s_add_i32 s26, s25, 1
	v_mfma_f32_16x16x32_bf16 v[122:125], v[160:163], v[172:175], v[122:125]
	s_cmp_lg_u32 s25, 2
	s_cselect_b32 s25, s26, 0
	s_mul_i32 s26, s25, 0x6000
	v_mfma_f32_16x16x32_bf16 v[118:121], v[164:167], v[172:175], v[118:121]
	v_lshl_add_u64 v[132:133], v[150:151], 0, 64
	v_lshl_add_u64 v[134:135], v[152:153], 0, 64
	v_lshl_add_u64 v[136:137], v[146:147], 0, 64
	v_mfma_f32_16x16x32_bf16 v[114:117], v[168:171], v[172:175], v[114:117]
	v_lshl_add_u64 v[140:141], v[138:139], 0, s[82:83]
	v_lshl_add_u64 v[138:139], v[138:139], 0, s[58:59]
	v_lshl_add_u64 v[148:149], v[148:149], 0, s[78:79]
	v_mfma_f32_16x16x32_bf16 v[110:113], v[142:145], v[176:179], v[110:113]
	v_lshl_add_u64 v[150:151], v[150:151], 0, s[78:79]
	v_lshl_add_u64 v[152:153], v[152:153], 0, s[78:79]
	v_lshl_add_u64 v[146:147], v[146:147], 0, s[78:79]
	v_mfma_f32_16x16x32_bf16 v[106:109], v[160:163], v[176:179], v[106:109]
	v_mfma_f32_16x16x32_bf16 v[102:105], v[164:167], v[176:179], v[102:105]
	v_mfma_f32_16x16x32_bf16 v[98:101], v[168:171], v[176:179], v[98:101]
	v_mfma_f32_16x16x32_bf16 v[94:97], v[142:145], v[180:183], v[94:97]
	v_mfma_f32_16x16x32_bf16 v[90:93], v[160:163], v[180:183], v[90:93]
	v_mfma_f32_16x16x32_bf16 v[86:89], v[164:167], v[180:183], v[86:89]
	v_mfma_f32_16x16x32_bf16 v[82:85], v[168:171], v[180:183], v[82:85]
	v_mfma_f32_16x16x32_bf16 v[78:81], v[142:145], v[184:187], v[78:81]
	v_mfma_f32_16x16x32_bf16 v[74:77], v[160:163], v[184:187], v[74:77]
	v_mfma_f32_16x16x32_bf16 v[70:73], v[164:167], v[184:187], v[70:73]
	v_mfma_f32_16x16x32_bf16 v[66:69], v[168:171], v[184:187], v[66:69]
	s_setprio 0
	ds_read_b128 v[172:175], v159 offset:4096
	ds_read_b128 v[176:179], v159 offset:5120
	ds_read_b128 v[180:183], v159 offset:6144
	ds_read_b128 v[184:187], v159 offset:7168
	s_waitcnt vmcnt(6) lgkmcnt(0)
	s_barrier
	s_waitcnt lgkmcnt(0)
	s_setprio 1
	v_mfma_f32_16x16x32_bf16 v[62:65], v[142:145], v[172:175], v[62:65]
	s_setprio 0
	s_setprio 1
	v_mfma_f32_16x16x32_bf16 v[46:49], v[142:145], v[176:179], v[46:49]
	v_mfma_f32_16x16x32_bf16 v[30:33], v[142:145], v[180:183], v[30:33]
	v_mfma_f32_16x16x32_bf16 v[14:17], v[142:145], v[184:187], v[14:17]
	v_add_u32_e32 v142, s26, v156
	s_nop 0
	v_readfirstlane_b32 s26, v142
	s_mov_b32 m0, s26
	v_mfma_f32_16x16x32_bf16 v[58:61], v[160:163], v[172:175], v[58:61]
	global_load_lds_dwordx4 v[130:131], off
	v_add_u32_e32 v130, 0x1000, v142
	v_mfma_f32_16x16x32_bf16 v[54:57], v[164:167], v[172:175], v[54:57]
	v_readfirstlane_b32 s26, v130
	v_add_u32_e32 v130, 0x2000, v142
	s_mov_b32 m0, s26
	v_readfirstlane_b32 s26, v130
	v_add_u32_e32 v130, 0x3000, v142
	global_load_lds_dwordx4 v[132:133], off
	s_mov_b32 m0, s26
	v_readfirstlane_b32 s26, v130
	v_add_u32_e32 v130, 0x4000, v142
	global_load_lds_dwordx4 v[134:135], off
	s_mov_b32 m0, s26
	v_readfirstlane_b32 s26, v130
	v_add_u32_e32 v130, 0x5000, v142
	global_load_lds_dwordx4 v[136:137], off
	s_mov_b32 m0, s26
	v_readfirstlane_b32 s26, v130
	global_load_lds_dwordx4 v[140:141], off
	s_mov_b32 m0, s26
	s_mul_i32 s26, s2, 0x6000
	global_load_lds_dwordx4 v[138:139], off
	s_add_i32 s26, s26, 0
	v_add3_u32 v142, s26, v157, v0
	v_add3_u32 v159, s26, v158, v0
	v_mfma_f32_16x16x32_bf16 v[50:53], v[168:171], v[172:175], v[50:53]
	s_setprio 0
	ds_read_b128 v[130:133], v142 offset:16384
	ds_read_b128 v[134:137], v142 offset:17408
	ds_read_b128 v[138:141], v142 offset:18432
	ds_read_b128 v[142:145], v142 offset:19456
	s_add_i32 s26, s2, 1
	s_cmp_lg_u32 s2, 2
	s_setprio 1
	v_mfma_f32_16x16x32_bf16 v[42:45], v[160:163], v[176:179], v[42:45]
	s_cselect_b32 s2, s26, 0
	s_add_i32 s26, s25, 1
	s_cmp_lg_u32 s25, 2
	v_mfma_f32_16x16x32_bf16 v[38:41], v[164:167], v[176:179], v[38:41]
	s_cselect_b32 s25, s26, 0
	s_add_u32 s12, s12, 0x80
	s_addc_u32 s13, s13, 0
	v_mfma_f32_16x16x32_bf16 v[34:37], v[168:171], v[176:179], v[34:37]
	s_cmpk_eq_i32 s12, 0x1580
	v_mfma_f32_16x16x32_bf16 v[26:29], v[160:163], v[180:183], v[26:29]
	v_mfma_f32_16x16x32_bf16 v[22:25], v[164:167], v[180:183], v[22:25]
	v_mfma_f32_16x16x32_bf16 v[18:21], v[168:171], v[180:183], v[18:21]
	v_mfma_f32_16x16x32_bf16 v[10:13], v[160:163], v[184:187], v[10:13]
	v_mfma_f32_16x16x32_bf16 v[6:9], v[164:167], v[184:187], v[6:9]
	v_mfma_f32_16x16x32_bf16 v[2:5], v[168:171], v[184:187], v[2:5]
	s_setprio 0
	ds_read_b128 v[160:163], v159
	ds_read_b128 v[164:167], v159 offset:1024
	ds_read_b128 v[168:171], v159 offset:2048
	ds_read_b128 v[172:175], v159 offset:3072
	s_waitcnt lgkmcnt(0)
	s_setprio 1
	v_mfma_f32_16x16x32_bf16 v[126:129], v[130:133], v[160:163], v[126:129]
	v_mfma_f32_16x16x32_bf16 v[122:125], v[134:137], v[160:163], v[122:125]
	v_mfma_f32_16x16x32_bf16 v[118:121], v[138:141], v[160:163], v[118:121]
	v_mfma_f32_16x16x32_bf16 v[114:117], v[142:145], v[160:163], v[114:117]
	v_mfma_f32_16x16x32_bf16 v[110:113], v[130:133], v[164:167], v[110:113]
	v_mfma_f32_16x16x32_bf16 v[106:109], v[134:137], v[164:167], v[106:109]
	v_mfma_f32_16x16x32_bf16 v[102:105], v[138:141], v[164:167], v[102:105]
	v_mfma_f32_16x16x32_bf16 v[98:101], v[142:145], v[164:167], v[98:101]
	v_mfma_f32_16x16x32_bf16 v[94:97], v[130:133], v[168:171], v[94:97]
	v_mfma_f32_16x16x32_bf16 v[90:93], v[134:137], v[168:171], v[90:93]
	v_mfma_f32_16x16x32_bf16 v[86:89], v[138:141], v[168:171], v[86:89]
	v_mfma_f32_16x16x32_bf16 v[82:85], v[142:145], v[168:171], v[82:85]
	v_mfma_f32_16x16x32_bf16 v[78:81], v[130:133], v[172:175], v[78:81]
	v_mfma_f32_16x16x32_bf16 v[74:77], v[134:137], v[172:175], v[74:77]
	v_mfma_f32_16x16x32_bf16 v[70:73], v[138:141], v[172:175], v[70:73]
	v_mfma_f32_16x16x32_bf16 v[66:69], v[142:145], v[172:175], v[66:69]
	s_setprio 0
	ds_read_b128 v[160:163], v159 offset:4096
	ds_read_b128 v[164:167], v159 offset:5120
	ds_read_b128 v[168:171], v159 offset:6144
	ds_read_b128 v[172:175], v159 offset:7168
	s_waitcnt lgkmcnt(0)
	s_setprio 1
	v_mfma_f32_16x16x32_bf16 v[62:65], v[130:133], v[160:163], v[62:65]
	v_mfma_f32_16x16x32_bf16 v[58:61], v[134:137], v[160:163], v[58:61]
	v_mfma_f32_16x16x32_bf16 v[54:57], v[138:141], v[160:163], v[54:57]
	v_mfma_f32_16x16x32_bf16 v[50:53], v[142:145], v[160:163], v[50:53]
	v_mfma_f32_16x16x32_bf16 v[46:49], v[130:133], v[164:167], v[46:49]
	v_mfma_f32_16x16x32_bf16 v[42:45], v[134:137], v[164:167], v[42:45]
	v_mfma_f32_16x16x32_bf16 v[38:41], v[138:141], v[164:167], v[38:41]
	v_mfma_f32_16x16x32_bf16 v[34:37], v[142:145], v[164:167], v[34:37]
	v_mfma_f32_16x16x32_bf16 v[30:33], v[130:133], v[168:171], v[30:33]
	v_mfma_f32_16x16x32_bf16 v[26:29], v[134:137], v[168:171], v[26:29]
	v_mfma_f32_16x16x32_bf16 v[22:25], v[138:141], v[168:171], v[22:25]
	v_mfma_f32_16x16x32_bf16 v[18:21], v[142:145], v[168:171], v[18:21]
	v_mfma_f32_16x16x32_bf16 v[14:17], v[130:133], v[172:175], v[14:17]
	v_mfma_f32_16x16x32_bf16 v[10:13], v[134:137], v[172:175], v[10:13]
	v_mfma_f32_16x16x32_bf16 v[6:9], v[138:141], v[172:175], v[6:9]
	v_mfma_f32_16x16x32_bf16 v[2:5], v[142:145], v[172:175], v[2:5]
	s_setprio 0
	s_cbranch_scc0 .LBB0_125
	v_add3_u32 v182, 0, v157, v0
	s_waitcnt vmcnt(6) lgkmcnt(0)
	s_barrier
	v_add_u32_e32 v142, 0xc000, v182
	v_add3_u32 v0, 0, v158, v0
	ds_read_b128 v[130:133], v142 offset:16384
	ds_read_b128 v[134:137], v142 offset:17408
	ds_read_b128 v[138:141], v142 offset:18432
	ds_read_b128 v[142:145], v142 offset:19456
	ds_read_b128 v[146:149], v0 offset:49152
	ds_read_b128 v[150:153], v0 offset:50176
	ds_read_b128 v[154:157], v0 offset:51200
	ds_read_b128 v[158:161], v0 offset:52224
	s_waitcnt lgkmcnt(0)
	v_mfma_f32_16x16x32_bf16 v[126:129], v[130:133], v[146:149], v[126:129]
	s_lshl_b64 s[10:11], s[10:11], 11
	s_add_u32 s2, s19, s10
	s_addc_u32 s11, s20, s11
	v_mfma_f32_16x16x32_bf16 v[122:125], v[134:137], v[146:149], v[122:125]
	s_lshl_b32 s10, s24, 1
	s_add_u32 s10, s2, s10
	s_addc_u32 s11, s11, 0
	v_mfma_f32_16x16x32_bf16 v[118:121], v[138:141], v[146:149], v[118:121]
	s_mov_b64 s[24:25], 0x3000
	v_mfma_f32_16x16x32_bf16 v[114:117], v[142:145], v[146:149], v[114:117]
	v_mfma_f32_16x16x32_bf16 v[110:113], v[130:133], v[150:153], v[110:113]
	v_mfma_f32_16x16x32_bf16 v[106:109], v[134:137], v[150:153], v[106:109]
	v_mfma_f32_16x16x32_bf16 v[102:105], v[138:141], v[150:153], v[102:105]
	v_mfma_f32_16x16x32_bf16 v[98:101], v[142:145], v[150:153], v[98:101]
	v_mfma_f32_16x16x32_bf16 v[94:97], v[130:133], v[154:157], v[94:97]
	v_mfma_f32_16x16x32_bf16 v[90:93], v[134:137], v[154:157], v[90:93]
	v_mfma_f32_16x16x32_bf16 v[146:149], v[138:141], v[154:157], v[86:89]
	v_mfma_f32_16x16x32_bf16 v[82:85], v[142:145], v[154:157], v[82:85]
	v_mfma_f32_16x16x32_bf16 v[150:153], v[130:133], v[158:161], v[78:81]
	v_mfma_f32_16x16x32_bf16 v[74:77], v[134:137], v[158:161], v[74:77]
	v_mfma_f32_16x16x32_bf16 v[70:73], v[138:141], v[158:161], v[70:73]
	v_mfma_f32_16x16x32_bf16 v[154:157], v[142:145], v[158:161], v[66:69]
	s_nop 2
	ds_read_b128 v[66:69], v0 offset:53248
	ds_read_b128 v[78:81], v0 offset:54272
	ds_read_b128 v[86:89], v0 offset:55296
	ds_read_b128 v[158:161], v0 offset:56320
	s_waitcnt vmcnt(0) lgkmcnt(0)
	s_barrier
	s_waitcnt lgkmcnt(0)
	v_mfma_f32_16x16x32_bf16 v[62:65], v[130:133], v[66:69], v[62:65]
	v_mfma_f32_16x16x32_bf16 v[162:165], v[134:137], v[66:69], v[58:61]
	v_mfma_f32_16x16x32_bf16 v[166:169], v[138:141], v[66:69], v[54:57]
	v_mfma_f32_16x16x32_bf16 v[50:53], v[142:145], v[66:69], v[50:53]
	v_mfma_f32_16x16x32_bf16 v[170:173], v[130:133], v[78:81], v[46:49]
	v_mfma_f32_16x16x32_bf16 v[42:45], v[134:137], v[78:81], v[42:45]
	v_mfma_f32_16x16x32_bf16 v[38:41], v[138:141], v[78:81], v[38:41]
	v_mfma_f32_16x16x32_bf16 v[174:177], v[142:145], v[78:81], v[34:37]
	v_mfma_f32_16x16x32_bf16 v[30:33], v[130:133], v[86:89], v[30:33]
	v_mfma_f32_16x16x32_bf16 v[178:181], v[134:137], v[86:89], v[26:29]
	v_mfma_f32_16x16x32_bf16 v[22:25], v[138:141], v[86:89], v[22:25]
	v_mfma_f32_16x16x32_bf16 v[18:21], v[142:145], v[86:89], v[18:21]
	v_mfma_f32_16x16x32_bf16 v[14:17], v[130:133], v[158:161], v[14:17]
	v_mfma_f32_16x16x32_bf16 v[10:13], v[134:137], v[158:161], v[10:13]
	v_mfma_f32_16x16x32_bf16 v[6:9], v[138:141], v[158:161], v[6:9]
	v_mfma_f32_16x16x32_bf16 v[2:5], v[142:145], v[158:161], v[2:5]
	ds_read_b128 v[130:133], v182 offset:16384
	ds_read_b128 v[134:137], v182 offset:17408
	ds_read_b128 v[138:141], v182 offset:18432
	ds_read_b128 v[142:145], v182 offset:19456
	ds_read_b128 v[26:29], v0
	ds_read_b128 v[34:37], v0 offset:1024
	ds_read_b128 v[46:49], v0 offset:2048
	ds_read_b128 v[158:161], v0 offset:3072
	s_waitcnt lgkmcnt(0)
	v_mfma_f32_16x16x32_bf16 v[110:113], v[130:133], v[34:37], v[110:113]
	v_mfma_f32_16x16x32_bf16 v[106:109], v[134:137], v[34:37], v[106:109]
	v_mfma_f32_16x16x32_bf16 v[102:105], v[138:141], v[34:37], v[102:105]
	v_mfma_f32_16x16x32_bf16 v[98:101], v[142:145], v[34:37], v[98:101]
	v_mfma_f32_16x16x32_bf16 v[86:89], v[130:133], v[46:49], v[94:97]
	v_mfma_f32_16x16x32_bf16 v[78:81], v[134:137], v[46:49], v[90:93]
	v_mfma_f32_16x16x32_bf16 v[66:69], v[138:141], v[46:49], v[146:149]
	s_nop 5
	v_cvt_pk_bf16_f32 v86, v86, v87
	v_cvt_pk_bf16_f32 v78, v78, v79
	v_cvt_pk_bf16_f32 v79, v80, v81
	v_mfma_f32_16x16x32_bf16 v[34:37], v[138:141], v[158:161], v[70:73]
	s_nop 2
	ds_read_b128 v[70:73], v0 offset:4096
	ds_read_b128 v[90:93], v0 offset:5120
	ds_read_b128 v[94:97], v0 offset:6144
	ds_read_b128 v[146:149], v0 offset:7168
	s_waitcnt vmcnt(0) lgkmcnt(0)
	s_barrier
	v_mfma_f32_16x16x32_bf16 v[126:129], v[130:133], v[26:29], v[126:129]
	v_cvt_pk_bf16_f32 v34, v34, v35
	v_cvt_pk_bf16_f32 v35, v36, v37
	v_mfma_f32_16x16x32_bf16 v[122:125], v[134:137], v[26:29], v[122:125]
	v_cvt_pk_bf16_f32 v66, v66, v67
	v_cvt_pk_bf16_f32 v67, v68, v69
	v_cvt_pk_bf16_f32 v87, v88, v89
	v_mfma_f32_16x16x32_bf16 v[118:121], v[138:141], v[26:29], v[118:121]
	v_mfma_f32_16x16x32_bf16 v[114:117], v[142:145], v[26:29], v[114:117]
	v_mfma_f32_16x16x32_bf16 v[58:61], v[142:145], v[46:49], v[82:85]
	v_mfma_f32_16x16x32_bf16 v[54:57], v[130:133], v[158:161], v[150:153]
	v_mfma_f32_16x16x32_bf16 v[46:49], v[134:137], v[158:161], v[74:77]
	s_nop 5
	v_cvt_pk_bf16_f32 v58, v58, v59
	v_cvt_pk_bf16_f32 v59, v60, v61
	v_cvt_pk_bf16_f32 v54, v54, v55
	v_mfma_f32_16x16x32_bf16 v[26:29], v[142:145], v[158:161], v[154:157]
	v_cvt_pk_bf16_f32 v55, v56, v57
	v_cvt_pk_bf16_f32 v46, v46, v47
	v_cvt_pk_bf16_f32 v47, v48, v49
	v_mfma_f32_16x16x32_bf16 v[150:153], v[130:133], v[70:73], v[62:65]
	v_mfma_f32_16x16x32_bf16 v[154:157], v[134:137], v[70:73], v[162:165]
	s_nop 2
	v_cvt_pk_bf16_f32 v26, v26, v27
	v_cvt_pk_bf16_f32 v27, v28, v29
	v_mfma_f32_16x16x32_bf16 v[82:85], v[138:141], v[70:73], v[166:169]
	v_mfma_f32_16x16x32_bf16 v[74:77], v[142:145], v[70:73], v[50:53]
	s_nop 0
	v_cvt_pk_bf16_f32 v28, v154, v155
	v_cvt_pk_bf16_f32 v29, v156, v157
	v_mfma_f32_16x16x32_bf16 v[70:73], v[130:133], v[90:93], v[170:173]
	v_mfma_f32_16x16x32_bf16 v[62:65], v[134:137], v[90:93], v[42:45]
	v_mfma_f32_16x16x32_bf16 v[50:53], v[138:141], v[90:93], v[38:41]
	v_mfma_f32_16x16x32_bf16 v[42:45], v[142:145], v[90:93], v[174:177]
	v_mov_b32_e32 v90, v196
	s_nop 0
	v_and_b32_e32 v0, 64, v90
	v_lshrrev_b32_e32 v92, 1, v90
	v_lshlrev_b32_e32 v0, 1, v0
	v_and_b32_e32 v92, 24, v92
	v_and_b32_e32 v91, 0xfffff8f, v90
	v_add3_u32 v0, 0, v0, v92
	v_mad_u64_u32 v[92:93], s[12:13], v91, s30, v[0:1]
	v_add_u32_e32 v48, 0x3000, v92
	v_mfma_f32_16x16x32_bf16 v[38:41], v[130:133], v[94:97], v[30:33]
	ds_write2_b64 v48, v[34:35], v[26:27] offset0:104 offset1:108
	v_cvt_pk_bf16_f32 v26, v150, v151
	v_cvt_pk_bf16_f32 v27, v152, v153
	v_mfma_f32_16x16x32_bf16 v[30:33], v[134:137], v[94:97], v[178:181]
	v_add_u32_e32 v34, 0x4000, v92
	ds_write2_b64 v34, v[26:27], v[28:29] offset0:128 offset1:132
	v_cvt_pk_bf16_f32 v26, v82, v83
	v_mfma_f32_16x16x32_bf16 v[22:25], v[138:141], v[94:97], v[22:25]
	v_cvt_pk_bf16_f32 v27, v84, v85
	v_cvt_pk_bf16_f32 v28, v74, v75
	v_cvt_pk_bf16_f32 v29, v76, v77
	v_mfma_f32_16x16x32_bf16 v[18:21], v[142:145], v[94:97], v[18:21]
	ds_write2_b64 v34, v[26:27], v[28:29] offset0:136 offset1:140
	v_cvt_pk_bf16_f32 v26, v70, v71
	v_cvt_pk_bf16_f32 v27, v72, v73
	v_cvt_pk_bf16_f32 v28, v62, v63
	v_cvt_pk_bf16_f32 v29, v64, v65
	v_add_u32_e32 v34, 0x5000, v92
	v_mfma_f32_16x16x32_bf16 v[6:9], v[138:141], v[146:149], v[6:9]
	ds_write2_b64 v34, v[26:27], v[28:29] offset0:160 offset1:164
	v_cvt_pk_bf16_f32 v26, v50, v51
	v_cvt_pk_bf16_f32 v27, v52, v53
	v_mfma_f32_16x16x32_bf16 v[2:5], v[142:145], v[146:149], v[2:5]
	v_cvt_pk_bf16_f32 v28, v42, v43
	v_cvt_pk_bf16_f32 v29, v44, v45
	v_cvt_pk_bf16_f32 v94, v126, v127
	v_cvt_pk_bf16_f32 v95, v128, v129
	v_cvt_pk_bf16_f32 v96, v122, v123
	v_cvt_pk_bf16_f32 v97, v124, v125
	ds_write2_b64 v34, v[26:27], v[28:29] offset0:168 offset1:172
	v_cvt_pk_bf16_f32 v28, v30, v31
	v_add_u32_e32 v30, 0x6000, v92
	v_cvt_pk_bf16_f32 v22, v22, v23
	v_cvt_pk_bf16_f32 v23, v24, v25
	v_cvt_pk_bf16_f32 v18, v18, v19
	v_cvt_pk_bf16_f32 v19, v20, v21
	v_mfma_f32_16x16x32_bf16 v[14:17], v[130:133], v[146:149], v[14:17]
	ds_write2_b64 v92, v[94:95], v[96:97] offset1:4
	v_cvt_pk_bf16_f32 v94, v118, v119
	v_cvt_pk_bf16_f32 v95, v120, v121
	v_mfma_f32_16x16x32_bf16 v[10:13], v[134:137], v[146:149], v[10:13]
	v_cvt_pk_bf16_f32 v96, v114, v115
	v_cvt_pk_bf16_f32 v97, v116, v117
	ds_write2_b64 v30, v[22:23], v[18:19] offset0:200 offset1:204
	v_or_b32_e32 v18, 0x70, v90
	ds_write2_b64 v92, v[94:95], v[96:97] offset0:8 offset1:12
	v_cvt_pk_bf16_f32 v94, v110, v111
	v_cvt_pk_bf16_f32 v95, v112, v113
	v_cvt_pk_bf16_f32 v96, v106, v107
	v_cvt_pk_bf16_f32 v97, v108, v109
	v_add_u32_e32 v91, 0x1000, v92
	v_mad_u64_u32 v[18:19], s[12:13], v18, s30, v[0:1]
	v_lshlrev_b32_e32 v0, 4, v90
	ds_write2_b64 v91, v[94:95], v[96:97] offset0:32 offset1:36
	v_cvt_pk_bf16_f32 v94, v102, v103
	v_cvt_pk_bf16_f32 v95, v104, v105
	v_cvt_pk_bf16_f32 v96, v98, v99
	v_cvt_pk_bf16_f32 v97, v100, v101
	v_add_u32_e32 v80, 0x2000, v92
	v_cvt_pk_bf16_f32 v6, v6, v7
	v_cvt_pk_bf16_f32 v7, v8, v9
	v_cvt_pk_bf16_f32 v2, v2, v3
	v_cvt_pk_bf16_f32 v3, v4, v5
	v_and_b32_e32 v0, 0xf0, v0
	v_ashrrev_i32_e32 v4, 4, v90
	ds_write2_b64 v91, v[94:95], v[96:97] offset0:40 offset1:44
	ds_write2_b64 v80, v[66:67], v[58:59] offset0:72 offset1:76
	ds_write2_b64 v18, v[6:7], v[2:3] offset0:8 offset1:12
	v_lshl_add_u64 v[2:3], s[10:11], 0, v[0:1]
	v_add_u32_e32 v0, 0, v0
	v_ashrrev_i32_e32 v5, 31, v4
	v_cvt_pk_bf16_f32 v26, v38, v39
	v_cvt_pk_bf16_f32 v27, v40, v41
	v_cvt_pk_bf16_f32 v29, v32, v33
	v_cvt_pk_bf16_f32 v14, v14, v15
	v_cvt_pk_bf16_f32 v15, v16, v17
	v_cvt_pk_bf16_f32 v10, v10, v11
	v_cvt_pk_bf16_f32 v11, v12, v13
	v_mad_u64_u32 v[6:7], s[10:11], v4, s30, v[0:1]
	v_lshlrev_b64 v[4:5], 11, v[4:5]
	ds_write2_b64 v80, v[86:87], v[78:79] offset0:64 offset1:68
	ds_write2_b64 v48, v[54:55], v[46:47] offset0:96 offset1:100
	ds_write2_b64 v30, v[26:27], v[28:29] offset0:192 offset1:196
	ds_write2_b64 v18, v[14:15], v[10:11] offset1:4
	s_waitcnt lgkmcnt(0)
	s_barrier
	v_lshl_add_u64 v[8:9], v[2:3], 0, v[4:5]
	ds_read_b128 v[4:7], v6
	s_waitcnt lgkmcnt(0)
	global_store_dwordx4 v[8:9], v[4:7], off
	s_nop 1
	v_add_u32_e32 v4, 0x100, v90
	v_ashrrev_i32_e32 v4, 4, v4
	v_ashrrev_i32_e32 v5, 31, v4
	v_mad_u64_u32 v[6:7], s[10:11], v4, s30, v[0:1]
	v_lshlrev_b64 v[4:5], 11, v[4:5]
	v_lshl_add_u64 v[8:9], v[2:3], 0, v[4:5]
	ds_read_b128 v[4:7], v6
	s_waitcnt lgkmcnt(0)
	global_store_dwordx4 v[8:9], v[4:7], off
	s_nop 1
	v_add_u32_e32 v4, 0x200, v90
	v_ashrrev_i32_e32 v4, 4, v4
	v_ashrrev_i32_e32 v5, 31, v4
	v_mad_u64_u32 v[6:7], s[10:11], v4, s30, v[0:1]
	v_lshlrev_b64 v[4:5], 11, v[4:5]
	v_lshl_add_u64 v[8:9], v[2:3], 0, v[4:5]
	ds_read_b128 v[4:7], v6
	s_waitcnt lgkmcnt(0)
	global_store_dwordx4 v[8:9], v[4:7], off
	s_nop 1
	v_add_u32_e32 v4, 0x300, v90
	v_ashrrev_i32_e32 v4, 4, v4
	v_ashrrev_i32_e32 v5, 31, v4
	v_mad_u64_u32 v[6:7], s[10:11], v4, s30, v[0:1]
	v_lshlrev_b64 v[4:5], 11, v[4:5]
	v_lshl_add_u64 v[8:9], v[2:3], 0, v[4:5]
	ds_read_b128 v[4:7], v6
	s_waitcnt lgkmcnt(0)
	global_store_dwordx4 v[8:9], v[4:7], off
	s_nop 1
	v_add_u32_e32 v4, 0x400, v90
	v_ashrrev_i32_e32 v4, 4, v4
	v_ashrrev_i32_e32 v5, 31, v4
	v_mad_u64_u32 v[6:7], s[10:11], v4, s30, v[0:1]
	v_lshlrev_b64 v[4:5], 11, v[4:5]
	v_lshl_add_u64 v[8:9], v[2:3], 0, v[4:5]
	ds_read_b128 v[4:7], v6
	s_waitcnt lgkmcnt(0)
	global_store_dwordx4 v[8:9], v[4:7], off
	s_nop 1
	v_add_u32_e32 v4, 0x500, v90
	v_ashrrev_i32_e32 v4, 4, v4
	v_ashrrev_i32_e32 v5, 31, v4
	v_mad_u64_u32 v[6:7], s[10:11], v4, s30, v[0:1]
	v_lshlrev_b64 v[4:5], 11, v[4:5]
	v_lshl_add_u64 v[8:9], v[2:3], 0, v[4:5]
	ds_read_b128 v[4:7], v6
	s_waitcnt lgkmcnt(0)
	global_store_dwordx4 v[8:9], v[4:7], off
	s_nop 1
	v_add_u32_e32 v4, 0x600, v90
	v_ashrrev_i32_e32 v4, 4, v4
	v_ashrrev_i32_e32 v5, 31, v4
	v_mad_u64_u32 v[6:7], s[10:11], v4, s30, v[0:1]
	v_lshlrev_b64 v[4:5], 11, v[4:5]
	v_lshl_add_u64 v[8:9], v[2:3], 0, v[4:5]
	ds_read_b128 v[4:7], v6
	s_waitcnt lgkmcnt(0)
	global_store_dwordx4 v[8:9], v[4:7], off
	s_nop 1
	v_add_u32_e32 v4, 0x700, v90
	v_ashrrev_i32_e32 v4, 4, v4
	v_ashrrev_i32_e32 v5, 31, v4
	v_mad_u64_u32 v[6:7], s[10:11], v4, s30, v[0:1]
	v_lshlrev_b64 v[4:5], 11, v[4:5]
	v_lshl_add_u64 v[8:9], v[2:3], 0, v[4:5]
	ds_read_b128 v[4:7], v6
	s_waitcnt lgkmcnt(0)
	global_store_dwordx4 v[8:9], v[4:7], off
	s_nop 1
	v_add_u32_e32 v4, 0x800, v90
	v_ashrrev_i32_e32 v4, 4, v4
	v_ashrrev_i32_e32 v5, 31, v4
	v_mad_u64_u32 v[6:7], s[10:11], v4, s30, v[0:1]
	v_lshlrev_b64 v[4:5], 11, v[4:5]
	v_lshl_add_u64 v[8:9], v[2:3], 0, v[4:5]
	ds_read_b128 v[4:7], v6
	s_waitcnt lgkmcnt(0)
	global_store_dwordx4 v[8:9], v[4:7], off
	s_nop 1
	v_add_u32_e32 v4, 0x900, v90
	v_ashrrev_i32_e32 v4, 4, v4
	v_ashrrev_i32_e32 v5, 31, v4
	v_mad_u64_u32 v[6:7], s[10:11], v4, s30, v[0:1]
	v_lshlrev_b64 v[4:5], 11, v[4:5]
	v_lshl_add_u64 v[8:9], v[2:3], 0, v[4:5]
	ds_read_b128 v[4:7], v6
	s_waitcnt lgkmcnt(0)
	global_store_dwordx4 v[8:9], v[4:7], off
	s_nop 1
	v_add_u32_e32 v4, 0xa00, v90
	v_ashrrev_i32_e32 v4, 4, v4
	v_ashrrev_i32_e32 v5, 31, v4
	v_mad_u64_u32 v[6:7], s[10:11], v4, s30, v[0:1]
	v_lshlrev_b64 v[4:5], 11, v[4:5]
	v_lshl_add_u64 v[8:9], v[2:3], 0, v[4:5]
	ds_read_b128 v[4:7], v6
	s_waitcnt lgkmcnt(0)
	global_store_dwordx4 v[8:9], v[4:7], off
	s_nop 1
	v_add_u32_e32 v4, 0xb00, v90
	v_ashrrev_i32_e32 v4, 4, v4
	v_ashrrev_i32_e32 v5, 31, v4
	v_mad_u64_u32 v[6:7], s[10:11], v4, s30, v[0:1]
	v_lshlrev_b64 v[4:5], 11, v[4:5]
	v_lshl_add_u64 v[8:9], v[2:3], 0, v[4:5]
	ds_read_b128 v[4:7], v6
	s_waitcnt lgkmcnt(0)
	global_store_dwordx4 v[8:9], v[4:7], off
	s_nop 1
	v_add_u32_e32 v4, 0xc00, v90
	v_ashrrev_i32_e32 v4, 4, v4
	v_ashrrev_i32_e32 v5, 31, v4
	v_mad_u64_u32 v[6:7], s[10:11], v4, s30, v[0:1]
	v_lshlrev_b64 v[4:5], 11, v[4:5]
	v_lshl_add_u64 v[8:9], v[2:3], 0, v[4:5]
	ds_read_b128 v[4:7], v6
	s_waitcnt lgkmcnt(0)
	global_store_dwordx4 v[8:9], v[4:7], off
	s_nop 1
	v_add_u32_e32 v4, 0xd00, v90
	v_ashrrev_i32_e32 v4, 4, v4
	v_ashrrev_i32_e32 v5, 31, v4
	v_mad_u64_u32 v[6:7], s[10:11], v4, s30, v[0:1]
	v_lshlrev_b64 v[4:5], 11, v[4:5]
	v_lshl_add_u64 v[8:9], v[2:3], 0, v[4:5]
	ds_read_b128 v[4:7], v6
	s_waitcnt lgkmcnt(0)
	global_store_dwordx4 v[8:9], v[4:7], off
	s_nop 1
	v_add_u32_e32 v4, 0xe00, v90
	v_ashrrev_i32_e32 v4, 4, v4
	v_ashrrev_i32_e32 v5, 31, v4
	v_mad_u64_u32 v[6:7], s[10:11], v4, s30, v[0:1]
	v_lshlrev_b64 v[4:5], 11, v[4:5]
	v_lshl_add_u64 v[8:9], v[2:3], 0, v[4:5]
	ds_read_b128 v[4:7], v6
	s_waitcnt lgkmcnt(0)
	global_store_dwordx4 v[8:9], v[4:7], off
	s_nop 1
	v_add_u32_e32 v4, 0xf00, v90
	v_ashrrev_i32_e32 v4, 4, v4
	v_ashrrev_i32_e32 v5, 31, v4
	v_mad_u64_u32 v[6:7], s[10:11], v4, s30, v[0:1]
	v_lshlrev_b64 v[4:5], 11, v[4:5]
	v_lshl_add_u64 v[8:9], v[2:3], 0, v[4:5]
	ds_read_b128 v[2:5], v6
	s_waitcnt lgkmcnt(0)
	global_store_dwordx4 v[8:9], v[2:5], off
	s_barrier
	s_branch .LBB0_118

.LBB0_142:
	v_lshl_add_u64 v[138:139], v[152:153], 0, s[0:1]
	s_mov_b64 s[44:45], 0x1220080
	v_lshl_add_u64 v[130:131], v[138:139], 0, s[44:45]
	s_mov_b64 s[44:45], 0x1200080
	v_lshl_add_u64 v[132:133], v[138:139], 0, s[44:45]
	s_mul_i32 s44, s42, 0x6000
	v_add_u32_e32 v134, s44, v151
	v_add_u32_e32 v135, 0x1000, v134
	v_readfirstlane_b32 s44, v134
	s_waitcnt vmcnt(6) lgkmcnt(0)
	s_barrier
	s_mov_b32 m0, s44
	v_readfirstlane_b32 s44, v135
	v_add_u32_e32 v135, 0x2000, v134
	global_load_lds_dwordx4 v[162:163], off
	s_mov_b32 m0, s44
	v_readfirstlane_b32 s44, v135
	v_add_u32_e32 v135, 0x3000, v134
	global_load_lds_dwordx4 v[164:165], off
	s_mov_b32 m0, s44
	v_readfirstlane_b32 s44, v135
	v_add_u32_e32 v135, 0x4000, v134
	global_load_lds_dwordx4 v[166:167], off
	s_mov_b32 m0, s44
	v_readfirstlane_b32 s44, v135
	global_load_lds_dwordx4 v[160:161], off
	s_mov_b32 m0, s44
	v_mov_b32_e32 v155, v1
	global_load_lds_dwordx4 v[132:133], off
	v_add_u32_e32 v132, 0x5000, v134
	v_mov_b32_e32 v157, v1
	v_readfirstlane_b32 s44, v132
	s_mov_b32 m0, s44
	s_mov_b64 s[44:45], 0x12000c0
	v_lshl_add_u64 v[140:141], v[138:139], 0, s[44:45]
	s_mov_b64 s[44:45], 0x12200c0
	v_lshl_add_u64 v[138:139], v[138:139], 0, s[44:45]
	s_mul_i32 s44, s43, 0x6000
	s_add_i32 s44, s44, 0
	global_load_lds_dwordx4 v[130:131], off
	v_mov_b32_e32 v159, v1
	v_add3_u32 v175, s44, v172, v173
	v_lshl_add_u64 v[130:131], v[162:163], 0, v[0:1]
	v_lshl_add_u64 v[132:133], v[164:165], 0, v[154:155]
	v_lshl_add_u64 v[134:135], v[166:167], 0, v[156:157]
	v_lshl_add_u64 v[136:137], v[160:161], 0, v[158:159]
	ds_read_b128 v[142:145], v175 offset:16384
	ds_read_b128 v[160:163], v175 offset:17408
	ds_read_b128 v[164:167], v175 offset:18432
	ds_read_b128 v[176:179], v175 offset:19456
	v_add3_u32 v175, s44, v174, v173
	ds_read_b128 v[180:183], v175
	ds_read_b128 v[184:187], v175 offset:1024
	ds_read_b128 v[188:191], v175 offset:2048
	ds_read_b128 v[192:195], v175 offset:3072
	s_add_i32 s44, s43, 1
	s_waitcnt lgkmcnt(0)
	s_setprio 1
	v_mfma_f32_16x16x32_bf16 v[126:129], v[142:145], v[180:183], v[126:129]
	s_cmp_lg_u32 s43, 2
	s_cselect_b32 s43, s44, 0
	s_add_i32 s44, s42, 1
	v_mfma_f32_16x16x32_bf16 v[122:125], v[160:163], v[180:183], v[122:125]
	s_cmp_lg_u32 s42, 2
	s_cselect_b32 s42, s44, 0
	s_mul_i32 s44, s42, 0x6000
	v_mfma_f32_16x16x32_bf16 v[118:121], v[164:167], v[180:183], v[118:121]
	v_mfma_f32_16x16x32_bf16 v[114:117], v[176:179], v[180:183], v[114:117]
	v_mfma_f32_16x16x32_bf16 v[110:113], v[142:145], v[184:187], v[110:113]
	v_mfma_f32_16x16x32_bf16 v[106:109], v[160:163], v[184:187], v[106:109]
	v_mfma_f32_16x16x32_bf16 v[102:105], v[164:167], v[184:187], v[102:105]
	v_mfma_f32_16x16x32_bf16 v[98:101], v[176:179], v[184:187], v[98:101]
	v_mfma_f32_16x16x32_bf16 v[94:97], v[142:145], v[188:191], v[94:97]
	v_mfma_f32_16x16x32_bf16 v[90:93], v[160:163], v[188:191], v[90:93]
	v_mfma_f32_16x16x32_bf16 v[86:89], v[164:167], v[188:191], v[86:89]
	v_mfma_f32_16x16x32_bf16 v[82:85], v[176:179], v[188:191], v[82:85]
	v_mfma_f32_16x16x32_bf16 v[78:81], v[142:145], v[192:195], v[78:81]
	v_mfma_f32_16x16x32_bf16 v[74:77], v[160:163], v[192:195], v[74:77]
	v_mfma_f32_16x16x32_bf16 v[70:73], v[164:167], v[192:195], v[70:73]
	v_mfma_f32_16x16x32_bf16 v[66:69], v[176:179], v[192:195], v[66:69]
	s_setprio 0
	ds_read_b128 v[180:183], v175 offset:4096
	ds_read_b128 v[184:187], v175 offset:5120
	ds_read_b128 v[188:191], v175 offset:6144
	ds_read_b128 v[192:195], v175 offset:7168
	s_waitcnt vmcnt(6) lgkmcnt(0)
	s_barrier
	s_waitcnt lgkmcnt(0)
	s_setprio 1
	v_mfma_f32_16x16x32_bf16 v[62:65], v[142:145], v[180:183], v[62:65]
	s_setprio 0
	s_setprio 1
	v_mfma_f32_16x16x32_bf16 v[46:49], v[142:145], v[184:187], v[46:49]
	v_mfma_f32_16x16x32_bf16 v[30:33], v[142:145], v[188:191], v[30:33]
	v_mfma_f32_16x16x32_bf16 v[14:17], v[142:145], v[192:195], v[14:17]
	v_add_u32_e32 v142, s44, v151
	v_add_u32_e32 v143, 0x1000, v142
	v_readfirstlane_b32 s44, v142
	s_mov_b32 m0, s44
	v_readfirstlane_b32 s44, v143
	v_add_u32_e32 v143, 0x2000, v142
	global_load_lds_dwordx4 v[130:131], off
	s_mov_b32 m0, s44
	v_readfirstlane_b32 s44, v143
	v_add_u32_e32 v143, 0x3000, v142
	global_load_lds_dwordx4 v[132:133], off
	s_mov_b32 m0, s44
	v_readfirstlane_b32 s44, v143
	v_add_u32_e32 v143, 0x4000, v142
	global_load_lds_dwordx4 v[134:135], off
	s_mov_b32 m0, s44
	v_readfirstlane_b32 s44, v143
	global_load_lds_dwordx4 v[136:137], off
	s_mov_b32 m0, s44
	v_mfma_f32_16x16x32_bf16 v[54:57], v[164:167], v[180:183], v[54:57]
	global_load_lds_dwordx4 v[140:141], off
	v_add_u32_e32 v140, 0x5000, v142
	v_mfma_f32_16x16x32_bf16 v[38:41], v[164:167], v[184:187], v[38:41]
	v_readfirstlane_b32 s44, v140
	s_mov_b32 m0, s44
	s_mul_i32 s44, s43, 0x6000
	global_load_lds_dwordx4 v[138:139], off
	s_add_i32 s44, s44, 0
	v_mfma_f32_16x16x32_bf16 v[22:25], v[164:167], v[188:191], v[22:25]
	v_add3_u32 v142, s44, v172, v173
	v_mfma_f32_16x16x32_bf16 v[6:9], v[164:167], v[192:195], v[6:9]
	v_lshl_add_u64 v[164:165], v[132:133], 0, v[154:155]
	v_add3_u32 v155, s44, v174, v173
	v_lshl_add_u64 v[166:167], v[134:135], 0, v[156:157]
	v_mfma_f32_16x16x32_bf16 v[58:61], v[160:163], v[180:183], v[58:61]
	s_add_i32 s44, s43, 1
	s_cmp_lg_u32 s43, 2
	s_cselect_b32 s43, s44, 0
	v_mfma_f32_16x16x32_bf16 v[50:53], v[176:179], v[180:183], v[50:53]
	s_add_i32 s44, s42, 1
	s_cmp_lg_u32 s42, 2
	s_cselect_b32 s42, s44, 0
	v_mfma_f32_16x16x32_bf16 v[42:45], v[160:163], v[184:187], v[42:45]
	s_add_u32 s0, s0, 0x80
	s_addc_u32 s1, s1, 0
	s_cmpk_eq_i32 s0, 0x780
	v_mfma_f32_16x16x32_bf16 v[34:37], v[176:179], v[184:187], v[34:37]
	v_mfma_f32_16x16x32_bf16 v[26:29], v[160:163], v[188:191], v[26:29]
	v_mfma_f32_16x16x32_bf16 v[18:21], v[176:179], v[188:191], v[18:21]
	v_mfma_f32_16x16x32_bf16 v[10:13], v[160:163], v[192:195], v[10:13]
	v_lshl_add_u64 v[162:163], v[130:131], 0, v[0:1]
	v_lshl_add_u64 v[160:161], v[136:137], 0, v[158:159]
	s_setprio 0
	ds_read_b128 v[130:133], v142 offset:16384
	ds_read_b128 v[134:137], v142 offset:17408
	ds_read_b128 v[138:141], v142 offset:18432
	ds_read_b128 v[142:145], v142 offset:19456
	s_setprio 1
	v_mfma_f32_16x16x32_bf16 v[2:5], v[176:179], v[192:195], v[2:5]
	s_setprio 0
	ds_read_b128 v[176:179], v155
	ds_read_b128 v[180:183], v155 offset:1024
	ds_read_b128 v[184:187], v155 offset:2048
	ds_read_b128 v[188:191], v155 offset:3072
	s_waitcnt lgkmcnt(0)
	s_setprio 1
	v_mfma_f32_16x16x32_bf16 v[126:129], v[130:133], v[176:179], v[126:129]
	v_mfma_f32_16x16x32_bf16 v[122:125], v[134:137], v[176:179], v[122:125]
	v_mfma_f32_16x16x32_bf16 v[118:121], v[138:141], v[176:179], v[118:121]
	v_mfma_f32_16x16x32_bf16 v[114:117], v[142:145], v[176:179], v[114:117]
	v_mfma_f32_16x16x32_bf16 v[110:113], v[130:133], v[180:183], v[110:113]
	v_mfma_f32_16x16x32_bf16 v[106:109], v[134:137], v[180:183], v[106:109]
	v_mfma_f32_16x16x32_bf16 v[102:105], v[138:141], v[180:183], v[102:105]
	v_mfma_f32_16x16x32_bf16 v[98:101], v[142:145], v[180:183], v[98:101]
	v_mfma_f32_16x16x32_bf16 v[94:97], v[130:133], v[184:187], v[94:97]
	v_mfma_f32_16x16x32_bf16 v[90:93], v[134:137], v[184:187], v[90:93]
	v_mfma_f32_16x16x32_bf16 v[86:89], v[138:141], v[184:187], v[86:89]
	v_mfma_f32_16x16x32_bf16 v[82:85], v[142:145], v[184:187], v[82:85]
	v_mfma_f32_16x16x32_bf16 v[78:81], v[130:133], v[188:191], v[78:81]
	v_mfma_f32_16x16x32_bf16 v[74:77], v[134:137], v[188:191], v[74:77]
	v_mfma_f32_16x16x32_bf16 v[70:73], v[138:141], v[188:191], v[70:73]
	v_mfma_f32_16x16x32_bf16 v[66:69], v[142:145], v[188:191], v[66:69]
	s_setprio 0
	ds_read_b128 v[176:179], v155 offset:4096
	ds_read_b128 v[180:183], v155 offset:5120
	ds_read_b128 v[184:187], v155 offset:6144
	ds_read_b128 v[188:191], v155 offset:7168
	s_waitcnt lgkmcnt(0)
	s_setprio 1
	v_mfma_f32_16x16x32_bf16 v[62:65], v[130:133], v[176:179], v[62:65]
	v_mfma_f32_16x16x32_bf16 v[58:61], v[134:137], v[176:179], v[58:61]
	v_mfma_f32_16x16x32_bf16 v[54:57], v[138:141], v[176:179], v[54:57]
	v_mfma_f32_16x16x32_bf16 v[50:53], v[142:145], v[176:179], v[50:53]
	v_mfma_f32_16x16x32_bf16 v[46:49], v[130:133], v[180:183], v[46:49]
	v_mfma_f32_16x16x32_bf16 v[42:45], v[134:137], v[180:183], v[42:45]
	v_mfma_f32_16x16x32_bf16 v[38:41], v[138:141], v[180:183], v[38:41]
	v_mfma_f32_16x16x32_bf16 v[34:37], v[142:145], v[180:183], v[34:37]
	v_mfma_f32_16x16x32_bf16 v[30:33], v[130:133], v[184:187], v[30:33]
	v_mfma_f32_16x16x32_bf16 v[26:29], v[134:137], v[184:187], v[26:29]
	v_mfma_f32_16x16x32_bf16 v[22:25], v[138:141], v[184:187], v[22:25]
	v_mfma_f32_16x16x32_bf16 v[18:21], v[142:145], v[184:187], v[18:21]
	v_mfma_f32_16x16x32_bf16 v[14:17], v[130:133], v[188:191], v[14:17]
	v_mfma_f32_16x16x32_bf16 v[10:13], v[134:137], v[188:191], v[10:13]
	v_mfma_f32_16x16x32_bf16 v[6:9], v[138:141], v[188:191], v[6:9]
	v_mfma_f32_16x16x32_bf16 v[2:5], v[142:145], v[188:191], v[2:5]
	s_setprio 0
	s_cbranch_scc0 .LBB0_142
	s_waitcnt vmcnt(6) lgkmcnt(0)
	s_barrier
	v_add3_u32 v0, 0, v172, v173
	v_add3_u32 v151, 0, v174, v173
	ds_read_b128 v[130:133], v0 offset:16384
	ds_read_b128 v[134:137], v0 offset:17408
	ds_read_b128 v[138:141], v0 offset:18432
	ds_read_b128 v[142:145], v0 offset:19456
	ds_read_b128 v[152:155], v151
	ds_read_b128 v[156:159], v151 offset:1024
	ds_read_b128 v[160:163], v151 offset:2048
	ds_read_b128 v[164:167], v151 offset:3072
	s_waitcnt lgkmcnt(0)
	v_mfma_f32_16x16x32_bf16 v[126:129], v[130:133], v[152:155], v[126:129]
	s_movk_i32 s89, 0x7fff
	s_mov_b32 s56, 0x800000
	s_movk_i32 s57, 0x1320
	v_mfma_f32_16x16x32_bf16 v[122:125], v[134:137], v[152:155], v[122:125]
	v_mfma_f32_16x16x32_bf16 v[118:121], v[138:141], v[152:155], v[118:121]
	v_mfma_f32_16x16x32_bf16 v[114:117], v[142:145], v[152:155], v[114:117]
	v_mfma_f32_16x16x32_bf16 v[110:113], v[130:133], v[156:159], v[110:113]
	v_mfma_f32_16x16x32_bf16 v[106:109], v[134:137], v[156:159], v[106:109]
	v_mfma_f32_16x16x32_bf16 v[102:105], v[138:141], v[156:159], v[102:105]
	v_mfma_f32_16x16x32_bf16 v[98:101], v[142:145], v[156:159], v[98:101]
	v_mfma_f32_16x16x32_bf16 v[94:97], v[130:133], v[160:163], v[94:97]
	v_mfma_f32_16x16x32_bf16 v[90:93], v[134:137], v[160:163], v[90:93]
	v_mfma_f32_16x16x32_bf16 v[86:89], v[138:141], v[160:163], v[86:89]
	v_mfma_f32_16x16x32_bf16 v[82:85], v[142:145], v[160:163], v[82:85]
	v_mfma_f32_16x16x32_bf16 v[78:81], v[130:133], v[164:167], v[78:81]
	v_mfma_f32_16x16x32_bf16 v[74:77], v[134:137], v[164:167], v[74:77]
	v_mfma_f32_16x16x32_bf16 v[70:73], v[138:141], v[164:167], v[70:73]
	v_mfma_f32_16x16x32_bf16 v[66:69], v[142:145], v[164:167], v[66:69]
	ds_read_b128 v[152:155], v151 offset:4096
	ds_read_b128 v[156:159], v151 offset:5120
	ds_read_b128 v[160:163], v151 offset:6144
	ds_read_b128 v[164:167], v151 offset:7168
	s_waitcnt vmcnt(0) lgkmcnt(0)
	s_barrier
	s_waitcnt lgkmcnt(0)
	v_mfma_f32_16x16x32_bf16 v[172:175], v[130:133], v[152:155], v[62:65]
	v_mfma_f32_16x16x32_bf16 v[58:61], v[134:137], v[152:155], v[58:61]
	v_mfma_f32_16x16x32_bf16 v[176:179], v[138:141], v[152:155], v[54:57]
	v_mfma_f32_16x16x32_bf16 v[50:53], v[142:145], v[152:155], v[50:53]
	v_mfma_f32_16x16x32_bf16 v[152:155], v[130:133], v[156:159], v[46:49]
	v_mfma_f32_16x16x32_bf16 v[42:45], v[134:137], v[156:159], v[42:45]
	v_mfma_f32_16x16x32_bf16 v[180:183], v[138:141], v[156:159], v[38:41]
	v_mfma_f32_16x16x32_bf16 v[34:37], v[142:145], v[156:159], v[34:37]
	v_mfma_f32_16x16x32_bf16 v[156:159], v[130:133], v[160:163], v[30:33]
	v_mfma_f32_16x16x32_bf16 v[26:29], v[134:137], v[160:163], v[26:29]
	v_mfma_f32_16x16x32_bf16 v[22:25], v[138:141], v[160:163], v[22:25]
	v_mfma_f32_16x16x32_bf16 v[18:21], v[142:145], v[160:163], v[18:21]
	v_mfma_f32_16x16x32_bf16 v[14:17], v[130:133], v[164:167], v[14:17]
	v_mfma_f32_16x16x32_bf16 v[10:13], v[134:137], v[164:167], v[10:13]
	v_mfma_f32_16x16x32_bf16 v[6:9], v[138:141], v[164:167], v[6:9]
	v_mfma_f32_16x16x32_bf16 v[2:5], v[142:145], v[164:167], v[2:5]
	ds_read_b128 v[130:133], v0 offset:40960
	ds_read_b128 v[134:137], v0 offset:41984
	ds_read_b128 v[138:141], v0 offset:43008
	ds_read_b128 v[142:145], v0 offset:44032
	ds_read_b128 v[30:33], v151 offset:24576
	ds_read_b128 v[38:41], v151 offset:25600
	ds_read_b128 v[46:49], v151 offset:26624
	ds_read_b128 v[160:163], v151 offset:27648
	v_add_u32_e32 v0, 0x1000, v150
	s_waitcnt lgkmcnt(0)
	v_mfma_f32_16x16x32_bf16 v[126:129], v[130:133], v[30:33], v[126:129]
	v_mfma_f32_16x16x32_bf16 v[122:125], v[134:137], v[30:33], v[122:125]
	v_mfma_f32_16x16x32_bf16 v[118:121], v[138:141], v[30:33], v[118:121]
	v_mfma_f32_16x16x32_bf16 v[114:117], v[142:145], v[30:33], v[114:117]
	v_mfma_f32_16x16x32_bf16 v[110:113], v[130:133], v[38:41], v[110:113]
	v_mfma_f32_16x16x32_bf16 v[106:109], v[134:137], v[38:41], v[106:109]
	v_mfma_f32_16x16x32_bf16 v[102:105], v[138:141], v[38:41], v[102:105]
	v_mfma_f32_16x16x32_bf16 v[98:101], v[142:145], v[38:41], v[98:101]
	v_mfma_f32_16x16x32_bf16 v[94:97], v[130:133], v[46:49], v[94:97]
	v_mfma_f32_16x16x32_bf16 v[90:93], v[134:137], v[46:49], v[90:93]
	v_mfma_f32_16x16x32_bf16 v[86:89], v[138:141], v[46:49], v[86:89]
	v_mfma_f32_16x16x32_bf16 v[62:65], v[142:145], v[46:49], v[82:85]
	v_mfma_f32_16x16x32_bf16 v[54:57], v[130:133], v[160:163], v[78:81]
	v_mfma_f32_16x16x32_bf16 v[46:49], v[134:137], v[160:163], v[74:77]
	s_nop 5
	v_cvt_pk_bf16_f32 v62, v62, v63
	v_cvt_pk_bf16_f32 v63, v64, v65
	v_cvt_pk_bf16_f32 v54, v54, v55
	v_mfma_f32_16x16x32_bf16 v[38:41], v[138:141], v[160:163], v[70:73]
	v_cvt_pk_bf16_f32 v55, v56, v57
	v_cvt_pk_bf16_f32 v46, v46, v47
	v_cvt_pk_bf16_f32 v47, v48, v49
	v_mfma_f32_16x16x32_bf16 v[30:33], v[142:145], v[160:163], v[66:69]
	s_nop 2
	ds_read_b128 v[66:69], v151 offset:28672
	ds_read_b128 v[70:73], v151 offset:29696
	ds_read_b128 v[74:77], v151 offset:30720
	ds_read_b128 v[78:81], v151 offset:31744
	s_waitcnt vmcnt(0) lgkmcnt(0)
	s_barrier
	v_mfma_f32_16x16x32_bf16 v[82:85], v[130:133], v[66:69], v[172:175]
	v_cvt_pk_bf16_f32 v38, v38, v39
	v_cvt_pk_bf16_f32 v39, v40, v41
	v_mfma_f32_16x16x32_bf16 v[160:163], v[134:137], v[66:69], v[58:61]
	v_cvt_pk_bf16_f32 v30, v30, v31
	v_cvt_pk_bf16_f32 v31, v32, v33
	v_mfma_f32_16x16x32_bf16 v[164:167], v[138:141], v[66:69], v[176:179]
	v_mfma_f32_16x16x32_bf16 v[66:69], v[142:145], v[66:69], v[50:53]
	s_nop 3
	v_cvt_pk_bf16_f32 v32, v160, v161
	v_cvt_pk_bf16_f32 v33, v162, v163
	v_mfma_f32_16x16x32_bf16 v[152:155], v[130:133], v[70:73], v[152:155]
	v_mfma_f32_16x16x32_bf16 v[58:61], v[134:137], v[70:73], v[42:45]
	v_mfma_f32_16x16x32_bf16 v[50:53], v[138:141], v[70:73], v[180:183]
	v_mfma_f32_16x16x32_bf16 v[42:45], v[142:145], v[70:73], v[34:37]
	v_cvt_pk_bf16_f32 v70, v126, v127
	v_cvt_pk_bf16_f32 v71, v128, v129
	v_cvt_pk_bf16_f32 v72, v122, v123
	v_cvt_pk_bf16_f32 v73, v124, v125
	ds_write2_b64 v150, v[70:71], v[72:73] offset1:4
	v_cvt_pk_bf16_f32 v70, v118, v119
	v_cvt_pk_bf16_f32 v71, v120, v121
	v_cvt_pk_bf16_f32 v72, v114, v115
	v_cvt_pk_bf16_f32 v73, v116, v117
	ds_write2_b64 v150, v[70:71], v[72:73] offset0:8 offset1:12
	v_cvt_pk_bf16_f32 v70, v110, v111
	v_cvt_pk_bf16_f32 v71, v112, v113
	v_cvt_pk_bf16_f32 v72, v106, v107
	v_cvt_pk_bf16_f32 v73, v108, v109
	ds_write2_b64 v0, v[70:71], v[72:73] offset0:32 offset1:36
	v_cvt_pk_bf16_f32 v70, v102, v103
	v_cvt_pk_bf16_f32 v71, v104, v105
	v_cvt_pk_bf16_f32 v72, v98, v99
	v_cvt_pk_bf16_f32 v73, v100, v101
	ds_write2_b64 v0, v[70:71], v[72:73] offset0:40 offset1:44
	v_cvt_pk_bf16_f32 v70, v94, v95
	v_cvt_pk_bf16_f32 v71, v96, v97
	v_cvt_pk_bf16_f32 v72, v90, v91
	v_cvt_pk_bf16_f32 v73, v92, v93
	v_add_u32_e32 v0, 0x2000, v150
	ds_write2_b64 v0, v[70:71], v[72:73] offset0:64 offset1:68
	v_cvt_pk_bf16_f32 v70, v86, v87
	v_cvt_pk_bf16_f32 v71, v88, v89
	ds_write2_b64 v0, v[70:71], v[62:63] offset0:72 offset1:76
	v_add_u32_e32 v0, 0x3000, v150
	v_mfma_f32_16x16x32_bf16 v[22:25], v[138:141], v[74:77], v[22:25]
	ds_write2_b64 v0, v[54:55], v[46:47] offset0:96 offset1:100
	ds_write2_b64 v0, v[38:39], v[30:31] offset0:104 offset1:108
	v_cvt_pk_bf16_f32 v30, v82, v83
	v_mfma_f32_16x16x32_bf16 v[18:21], v[142:145], v[74:77], v[18:21]
	v_cvt_pk_bf16_f32 v31, v84, v85
	v_add_u32_e32 v0, 0x4000, v150
	ds_write2_b64 v0, v[30:31], v[32:33] offset0:128 offset1:132
	v_cvt_pk_bf16_f32 v30, v164, v165
	v_cvt_pk_bf16_f32 v31, v166, v167
	v_cvt_pk_bf16_f32 v32, v66, v67
	v_cvt_pk_bf16_f32 v33, v68, v69
	v_mfma_f32_16x16x32_bf16 v[34:37], v[130:133], v[74:77], v[156:159]
	ds_write2_b64 v0, v[30:31], v[32:33] offset0:136 offset1:140
	v_cvt_pk_bf16_f32 v30, v152, v153
	v_cvt_pk_bf16_f32 v31, v154, v155
	v_mfma_f32_16x16x32_bf16 v[26:29], v[134:137], v[74:77], v[26:29]
	v_cvt_pk_bf16_f32 v32, v58, v59
	v_cvt_pk_bf16_f32 v33, v60, v61
	v_add_u32_e32 v0, 0x5000, v150
	v_mfma_f32_16x16x32_bf16 v[6:9], v[138:141], v[78:81], v[6:9]
	ds_write2_b64 v0, v[30:31], v[32:33] offset0:160 offset1:164
	v_cvt_pk_bf16_f32 v30, v50, v51
	v_cvt_pk_bf16_f32 v31, v52, v53
	v_mfma_f32_16x16x32_bf16 v[2:5], v[142:145], v[78:81], v[2:5]
	v_cvt_pk_bf16_f32 v32, v42, v43
	v_cvt_pk_bf16_f32 v33, v44, v45
	ds_write2_b64 v0, v[30:31], v[32:33] offset0:168 offset1:172
	v_mfma_f32_16x16x32_bf16 v[14:17], v[130:133], v[78:81], v[14:17]
	v_add_u32_e32 v0, 0x6000, v150
	v_cvt_pk_bf16_f32 v22, v22, v23
	v_cvt_pk_bf16_f32 v23, v24, v25
	v_mfma_f32_16x16x32_bf16 v[10:13], v[134:137], v[78:81], v[10:13]
	v_cvt_pk_bf16_f32 v18, v18, v19
	v_cvt_pk_bf16_f32 v19, v20, v21
	ds_write2_b64 v0, v[22:23], v[18:19] offset0:200 offset1:204
	v_lshl_or_b32 v22, s41, 6, v168
	v_cvt_pk_bf16_f32 v30, v34, v35
	v_cvt_pk_bf16_f32 v31, v36, v37
	v_cvt_pk_bf16_f32 v26, v26, v27
	v_cvt_pk_bf16_f32 v27, v28, v29
	v_cvt_pk_bf16_f32 v6, v6, v7
	v_cvt_pk_bf16_f32 v7, v8, v9
	v_cvt_pk_bf16_f32 v2, v2, v3
	v_cvt_pk_bf16_f32 v3, v4, v5
	v_ashrrev_i32_e32 v23, 31, v22
	ds_write2_b64 v0, v[30:31], v[26:27] offset0:192 offset1:196
	v_cvt_pk_bf16_f32 v14, v14, v15
	v_cvt_pk_bf16_f32 v15, v16, v17
	v_cvt_pk_bf16_f32 v10, v10, v11
	v_cvt_pk_bf16_f32 v11, v12, v13
	ds_write2_b64 v149, v[6:7], v[2:3] offset0:8 offset1:12
	v_add_u32_e32 v0, 0xb00, v22
	v_lshlrev_b64 v[2:3], 2, v[22:23]
	ds_write2_b64 v149, v[14:15], v[10:11] offset1:4
	v_lshl_add_u64 v[4:5], s[12:13], 0, v[2:3]
	v_lshl_add_u64 v[6:7], s[16:17], 0, v[2:3]
	v_lshl_add_u64 v[10:11], s[18:19], 0, v[2:3]
	v_lshl_add_u64 v[14:15], s[14:15], 0, v[2:3]
	v_lshlrev_b64 v[2:3], 2, v[0:1]
	s_waitcnt lgkmcnt(0)
	s_barrier
	v_lshl_add_u64 v[24:25], s[12:13], 0, v[2:3]
	v_lshl_add_u64 v[26:27], s[16:17], 0, v[2:3]
	v_lshl_add_u64 v[28:29], s[18:19], 0, v[2:3]
	v_lshl_add_u64 v[30:31], s[14:15], 0, v[2:3]
	ds_read_b64 v[32:33], v170
	ds_read_b64 v[34:35], v171
	ds_read2_b64 v[18:21], v148 offset1:16
	global_load_dwordx4 v[2:5], v[4:5], off
	s_nop 0
	global_load_dwordx4 v[6:9], v[6:7], off
	s_nop 0
	global_load_dwordx4 v[10:13], v[10:11], off
	s_nop 0
	global_load_dwordx4 v[14:17], v[14:15], off
	s_nop 0
	global_load_dwordx4 v[52:55], v[24:25], off
	global_load_dwordx4 v[56:59], v[26:27], off
	global_load_dwordx4 v[60:63], v[28:29], off
	global_load_dwordx4 v[64:67], v[30:31], off
	v_add_u32_e32 v0, s40, v169
	s_waitcnt lgkmcnt(2)
	v_lshlrev_b32_e32 v44, 16, v32
	s_waitcnt lgkmcnt(1)
	v_and_b32_e32 v45, 0xffff0000, v34
	v_lshlrev_b32_e32 v46, 16, v34
	v_and_b32_e32 v47, 0xffff0000, v32
	s_waitcnt lgkmcnt(0)
	v_lshlrev_b32_e32 v48, 16, v18
	v_and_b32_e32 v49, 0xffff0000, v20
	v_lshlrev_b32_e32 v50, 16, v20
	v_and_b32_e32 v51, 0xffff0000, v18
	v_lshlrev_b32_e32 v36, 16, v33
	v_and_b32_e32 v37, 0xffff0000, v35
	v_lshlrev_b32_e32 v38, 16, v35
	v_and_b32_e32 v39, 0xffff0000, v33
	v_lshlrev_b32_e32 v40, 16, v19
	v_and_b32_e32 v41, 0xffff0000, v21
	v_lshlrev_b32_e32 v42, 16, v21
	v_and_b32_e32 v43, 0xffff0000, v19
	v_lshl_add_u64 v[18:19], v[22:23], 1, s[10:11]
	v_add_u32_e32 v68, s39, v0
	s_mov_b32 s39, 0
	s_waitcnt vmcnt(7)
	v_mov_b32_e32 v25, v5
	s_waitcnt vmcnt(6)
	v_mov_b32_e32 v23, v9
	s_waitcnt vmcnt(5)
	v_mov_b32_e32 v21, v13
	s_waitcnt vmcnt(4)
	v_mov_b32_e32 v27, v17
	s_waitcnt vmcnt(3)
	v_mov_b32_e32 v24, v54
	s_waitcnt vmcnt(2)
	v_mov_b32_e32 v22, v58
	s_waitcnt vmcnt(1)
	v_mov_b32_e32 v20, v62
	s_waitcnt vmcnt(0)
	v_mov_b32_e32 v26, v66
	v_mov_b32_e32 v13, v63
	v_mov_b32_e32 v9, v59
	v_mov_b32_e32 v5, v55
	v_mov_b32_e32 v17, v67
	v_mov_b32_e32 v28, v60
	v_mov_b32_e32 v29, v11
	v_mov_b32_e32 v30, v56
	v_mov_b32_e32 v31, v7
	v_mov_b32_e32 v32, v52
	v_mov_b32_e32 v33, v3
	v_mov_b32_e32 v34, v64
	v_mov_b32_e32 v35, v15
	v_mov_b32_e32 v11, v61
	v_mov_b32_e32 v7, v57
	v_mov_b32_e32 v3, v53
	v_mov_b32_e32 v15, v65
	s_branch .LBB0_145

.LBB0_175:
	s_nop 0
	v_lshl_add_u32 v10, s26, 14, v126
	v_add_u32_e32 v13, 0x1000, v10
	v_readfirstlane_b32 s2, v10
	s_waitcnt vmcnt(4) lgkmcnt(0)
	s_barrier
	v_add_u32_e32 v11, 0x2000, v10
	s_mov_b32 m0, s2
	v_readfirstlane_b32 s2, v13
	v_add_u32_e32 v12, 0x3000, v10
	global_load_lds_dwordx4 v[116:117], off
	s_mov_b32 m0, s2
	v_readfirstlane_b32 s2, v11
	v_lshl_add_u64 v[120:121], v[118:119], 0, s[12:13]
	global_load_lds_dwordx4 v[114:115], off
	s_mov_b32 m0, s2
	v_readfirstlane_b32 s2, v12
	global_load_lds_dwordx4 v[120:121], off
	s_mov_b32 m0, s2
	s_lshl_b32 s2, s27, 14
	v_lshl_add_u64 v[10:11], v[120:121], 0, s[40:41]
	s_add_i32 s2, s2, 0
	global_load_lds_dwordx4 v[10:11], off
	v_add3_u32 v10, s2, v128, v0
	ds_read_b128 v[98:101], v10 offset:8192
	ds_read_b128 v[102:105], v10 offset:9216
	ds_read_b128 v[106:109], v10 offset:10240
	ds_read_b128 v[110:113], v10 offset:11264
	v_add3_u32 v10, s2, v127, v0
	ds_read_b128 v[78:81], v10
	ds_read_b128 v[82:85], v10 offset:1024
	ds_read_b128 v[94:97], v10 offset:2048
	ds_read_b128 v[130:133], v10 offset:3072
	s_add_i32 s2, s27, 1
	s_cmp_lg_u32 s27, 2
	s_cselect_b32 s2, s2, 0
	s_add_i32 s27, s26, 1
	s_cmp_lg_u32 s26, 2
	s_cselect_b32 s27, s27, 0
	s_waitcnt lgkmcnt(0)
	s_setprio 1
	v_mfma_f32_16x16x32_bf16 v[10:13], v[98:101], v[78:81], v[74:77]
	v_lshl_add_u64 v[124:125], v[116:117], 0, 64
	s_setprio 0
	s_waitcnt vmcnt(4) lgkmcnt(0)
	s_barrier
	s_setprio 1
	v_mfma_f32_16x16x32_bf16 v[14:17], v[102:105], v[78:81], v[70:73]
	s_setprio 0
	v_lshl_add_u64 v[122:123], v[114:115], 0, 64
	v_lshl_add_u64 v[142:143], v[116:117], 0, s[78:79]
	s_setprio 1
	v_mfma_f32_16x16x32_bf16 v[30:33], v[106:109], v[78:81], v[66:69]
	v_lshl_add_u64 v[144:145], v[114:115], 0, s[78:79]
	v_lshl_add_u64 v[116:117], v[116:117], 0, s[84:85]
	v_lshl_add_u64 v[114:115], v[114:115], 0, s[84:85]
	v_mfma_f32_16x16x32_bf16 v[66:69], v[110:113], v[78:81], v[62:65]
	v_mfma_f32_16x16x32_bf16 v[70:73], v[98:101], v[82:85], v[58:61]
	v_mfma_f32_16x16x32_bf16 v[74:77], v[102:105], v[82:85], v[54:57]
	v_mfma_f32_16x16x32_bf16 v[78:81], v[106:109], v[82:85], v[50:53]
	v_mfma_f32_16x16x32_bf16 v[46:49], v[110:113], v[82:85], v[46:49]
	v_mfma_f32_16x16x32_bf16 v[82:85], v[98:101], v[94:97], v[42:45]
	v_mfma_f32_16x16x32_bf16 v[86:89], v[102:105], v[94:97], v[38:41]
	v_mfma_f32_16x16x32_bf16 v[90:93], v[106:109], v[94:97], v[34:37]
	v_mfma_f32_16x16x32_bf16 v[94:97], v[110:113], v[94:97], v[26:29]
	v_mfma_f32_16x16x32_bf16 v[110:113], v[110:113], v[130:133], v[2:5]
	s_nop 2
	v_lshl_add_u32 v2, s27, 14, v126
	v_add_u32_e32 v3, 0x1000, v2
	v_readfirstlane_b32 s26, v2
	v_add_u32_e32 v5, 0x2000, v2
	s_mov_b32 m0, s26
	v_readfirstlane_b32 s26, v3
	v_add_u32_e32 v4, 0x3000, v2
	global_load_lds_dwordx4 v[124:125], off
	s_mov_b32 m0, s26
	v_readfirstlane_b32 s26, v5
	global_load_lds_dwordx4 v[122:123], off
	v_lshl_add_u64 v[2:3], v[120:121], 0, 64
	s_mov_b32 m0, s26
	v_readfirstlane_b32 s26, v4
	global_load_lds_dwordx4 v[2:3], off
	s_mov_b32 m0, s26
	s_lshl_b32 s26, s2, 14
	v_lshl_add_u64 v[2:3], v[120:121], 0, s[36:37]
	s_add_i32 s26, s26, 0
	v_mfma_f32_16x16x32_bf16 v[102:105], v[102:105], v[130:133], v[18:21]
	global_load_lds_dwordx4 v[2:3], off
	v_add3_u32 v26, s26, v127, v0
	s_nop 0
	v_add3_u32 v18, s26, v128, v0
	v_mfma_f32_16x16x32_bf16 v[98:101], v[98:101], v[130:133], v[22:25]
	s_add_i32 s26, s2, 1
	s_cmp_lg_u32 s2, 2
	s_cselect_b32 s26, s26, 0
	v_mfma_f32_16x16x32_bf16 v[106:109], v[106:109], v[130:133], v[6:9]
	s_setprio 0
	ds_read_b128 v[2:5], v18 offset:8192
	s_nop 1
	ds_read_b128 v[6:9], v18 offset:9216
	ds_read_b128 v[122:125], v18 offset:10240
	ds_read_b128 v[130:133], v18 offset:11264
	s_add_i32 s2, s27, 1
	ds_read_b128 v[18:21], v26
	ds_read_b128 v[22:25], v26 offset:1024
	ds_read_b128 v[134:137], v26 offset:2048
	ds_read_b128 v[138:141], v26 offset:3072
	s_cmp_lg_u32 s27, 2
	s_cselect_b32 s2, s2, 0
	s_waitcnt lgkmcnt(0)
	s_setprio 1
	v_mfma_f32_16x16x32_bf16 v[50:53], v[130:133], v[18:21], v[66:69]
	s_setprio 0
	s_waitcnt vmcnt(4) lgkmcnt(0)
	s_barrier
	s_setprio 1
	v_mfma_f32_16x16x32_bf16 v[62:65], v[2:5], v[18:21], v[10:13]
	s_nop 0
	v_lshl_add_u32 v66, s2, 14, v126
	v_add_u32_e32 v67, 0x1000, v66
	v_readfirstlane_b32 s27, v66
	v_add_u32_e32 v69, 0x2000, v66
	s_mov_b32 m0, s27
	v_readfirstlane_b32 s27, v67
	v_add_u32_e32 v68, 0x3000, v66
	global_load_lds_dwordx4 v[142:143], off
	s_mov_b32 m0, s27
	v_readfirstlane_b32 s27, v69
	global_load_lds_dwordx4 v[144:145], off
	v_lshl_add_u64 v[66:67], v[120:121], 0, s[78:79]
	s_mov_b32 m0, s27
	v_readfirstlane_b32 s27, v68
	global_load_lds_dwordx4 v[66:67], off
	v_lshl_add_u64 v[66:67], v[120:121], 0, s[50:51]
	s_mov_b32 m0, s27
	s_lshl_b32 s27, s26, 14
	global_load_lds_dwordx4 v[66:67], off
	s_add_i32 s27, s27, 0
	v_add3_u32 v66, s27, v128, v0
	v_mfma_f32_16x16x32_bf16 v[58:61], v[6:9], v[18:21], v[14:17]
	v_mfma_f32_16x16x32_bf16 v[54:57], v[122:125], v[18:21], v[30:33]
	v_mfma_f32_16x16x32_bf16 v[34:37], v[2:5], v[22:25], v[70:73]
	v_mfma_f32_16x16x32_bf16 v[38:41], v[6:9], v[22:25], v[74:77]
	v_mfma_f32_16x16x32_bf16 v[42:45], v[122:125], v[22:25], v[78:81]
	v_mfma_f32_16x16x32_bf16 v[46:49], v[130:133], v[22:25], v[46:49]
	v_mfma_f32_16x16x32_bf16 v[18:21], v[2:5], v[134:137], v[82:85]
	v_mfma_f32_16x16x32_bf16 v[22:25], v[6:9], v[134:137], v[86:89]
	v_mfma_f32_16x16x32_bf16 v[26:29], v[122:125], v[134:137], v[90:93]
	s_setprio 0
	ds_read_b128 v[78:81], v66 offset:8192
	ds_read_b128 v[82:85], v66 offset:9216
	ds_read_b128 v[86:89], v66 offset:10240
	ds_read_b128 v[90:93], v66 offset:11264
	v_add3_u32 v66, s27, v127, v0
	s_add_i32 s27, s26, 1
	s_setprio 1
	v_mfma_f32_16x16x32_bf16 v[30:33], v[130:133], v[134:137], v[94:97]
	s_cmp_lg_u32 s26, 2
	s_cselect_b32 s27, s27, 0
	s_add_i32 s26, s2, 1
	v_mfma_f32_16x16x32_bf16 v[2:5], v[2:5], v[138:141], v[98:101]
	s_cmp_lg_u32 s2, 2
	s_cselect_b32 s26, s26, 0
	s_add_u32 s12, s12, 0xc0
	v_mfma_f32_16x16x32_bf16 v[6:9], v[6:9], v[138:141], v[102:105]
	s_addc_u32 s13, s13, 0
	s_cmpk_eq_i32 s12, 0x780
	v_mfma_f32_16x16x32_bf16 v[10:13], v[122:125], v[138:141], v[106:109]
	s_setprio 0
	ds_read_b128 v[94:97], v66
	ds_read_b128 v[98:101], v66 offset:1024
	ds_read_b128 v[102:105], v66 offset:2048
	ds_read_b128 v[106:109], v66 offset:3072
	s_setprio 1
	v_mfma_f32_16x16x32_bf16 v[14:17], v[130:133], v[138:141], v[110:113]
	s_setprio 0
	s_waitcnt lgkmcnt(0)
	s_setprio 1
	v_mfma_f32_16x16x32_bf16 v[74:77], v[78:81], v[94:97], v[62:65]
	v_mfma_f32_16x16x32_bf16 v[70:73], v[82:85], v[94:97], v[58:61]
	v_mfma_f32_16x16x32_bf16 v[66:69], v[86:89], v[94:97], v[54:57]
	v_mfma_f32_16x16x32_bf16 v[62:65], v[90:93], v[94:97], v[50:53]
	v_mfma_f32_16x16x32_bf16 v[58:61], v[78:81], v[98:101], v[34:37]
	v_mfma_f32_16x16x32_bf16 v[54:57], v[82:85], v[98:101], v[38:41]
	v_mfma_f32_16x16x32_bf16 v[50:53], v[86:89], v[98:101], v[42:45]
	v_mfma_f32_16x16x32_bf16 v[46:49], v[90:93], v[98:101], v[46:49]
	v_mfma_f32_16x16x32_bf16 v[42:45], v[78:81], v[102:105], v[18:21]
	v_mfma_f32_16x16x32_bf16 v[38:41], v[82:85], v[102:105], v[22:25]
	v_mfma_f32_16x16x32_bf16 v[34:37], v[86:89], v[102:105], v[26:29]
	v_mfma_f32_16x16x32_bf16 v[26:29], v[90:93], v[102:105], v[30:33]
	v_mfma_f32_16x16x32_bf16 v[22:25], v[78:81], v[106:109], v[2:5]
	v_mfma_f32_16x16x32_bf16 v[18:21], v[82:85], v[106:109], v[6:9]
	v_mfma_f32_16x16x32_bf16 v[6:9], v[86:89], v[106:109], v[10:13]
	v_mfma_f32_16x16x32_bf16 v[2:5], v[90:93], v[106:109], v[14:17]
	s_setprio 0
	s_cbranch_scc0 .LBB0_175
	s_waitcnt vmcnt(4) lgkmcnt(0)
	s_barrier
	v_add3_u32 v98, 0, v128, v0
	v_add3_u32 v0, 0, v127, v0
	ds_read_b128 v[10:13], v98 offset:8192
	ds_read_b128 v[14:17], v98 offset:9216
	ds_read_b128 v[30:33], v98 offset:10240
	ds_read_b128 v[78:81], v98 offset:11264
	ds_read_b128 v[82:85], v0
	ds_read_b128 v[86:89], v0 offset:1024
	ds_read_b128 v[90:93], v0 offset:2048
	ds_read_b128 v[94:97], v0 offset:3072
	s_waitcnt vmcnt(0) lgkmcnt(0)
	s_barrier
	s_waitcnt lgkmcnt(0)
	v_mfma_f32_16x16x32_bf16 v[74:77], v[10:13], v[82:85], v[74:77]
	s_add_u32 s2, s19, s10
	s_addc_u32 s11, s20, s11
	s_lshl_b32 s10, s25, 1
	v_mfma_f32_16x16x32_bf16 v[70:73], v[14:17], v[82:85], v[70:73]
	s_add_u32 s10, s2, s10
	s_mov_b32 s2, 0xfffffc0
	s_addc_u32 s11, s11, 0
	v_mfma_f32_16x16x32_bf16 v[66:69], v[30:33], v[82:85], v[66:69]
	s_mov_b64 s[90:91], 0x20080
	s_mov_b64 s[96:97], 0x20040
	s_mov_b64 s[76:77], 0x20000
	v_mfma_f32_16x16x32_bf16 v[62:65], v[78:81], v[82:85], v[62:65]
	v_mfma_f32_16x16x32_bf16 v[58:61], v[10:13], v[86:89], v[58:61]
	v_mfma_f32_16x16x32_bf16 v[54:57], v[14:17], v[86:89], v[54:57]
	v_mfma_f32_16x16x32_bf16 v[50:53], v[30:33], v[86:89], v[50:53]
	v_mfma_f32_16x16x32_bf16 v[46:49], v[78:81], v[86:89], v[46:49]
	v_mfma_f32_16x16x32_bf16 v[42:45], v[10:13], v[90:93], v[42:45]
	v_mfma_f32_16x16x32_bf16 v[38:41], v[14:17], v[90:93], v[38:41]
	v_mfma_f32_16x16x32_bf16 v[34:37], v[30:33], v[90:93], v[34:37]
	v_mfma_f32_16x16x32_bf16 v[26:29], v[78:81], v[90:93], v[26:29]
	v_mfma_f32_16x16x32_bf16 v[10:13], v[10:13], v[94:97], v[22:25]
	v_mfma_f32_16x16x32_bf16 v[14:17], v[14:17], v[94:97], v[18:21]
	v_mfma_f32_16x16x32_bf16 v[6:9], v[30:33], v[94:97], v[6:9]
	v_mfma_f32_16x16x32_bf16 v[2:5], v[78:81], v[94:97], v[2:5]
	s_nop 0
	ds_read_b128 v[18:21], v98 offset:24576
	ds_read_b128 v[22:25], v98 offset:25600
	ds_read_b128 v[30:33], v98 offset:26624
	ds_read_b128 v[78:81], v98 offset:27648
	ds_read_b128 v[82:85], v0 offset:16384
	ds_read_b128 v[86:89], v0 offset:17408
	ds_read_b128 v[90:93], v0 offset:18432
	ds_read_b128 v[94:97], v0 offset:19456
	s_waitcnt vmcnt(0) lgkmcnt(0)
	s_barrier
	v_mfma_f32_16x16x32_bf16 v[74:77], v[18:21], v[82:85], v[74:77]
	v_mfma_f32_16x16x32_bf16 v[70:73], v[22:25], v[82:85], v[70:73]
	v_mfma_f32_16x16x32_bf16 v[54:57], v[22:25], v[86:89], v[54:57]
	v_mfma_f32_16x16x32_bf16 v[38:41], v[22:25], v[90:93], v[38:41]
	v_mfma_f32_16x16x32_bf16 v[14:17], v[22:25], v[94:97], v[14:17]
	v_mov_b32_e32 v22, v196
	v_mfma_f32_16x16x32_bf16 v[66:69], v[30:33], v[82:85], v[66:69]
	v_and_b32_e32 v23, 15, v22
	v_and_b32_e32 v0, 64, v22
	v_lshl_add_u32 v0, v0, 1, 0
	v_mfma_f32_16x16x32_bf16 v[62:65], v[78:81], v[82:85], v[62:65]
	v_mfma_f32_16x16x32_bf16 v[58:61], v[18:21], v[86:89], v[58:61]
	v_mfma_f32_16x16x32_bf16 v[42:45], v[18:21], v[90:93], v[42:45]
	v_mfma_f32_16x16x32_bf16 v[10:13], v[18:21], v[94:97], v[10:13]
	v_lshrrev_b32_e32 v18, 1, v22
	v_and_or_b32 v19, v18, s2, v23
	v_and_b32_e32 v18, 24, v18
	v_mfma_f32_16x16x32_bf16 v[50:53], v[30:33], v[86:89], v[50:53]
	v_mul_lo_u32 v19, v19, s30
	v_add3_u32 v0, v0, v18, v19
	v_cvt_pk_bf16_f32 v18, v74, v75
	v_mfma_f32_16x16x32_bf16 v[46:49], v[78:81], v[86:89], v[46:49]
	v_cvt_pk_bf16_f32 v19, v76, v77
	v_cvt_pk_bf16_f32 v20, v70, v71
	v_cvt_pk_bf16_f32 v21, v72, v73
	v_mfma_f32_16x16x32_bf16 v[6:9], v[30:33], v[94:97], v[6:9]
	ds_write2_b64 v0, v[18:19], v[20:21] offset1:4
	v_cvt_pk_bf16_f32 v18, v66, v67
	v_cvt_pk_bf16_f32 v19, v68, v69
	v_mfma_f32_16x16x32_bf16 v[2:5], v[78:81], v[94:97], v[2:5]
	v_cvt_pk_bf16_f32 v20, v62, v63
	v_cvt_pk_bf16_f32 v21, v64, v65
	ds_write2_b64 v0, v[18:19], v[20:21] offset0:8 offset1:12
	v_cvt_pk_bf16_f32 v18, v58, v59
	v_cvt_pk_bf16_f32 v19, v60, v61
	v_cvt_pk_bf16_f32 v20, v54, v55
	v_cvt_pk_bf16_f32 v21, v56, v57
	v_add_u32_e32 v24, 0x1000, v0
	v_mfma_f32_16x16x32_bf16 v[34:37], v[30:33], v[90:93], v[34:37]
	ds_write2_b64 v24, v[18:19], v[20:21] offset0:32 offset1:36
	v_cvt_pk_bf16_f32 v18, v50, v51
	v_cvt_pk_bf16_f32 v19, v52, v53
	v_mfma_f32_16x16x32_bf16 v[26:29], v[78:81], v[90:93], v[26:29]
	v_cvt_pk_bf16_f32 v20, v46, v47
	v_cvt_pk_bf16_f32 v21, v48, v49
	ds_write2_b64 v24, v[18:19], v[20:21] offset0:40 offset1:44
	v_add_u32_e32 v24, 0x2000, v0
	v_cvt_pk_bf16_f32 v10, v10, v11
	v_cvt_pk_bf16_f32 v11, v12, v13
	v_cvt_pk_bf16_f32 v12, v14, v15
	v_cvt_pk_bf16_f32 v13, v16, v17
	v_add_u32_e32 v0, 0x3000, v0
	v_cvt_pk_bf16_f32 v6, v6, v7
	v_cvt_pk_bf16_f32 v7, v8, v9
	v_cvt_pk_bf16_f32 v2, v2, v3
	v_cvt_pk_bf16_f32 v3, v4, v5
	ds_write2_b64 v0, v[10:11], v[12:13] offset0:96 offset1:100
	ds_write2_b64 v0, v[6:7], v[2:3] offset0:104 offset1:108
	v_lshlrev_b32_e32 v0, 4, v23
	v_ashrrev_i32_e32 v2, 4, v22
	v_cvt_pk_bf16_f32 v18, v42, v43
	v_cvt_pk_bf16_f32 v19, v44, v45
	v_cvt_pk_bf16_f32 v20, v38, v39
	v_cvt_pk_bf16_f32 v21, v40, v41
	v_lshl_add_u64 v[6:7], s[10:11], 0, v[0:1]
	v_add_u32_e32 v0, 0, v0
	v_ashrrev_i32_e32 v3, 31, v2
	ds_write2_b64 v24, v[18:19], v[20:21] offset0:64 offset1:68
	v_cvt_pk_bf16_f32 v18, v34, v35
	v_cvt_pk_bf16_f32 v19, v36, v37
	v_cvt_pk_bf16_f32 v20, v26, v27
	v_cvt_pk_bf16_f32 v21, v28, v29
	v_mad_u64_u32 v[4:5], s[10:11], v2, s30, v[0:1]
	v_lshlrev_b64 v[2:3], 11, v[2:3]
	ds_write2_b64 v24, v[18:19], v[20:21] offset0:72 offset1:76
	s_waitcnt lgkmcnt(0)
	s_barrier
	v_lshl_add_u64 v[8:9], v[6:7], 0, v[2:3]
	ds_read_b128 v[2:5], v4
	s_waitcnt lgkmcnt(0)
	global_store_dwordx4 v[8:9], v[2:5], off
	s_nop 1
	v_add_u32_e32 v2, 0x100, v22
	v_ashrrev_i32_e32 v2, 4, v2
	v_ashrrev_i32_e32 v3, 31, v2
	v_mad_u64_u32 v[4:5], s[10:11], v2, s30, v[0:1]
	v_lshlrev_b64 v[2:3], 11, v[2:3]
	v_lshl_add_u64 v[8:9], v[6:7], 0, v[2:3]
	ds_read_b128 v[2:5], v4
	s_waitcnt lgkmcnt(0)
	global_store_dwordx4 v[8:9], v[2:5], off
	s_nop 1
	v_add_u32_e32 v2, 0x200, v22
	v_ashrrev_i32_e32 v2, 4, v2
	v_ashrrev_i32_e32 v3, 31, v2
	v_mad_u64_u32 v[4:5], s[10:11], v2, s30, v[0:1]
	v_lshlrev_b64 v[2:3], 11, v[2:3]
	v_lshl_add_u64 v[8:9], v[6:7], 0, v[2:3]
	ds_read_b128 v[2:5], v4
	s_waitcnt lgkmcnt(0)
	global_store_dwordx4 v[8:9], v[2:5], off
	s_nop 1
	v_add_u32_e32 v2, 0x300, v22
	v_ashrrev_i32_e32 v2, 4, v2
	v_ashrrev_i32_e32 v3, 31, v2
	v_mad_u64_u32 v[4:5], s[10:11], v2, s30, v[0:1]
	v_lshlrev_b64 v[2:3], 11, v[2:3]
	v_lshl_add_u64 v[8:9], v[6:7], 0, v[2:3]
	ds_read_b128 v[2:5], v4
	s_waitcnt lgkmcnt(0)
	global_store_dwordx4 v[8:9], v[2:5], off
	s_nop 1
	v_add_u32_e32 v2, 0x400, v22
	v_ashrrev_i32_e32 v2, 4, v2
	v_ashrrev_i32_e32 v3, 31, v2
	v_mad_u64_u32 v[4:5], s[10:11], v2, s30, v[0:1]
	v_lshlrev_b64 v[2:3], 11, v[2:3]
	v_lshl_add_u64 v[8:9], v[6:7], 0, v[2:3]
	ds_read_b128 v[2:5], v4
	s_waitcnt lgkmcnt(0)
	global_store_dwordx4 v[8:9], v[2:5], off
	s_nop 1
	v_add_u32_e32 v2, 0x500, v22
	v_ashrrev_i32_e32 v2, 4, v2
	v_ashrrev_i32_e32 v3, 31, v2
	v_mad_u64_u32 v[4:5], s[10:11], v2, s30, v[0:1]
	v_lshlrev_b64 v[2:3], 11, v[2:3]
	v_lshl_add_u64 v[8:9], v[6:7], 0, v[2:3]
	ds_read_b128 v[2:5], v4
	s_waitcnt lgkmcnt(0)
	global_store_dwordx4 v[8:9], v[2:5], off
	s_nop 1
	v_add_u32_e32 v2, 0x600, v22
	v_ashrrev_i32_e32 v2, 4, v2
	v_ashrrev_i32_e32 v3, 31, v2
	v_mad_u64_u32 v[4:5], s[10:11], v2, s30, v[0:1]
	v_lshlrev_b64 v[2:3], 11, v[2:3]
	v_lshl_add_u64 v[8:9], v[6:7], 0, v[2:3]
	ds_read_b128 v[2:5], v4
	s_waitcnt lgkmcnt(0)
	global_store_dwordx4 v[8:9], v[2:5], off
	s_nop 1
	v_add_u32_e32 v2, 0x700, v22
	v_ashrrev_i32_e32 v2, 4, v2
	v_ashrrev_i32_e32 v3, 31, v2
	v_mad_u64_u32 v[4:5], s[10:11], v2, s30, v[0:1]
	v_lshlrev_b64 v[2:3], 11, v[2:3]
	v_lshl_add_u64 v[6:7], v[6:7], 0, v[2:3]
	ds_read_b128 v[2:5], v4
	s_mov_b64 s[10:11], 0
	s_waitcnt lgkmcnt(0)
	global_store_dwordx4 v[6:7], v[2:5], off
	s_barrier

.LBB0_179:
	v_lshl_add_u64 v[138:139], v[154:155], 0, s[12:13]
	s_mov_b64 s[26:27], 0x1020080
	v_lshl_add_u64 v[140:141], v[138:139], 0, s[26:27]
	s_mov_b64 s[26:27], 0x1000080
	v_lshl_add_u64 v[142:143], v[138:139], 0, s[26:27]
	s_mul_i32 s26, s25, 0x6000
	v_add_u32_e32 v144, s26, v156
	v_add_u32_e32 v132, 0x1000, v144
	v_readfirstlane_b32 s26, v144
	s_waitcnt vmcnt(6) lgkmcnt(0)
	s_barrier
	s_mov_b32 m0, s26
	v_readfirstlane_b32 s26, v132
	v_add_u32_e32 v134, 0x2000, v144
	global_load_lds_dwordx4 v[148:149], off
	s_mov_b32 m0, s26
	v_readfirstlane_b32 s26, v134
	v_add_u32_e32 v136, 0x3000, v144
	global_load_lds_dwordx4 v[150:151], off
	s_mov_b32 m0, s26
	v_readfirstlane_b32 s26, v136
	v_add_u32_e32 v145, 0x4000, v144
	global_load_lds_dwordx4 v[152:153], off
	s_mov_b32 m0, s26
	v_readfirstlane_b32 s26, v145
	global_load_lds_dwordx4 v[146:147], off
	s_mov_b32 m0, s26
	v_lshl_add_u64 v[130:131], v[148:149], 0, 64
	global_load_lds_dwordx4 v[142:143], off
	v_add_u32_e32 v142, 0x5000, v144
	v_lshl_add_u64 v[132:133], v[150:151], 0, 64
	v_readfirstlane_b32 s26, v142
	s_mov_b32 m0, s26
	s_mov_b64 s[26:27], 0x10000c0
	global_load_lds_dwordx4 v[140:141], off
	v_lshl_add_u64 v[140:141], v[138:139], 0, s[26:27]
	s_mov_b64 s[26:27], 0x10200c0
	v_lshl_add_u64 v[138:139], v[138:139], 0, s[26:27]
	s_mul_i32 s26, s2, 0x6000
	s_add_i32 s26, s26, 0
	v_add3_u32 v159, s26, v157, v0
	ds_read_b128 v[142:145], v159 offset:16384
	ds_read_b128 v[160:163], v159 offset:17408
	ds_read_b128 v[164:167], v159 offset:18432
	ds_read_b128 v[168:171], v159 offset:19456
	v_add3_u32 v159, s26, v158, v0
	ds_read_b128 v[172:175], v159
	ds_read_b128 v[176:179], v159 offset:1024
	ds_read_b128 v[180:183], v159 offset:2048
	ds_read_b128 v[184:187], v159 offset:3072
	s_add_i32 s26, s2, 1
	s_waitcnt lgkmcnt(0)
	s_setprio 1
	v_mfma_f32_16x16x32_bf16 v[126:129], v[142:145], v[172:175], v[126:129]
	s_cmp_lg_u32 s2, 2
	s_cselect_b32 s2, s26, 0
	s_add_i32 s26, s25, 1
	v_mfma_f32_16x16x32_bf16 v[122:125], v[160:163], v[172:175], v[122:125]
	s_cmp_lg_u32 s25, 2
	s_cselect_b32 s25, s26, 0
	s_mul_i32 s26, s25, 0x6000
	v_mfma_f32_16x16x32_bf16 v[118:121], v[164:167], v[172:175], v[118:121]
	v_lshl_add_u64 v[134:135], v[152:153], 0, 64
	v_lshl_add_u64 v[136:137], v[146:147], 0, 64
	v_lshl_add_u64 v[148:149], v[148:149], 0, s[78:79]
	v_mfma_f32_16x16x32_bf16 v[114:117], v[168:171], v[172:175], v[114:117]
	v_lshl_add_u64 v[150:151], v[150:151], 0, s[78:79]
	v_lshl_add_u64 v[152:153], v[152:153], 0, s[78:79]
	v_lshl_add_u64 v[146:147], v[146:147], 0, s[78:79]
	v_mfma_f32_16x16x32_bf16 v[110:113], v[142:145], v[176:179], v[110:113]
	v_mfma_f32_16x16x32_bf16 v[106:109], v[160:163], v[176:179], v[106:109]
	v_mfma_f32_16x16x32_bf16 v[102:105], v[164:167], v[176:179], v[102:105]
	v_mfma_f32_16x16x32_bf16 v[98:101], v[168:171], v[176:179], v[98:101]
	v_mfma_f32_16x16x32_bf16 v[94:97], v[142:145], v[180:183], v[94:97]
	v_mfma_f32_16x16x32_bf16 v[90:93], v[160:163], v[180:183], v[90:93]
	v_mfma_f32_16x16x32_bf16 v[86:89], v[164:167], v[180:183], v[86:89]
	v_mfma_f32_16x16x32_bf16 v[82:85], v[168:171], v[180:183], v[82:85]
	v_mfma_f32_16x16x32_bf16 v[78:81], v[142:145], v[184:187], v[78:81]
	v_mfma_f32_16x16x32_bf16 v[74:77], v[160:163], v[184:187], v[74:77]
	v_mfma_f32_16x16x32_bf16 v[70:73], v[164:167], v[184:187], v[70:73]
	v_mfma_f32_16x16x32_bf16 v[66:69], v[168:171], v[184:187], v[66:69]
	s_setprio 0
	ds_read_b128 v[172:175], v159 offset:4096
	ds_read_b128 v[176:179], v159 offset:5120
	ds_read_b128 v[180:183], v159 offset:6144
	ds_read_b128 v[184:187], v159 offset:7168
	s_waitcnt vmcnt(6) lgkmcnt(0)
	s_barrier
	s_waitcnt lgkmcnt(0)
	s_setprio 1
	v_mfma_f32_16x16x32_bf16 v[62:65], v[142:145], v[172:175], v[62:65]
	s_setprio 0
	s_setprio 1
	v_mfma_f32_16x16x32_bf16 v[46:49], v[142:145], v[176:179], v[46:49]
	v_mfma_f32_16x16x32_bf16 v[30:33], v[142:145], v[180:183], v[30:33]
	v_mfma_f32_16x16x32_bf16 v[14:17], v[142:145], v[184:187], v[14:17]
	v_add_u32_e32 v142, s26, v156
	s_nop 0
	v_readfirstlane_b32 s26, v142
	s_mov_b32 m0, s26
	v_mfma_f32_16x16x32_bf16 v[58:61], v[160:163], v[172:175], v[58:61]
	global_load_lds_dwordx4 v[130:131], off
	v_add_u32_e32 v130, 0x1000, v142
	v_mfma_f32_16x16x32_bf16 v[54:57], v[164:167], v[172:175], v[54:57]
	v_readfirstlane_b32 s26, v130
	v_add_u32_e32 v130, 0x2000, v142
	s_mov_b32 m0, s26
	v_readfirstlane_b32 s26, v130
	v_add_u32_e32 v130, 0x3000, v142
	global_load_lds_dwordx4 v[132:133], off
	s_mov_b32 m0, s26
	v_readfirstlane_b32 s26, v130
	v_add_u32_e32 v130, 0x4000, v142
	global_load_lds_dwordx4 v[134:135], off
	s_mov_b32 m0, s26
	v_readfirstlane_b32 s26, v130
	v_add_u32_e32 v130, 0x5000, v142
	global_load_lds_dwordx4 v[136:137], off
	s_mov_b32 m0, s26
	v_readfirstlane_b32 s26, v130
	global_load_lds_dwordx4 v[140:141], off
	s_mov_b32 m0, s26
	s_mul_i32 s26, s2, 0x6000
	global_load_lds_dwordx4 v[138:139], off
	s_add_i32 s26, s26, 0
	v_add3_u32 v142, s26, v157, v0
	v_add3_u32 v159, s26, v158, v0
	v_mfma_f32_16x16x32_bf16 v[50:53], v[168:171], v[172:175], v[50:53]
	s_setprio 0
	ds_read_b128 v[130:133], v142 offset:16384
	ds_read_b128 v[134:137], v142 offset:17408
	ds_read_b128 v[138:141], v142 offset:18432
	ds_read_b128 v[142:145], v142 offset:19456
	s_add_i32 s26, s2, 1
	s_cmp_lg_u32 s2, 2
	s_setprio 1
	v_mfma_f32_16x16x32_bf16 v[42:45], v[160:163], v[176:179], v[42:45]
	s_cselect_b32 s2, s26, 0
	s_add_i32 s26, s25, 1
	s_cmp_lg_u32 s25, 2
	v_mfma_f32_16x16x32_bf16 v[38:41], v[164:167], v[176:179], v[38:41]
	s_cselect_b32 s25, s26, 0
	s_add_u32 s12, s12, 0x80
	s_addc_u32 s13, s13, 0
	v_mfma_f32_16x16x32_bf16 v[34:37], v[168:171], v[176:179], v[34:37]
	s_cmpk_eq_i32 s12, 0x780
	v_mfma_f32_16x16x32_bf16 v[26:29], v[160:163], v[180:183], v[26:29]
	v_mfma_f32_16x16x32_bf16 v[22:25], v[164:167], v[180:183], v[22:25]
	v_mfma_f32_16x16x32_bf16 v[18:21], v[168:171], v[180:183], v[18:21]
	v_mfma_f32_16x16x32_bf16 v[10:13], v[160:163], v[184:187], v[10:13]
	v_mfma_f32_16x16x32_bf16 v[6:9], v[164:167], v[184:187], v[6:9]
	v_mfma_f32_16x16x32_bf16 v[2:5], v[168:171], v[184:187], v[2:5]
	s_setprio 0
	ds_read_b128 v[160:163], v159
	ds_read_b128 v[164:167], v159 offset:1024
	ds_read_b128 v[168:171], v159 offset:2048
	ds_read_b128 v[172:175], v159 offset:3072
	s_waitcnt lgkmcnt(0)
	s_setprio 1
	v_mfma_f32_16x16x32_bf16 v[126:129], v[130:133], v[160:163], v[126:129]
	v_mfma_f32_16x16x32_bf16 v[122:125], v[134:137], v[160:163], v[122:125]
	v_mfma_f32_16x16x32_bf16 v[118:121], v[138:141], v[160:163], v[118:121]
	v_mfma_f32_16x16x32_bf16 v[114:117], v[142:145], v[160:163], v[114:117]
	v_mfma_f32_16x16x32_bf16 v[110:113], v[130:133], v[164:167], v[110:113]
	v_mfma_f32_16x16x32_bf16 v[106:109], v[134:137], v[164:167], v[106:109]
	v_mfma_f32_16x16x32_bf16 v[102:105], v[138:141], v[164:167], v[102:105]
	v_mfma_f32_16x16x32_bf16 v[98:101], v[142:145], v[164:167], v[98:101]
	v_mfma_f32_16x16x32_bf16 v[94:97], v[130:133], v[168:171], v[94:97]
	v_mfma_f32_16x16x32_bf16 v[90:93], v[134:137], v[168:171], v[90:93]
	v_mfma_f32_16x16x32_bf16 v[86:89], v[138:141], v[168:171], v[86:89]
	v_mfma_f32_16x16x32_bf16 v[82:85], v[142:145], v[168:171], v[82:85]
	v_mfma_f32_16x16x32_bf16 v[78:81], v[130:133], v[172:175], v[78:81]
	v_mfma_f32_16x16x32_bf16 v[74:77], v[134:137], v[172:175], v[74:77]
	v_mfma_f32_16x16x32_bf16 v[70:73], v[138:141], v[172:175], v[70:73]
	v_mfma_f32_16x16x32_bf16 v[66:69], v[142:145], v[172:175], v[66:69]
	s_setprio 0
	ds_read_b128 v[160:163], v159 offset:4096
	ds_read_b128 v[164:167], v159 offset:5120
	ds_read_b128 v[168:171], v159 offset:6144
	ds_read_b128 v[172:175], v159 offset:7168
	s_waitcnt lgkmcnt(0)
	s_setprio 1
	v_mfma_f32_16x16x32_bf16 v[62:65], v[130:133], v[160:163], v[62:65]
	v_mfma_f32_16x16x32_bf16 v[58:61], v[134:137], v[160:163], v[58:61]
	v_mfma_f32_16x16x32_bf16 v[54:57], v[138:141], v[160:163], v[54:57]
	v_mfma_f32_16x16x32_bf16 v[50:53], v[142:145], v[160:163], v[50:53]
	v_mfma_f32_16x16x32_bf16 v[46:49], v[130:133], v[164:167], v[46:49]
	v_mfma_f32_16x16x32_bf16 v[42:45], v[134:137], v[164:167], v[42:45]
	v_mfma_f32_16x16x32_bf16 v[38:41], v[138:141], v[164:167], v[38:41]
	v_mfma_f32_16x16x32_bf16 v[34:37], v[142:145], v[164:167], v[34:37]
	v_mfma_f32_16x16x32_bf16 v[30:33], v[130:133], v[168:171], v[30:33]
	v_mfma_f32_16x16x32_bf16 v[26:29], v[134:137], v[168:171], v[26:29]
	v_mfma_f32_16x16x32_bf16 v[22:25], v[138:141], v[168:171], v[22:25]
	v_mfma_f32_16x16x32_bf16 v[18:21], v[142:145], v[168:171], v[18:21]
	v_mfma_f32_16x16x32_bf16 v[14:17], v[130:133], v[172:175], v[14:17]
	v_mfma_f32_16x16x32_bf16 v[10:13], v[134:137], v[172:175], v[10:13]
	v_mfma_f32_16x16x32_bf16 v[6:9], v[138:141], v[172:175], v[6:9]
	v_mfma_f32_16x16x32_bf16 v[2:5], v[142:145], v[172:175], v[2:5]
	s_setprio 0
	s_cbranch_scc0 .LBB0_179
	s_waitcnt vmcnt(6) lgkmcnt(0)
	s_barrier
	v_add3_u32 v182, 0, v157, v0
	v_add3_u32 v0, 0, v158, v0
	ds_read_b128 v[130:133], v182 offset:16384
	ds_read_b128 v[134:137], v182 offset:17408
	ds_read_b128 v[138:141], v182 offset:18432
	ds_read_b128 v[142:145], v182 offset:19456
	ds_read_b128 v[146:149], v0
	ds_read_b128 v[150:153], v0 offset:1024
	ds_read_b128 v[154:157], v0 offset:2048
	ds_read_b128 v[158:161], v0 offset:3072
	s_waitcnt lgkmcnt(0)
	v_mfma_f32_16x16x32_bf16 v[126:129], v[130:133], v[146:149], v[126:129]
	s_add_u32 s2, s19, s10
	s_addc_u32 s11, s20, s11
	s_lshl_b32 s10, s24, 1
	v_mfma_f32_16x16x32_bf16 v[122:125], v[134:137], v[146:149], v[122:125]
	s_add_u32 s10, s2, s10
	s_addc_u32 s11, s11, 0
	v_mfma_f32_16x16x32_bf16 v[118:121], v[138:141], v[146:149], v[118:121]
	v_mfma_f32_16x16x32_bf16 v[114:117], v[142:145], v[146:149], v[114:117]
	v_mfma_f32_16x16x32_bf16 v[110:113], v[130:133], v[150:153], v[110:113]
	v_mfma_f32_16x16x32_bf16 v[106:109], v[134:137], v[150:153], v[106:109]
	v_mfma_f32_16x16x32_bf16 v[102:105], v[138:141], v[150:153], v[102:105]
	v_mfma_f32_16x16x32_bf16 v[98:101], v[142:145], v[150:153], v[98:101]
	v_mfma_f32_16x16x32_bf16 v[94:97], v[130:133], v[154:157], v[94:97]
	v_mfma_f32_16x16x32_bf16 v[90:93], v[134:137], v[154:157], v[90:93]
	v_mfma_f32_16x16x32_bf16 v[146:149], v[138:141], v[154:157], v[86:89]
	v_mfma_f32_16x16x32_bf16 v[82:85], v[142:145], v[154:157], v[82:85]
	v_mfma_f32_16x16x32_bf16 v[150:153], v[130:133], v[158:161], v[78:81]
	v_mfma_f32_16x16x32_bf16 v[74:77], v[134:137], v[158:161], v[74:77]
	v_mfma_f32_16x16x32_bf16 v[70:73], v[138:141], v[158:161], v[70:73]
	v_mfma_f32_16x16x32_bf16 v[154:157], v[142:145], v[158:161], v[66:69]
	s_nop 2
	ds_read_b128 v[66:69], v0 offset:4096
	ds_read_b128 v[78:81], v0 offset:5120
	ds_read_b128 v[86:89], v0 offset:6144
	ds_read_b128 v[158:161], v0 offset:7168
	s_waitcnt vmcnt(0) lgkmcnt(0)
	s_barrier
	s_waitcnt lgkmcnt(0)
	v_mfma_f32_16x16x32_bf16 v[62:65], v[130:133], v[66:69], v[62:65]
	v_mfma_f32_16x16x32_bf16 v[162:165], v[134:137], v[66:69], v[58:61]
	v_mfma_f32_16x16x32_bf16 v[166:169], v[138:141], v[66:69], v[54:57]
	v_mfma_f32_16x16x32_bf16 v[50:53], v[142:145], v[66:69], v[50:53]
	v_mfma_f32_16x16x32_bf16 v[170:173], v[130:133], v[78:81], v[46:49]
	v_mfma_f32_16x16x32_bf16 v[42:45], v[134:137], v[78:81], v[42:45]
	v_mfma_f32_16x16x32_bf16 v[38:41], v[138:141], v[78:81], v[38:41]
	v_mfma_f32_16x16x32_bf16 v[174:177], v[142:145], v[78:81], v[34:37]
	v_mfma_f32_16x16x32_bf16 v[30:33], v[130:133], v[86:89], v[30:33]
	v_mfma_f32_16x16x32_bf16 v[178:181], v[134:137], v[86:89], v[26:29]
	v_mfma_f32_16x16x32_bf16 v[22:25], v[138:141], v[86:89], v[22:25]
	v_mfma_f32_16x16x32_bf16 v[18:21], v[142:145], v[86:89], v[18:21]
	v_mfma_f32_16x16x32_bf16 v[14:17], v[130:133], v[158:161], v[14:17]
	v_mfma_f32_16x16x32_bf16 v[10:13], v[134:137], v[158:161], v[10:13]
	v_mfma_f32_16x16x32_bf16 v[6:9], v[138:141], v[158:161], v[6:9]
	v_mfma_f32_16x16x32_bf16 v[2:5], v[142:145], v[158:161], v[2:5]
	ds_read_b128 v[130:133], v182 offset:40960
	ds_read_b128 v[134:137], v182 offset:41984
	ds_read_b128 v[138:141], v182 offset:43008
	ds_read_b128 v[142:145], v182 offset:44032
	ds_read_b128 v[26:29], v0 offset:24576
	ds_read_b128 v[34:37], v0 offset:25600
	ds_read_b128 v[46:49], v0 offset:26624
	ds_read_b128 v[158:161], v0 offset:27648
	s_waitcnt lgkmcnt(0)
	v_mfma_f32_16x16x32_bf16 v[110:113], v[130:133], v[34:37], v[110:113]
	v_mfma_f32_16x16x32_bf16 v[106:109], v[134:137], v[34:37], v[106:109]
	v_mfma_f32_16x16x32_bf16 v[102:105], v[138:141], v[34:37], v[102:105]
	v_mfma_f32_16x16x32_bf16 v[98:101], v[142:145], v[34:37], v[98:101]
	v_mfma_f32_16x16x32_bf16 v[86:89], v[130:133], v[46:49], v[94:97]
	v_mfma_f32_16x16x32_bf16 v[78:81], v[134:137], v[46:49], v[90:93]
	v_mfma_f32_16x16x32_bf16 v[66:69], v[138:141], v[46:49], v[146:149]
	s_nop 5
	v_cvt_pk_bf16_f32 v86, v86, v87
	v_cvt_pk_bf16_f32 v78, v78, v79
	v_cvt_pk_bf16_f32 v79, v80, v81
	v_mfma_f32_16x16x32_bf16 v[34:37], v[138:141], v[158:161], v[70:73]
	s_nop 2
	ds_read_b128 v[70:73], v0 offset:28672
	ds_read_b128 v[90:93], v0 offset:29696
	ds_read_b128 v[94:97], v0 offset:30720
	ds_read_b128 v[146:149], v0 offset:31744
	s_waitcnt vmcnt(0) lgkmcnt(0)
	s_barrier
	v_mfma_f32_16x16x32_bf16 v[126:129], v[130:133], v[26:29], v[126:129]
	v_cvt_pk_bf16_f32 v34, v34, v35
	v_cvt_pk_bf16_f32 v35, v36, v37
	v_mfma_f32_16x16x32_bf16 v[122:125], v[134:137], v[26:29], v[122:125]
	v_cvt_pk_bf16_f32 v66, v66, v67
	v_cvt_pk_bf16_f32 v67, v68, v69
	v_cvt_pk_bf16_f32 v87, v88, v89
	v_mfma_f32_16x16x32_bf16 v[118:121], v[138:141], v[26:29], v[118:121]
	v_mfma_f32_16x16x32_bf16 v[114:117], v[142:145], v[26:29], v[114:117]
	v_mfma_f32_16x16x32_bf16 v[58:61], v[142:145], v[46:49], v[82:85]
	v_mfma_f32_16x16x32_bf16 v[54:57], v[130:133], v[158:161], v[150:153]
	v_mfma_f32_16x16x32_bf16 v[46:49], v[134:137], v[158:161], v[74:77]
	s_nop 5
	v_cvt_pk_bf16_f32 v58, v58, v59
	v_cvt_pk_bf16_f32 v59, v60, v61
	v_cvt_pk_bf16_f32 v54, v54, v55
	v_mfma_f32_16x16x32_bf16 v[26:29], v[142:145], v[158:161], v[154:157]
	v_cvt_pk_bf16_f32 v55, v56, v57
	v_cvt_pk_bf16_f32 v46, v46, v47
	v_cvt_pk_bf16_f32 v47, v48, v49
	v_mfma_f32_16x16x32_bf16 v[150:153], v[130:133], v[70:73], v[62:65]
	v_mfma_f32_16x16x32_bf16 v[154:157], v[134:137], v[70:73], v[162:165]
	s_nop 2
	v_cvt_pk_bf16_f32 v26, v26, v27
	v_cvt_pk_bf16_f32 v27, v28, v29
	v_mfma_f32_16x16x32_bf16 v[82:85], v[138:141], v[70:73], v[166:169]
	v_mfma_f32_16x16x32_bf16 v[74:77], v[142:145], v[70:73], v[50:53]
	s_nop 0
	v_cvt_pk_bf16_f32 v28, v154, v155
	v_cvt_pk_bf16_f32 v29, v156, v157
	v_mfma_f32_16x16x32_bf16 v[70:73], v[130:133], v[90:93], v[170:173]
	v_mfma_f32_16x16x32_bf16 v[62:65], v[134:137], v[90:93], v[42:45]
	v_mfma_f32_16x16x32_bf16 v[50:53], v[138:141], v[90:93], v[38:41]
	v_mfma_f32_16x16x32_bf16 v[42:45], v[142:145], v[90:93], v[174:177]
	v_mov_b32_e32 v90, v196
	s_nop 0
	v_and_b32_e32 v0, 64, v90
	v_lshrrev_b32_e32 v92, 1, v90
	v_lshlrev_b32_e32 v0, 1, v0
	v_and_b32_e32 v92, 24, v92
	v_and_b32_e32 v91, 0xfffff8f, v90
	v_add3_u32 v0, 0, v0, v92
	v_mad_u64_u32 v[92:93], s[12:13], v91, s30, v[0:1]
	v_add_u32_e32 v48, 0x3000, v92
	v_mfma_f32_16x16x32_bf16 v[38:41], v[130:133], v[94:97], v[30:33]
	ds_write2_b64 v48, v[34:35], v[26:27] offset0:104 offset1:108
	v_cvt_pk_bf16_f32 v26, v150, v151
	v_cvt_pk_bf16_f32 v27, v152, v153
	v_mfma_f32_16x16x32_bf16 v[30:33], v[134:137], v[94:97], v[178:181]
	v_add_u32_e32 v34, 0x4000, v92
	ds_write2_b64 v34, v[26:27], v[28:29] offset0:128 offset1:132
	v_cvt_pk_bf16_f32 v26, v82, v83
	v_mfma_f32_16x16x32_bf16 v[22:25], v[138:141], v[94:97], v[22:25]
	v_cvt_pk_bf16_f32 v27, v84, v85
	v_cvt_pk_bf16_f32 v28, v74, v75
	v_cvt_pk_bf16_f32 v29, v76, v77
	v_mfma_f32_16x16x32_bf16 v[18:21], v[142:145], v[94:97], v[18:21]
	ds_write2_b64 v34, v[26:27], v[28:29] offset0:136 offset1:140
	v_cvt_pk_bf16_f32 v26, v70, v71
	v_cvt_pk_bf16_f32 v27, v72, v73
	v_cvt_pk_bf16_f32 v28, v62, v63
	v_cvt_pk_bf16_f32 v29, v64, v65
	v_add_u32_e32 v34, 0x5000, v92
	v_mfma_f32_16x16x32_bf16 v[6:9], v[138:141], v[146:149], v[6:9]
	ds_write2_b64 v34, v[26:27], v[28:29] offset0:160 offset1:164
	v_cvt_pk_bf16_f32 v26, v50, v51
	v_cvt_pk_bf16_f32 v27, v52, v53
	v_mfma_f32_16x16x32_bf16 v[2:5], v[142:145], v[146:149], v[2:5]
	v_cvt_pk_bf16_f32 v28, v42, v43
	v_cvt_pk_bf16_f32 v29, v44, v45
	v_cvt_pk_bf16_f32 v94, v126, v127
	v_cvt_pk_bf16_f32 v95, v128, v129
	v_cvt_pk_bf16_f32 v96, v122, v123
	v_cvt_pk_bf16_f32 v97, v124, v125
	ds_write2_b64 v34, v[26:27], v[28:29] offset0:168 offset1:172
	v_cvt_pk_bf16_f32 v28, v30, v31
	v_add_u32_e32 v30, 0x6000, v92
	v_cvt_pk_bf16_f32 v22, v22, v23
	v_cvt_pk_bf16_f32 v23, v24, v25
	v_cvt_pk_bf16_f32 v18, v18, v19
	v_cvt_pk_bf16_f32 v19, v20, v21
	v_mfma_f32_16x16x32_bf16 v[14:17], v[130:133], v[146:149], v[14:17]
	ds_write2_b64 v92, v[94:95], v[96:97] offset1:4
	v_cvt_pk_bf16_f32 v94, v118, v119
	v_cvt_pk_bf16_f32 v95, v120, v121
	v_mfma_f32_16x16x32_bf16 v[10:13], v[134:137], v[146:149], v[10:13]
	v_cvt_pk_bf16_f32 v96, v114, v115
	v_cvt_pk_bf16_f32 v97, v116, v117
	ds_write2_b64 v30, v[22:23], v[18:19] offset0:200 offset1:204
	v_or_b32_e32 v18, 0x70, v90
	ds_write2_b64 v92, v[94:95], v[96:97] offset0:8 offset1:12
	v_cvt_pk_bf16_f32 v94, v110, v111
	v_cvt_pk_bf16_f32 v95, v112, v113
	v_cvt_pk_bf16_f32 v96, v106, v107
	v_cvt_pk_bf16_f32 v97, v108, v109
	v_add_u32_e32 v91, 0x1000, v92
	v_mad_u64_u32 v[18:19], s[12:13], v18, s30, v[0:1]
	v_lshlrev_b32_e32 v0, 4, v90
	ds_write2_b64 v91, v[94:95], v[96:97] offset0:32 offset1:36
	v_cvt_pk_bf16_f32 v94, v102, v103
	v_cvt_pk_bf16_f32 v95, v104, v105
	v_cvt_pk_bf16_f32 v96, v98, v99
	v_cvt_pk_bf16_f32 v97, v100, v101
	v_add_u32_e32 v80, 0x2000, v92
	v_cvt_pk_bf16_f32 v6, v6, v7
	v_cvt_pk_bf16_f32 v7, v8, v9
	v_cvt_pk_bf16_f32 v2, v2, v3
	v_cvt_pk_bf16_f32 v3, v4, v5
	v_and_b32_e32 v0, 0xf0, v0
	v_ashrrev_i32_e32 v4, 4, v90
	ds_write2_b64 v91, v[94:95], v[96:97] offset0:40 offset1:44
	ds_write2_b64 v80, v[66:67], v[58:59] offset0:72 offset1:76
	ds_write2_b64 v18, v[6:7], v[2:3] offset0:8 offset1:12
	v_lshl_add_u64 v[2:3], s[10:11], 0, v[0:1]
	v_add_u32_e32 v0, 0, v0
	v_ashrrev_i32_e32 v5, 31, v4
	v_cvt_pk_bf16_f32 v26, v38, v39
	v_cvt_pk_bf16_f32 v27, v40, v41
	v_cvt_pk_bf16_f32 v29, v32, v33
	v_cvt_pk_bf16_f32 v14, v14, v15
	v_cvt_pk_bf16_f32 v15, v16, v17
	v_cvt_pk_bf16_f32 v10, v10, v11
	v_cvt_pk_bf16_f32 v11, v12, v13
	v_mad_u64_u32 v[6:7], s[10:11], v4, s30, v[0:1]
	v_lshlrev_b64 v[4:5], 11, v[4:5]
	ds_write2_b64 v80, v[86:87], v[78:79] offset0:64 offset1:68
	ds_write2_b64 v48, v[54:55], v[46:47] offset0:96 offset1:100
	ds_write2_b64 v30, v[26:27], v[28:29] offset0:192 offset1:196
	ds_write2_b64 v18, v[14:15], v[10:11] offset1:4
	s_waitcnt lgkmcnt(0)
	s_barrier
	v_lshl_add_u64 v[8:9], v[2:3], 0, v[4:5]
	ds_read_b128 v[4:7], v6
	s_waitcnt lgkmcnt(0)
	global_store_dwordx4 v[8:9], v[4:7], off
	s_nop 1
	v_add_u32_e32 v4, 0x100, v90
	v_ashrrev_i32_e32 v4, 4, v4
	v_ashrrev_i32_e32 v5, 31, v4
	v_mad_u64_u32 v[6:7], s[10:11], v4, s30, v[0:1]
	v_lshlrev_b64 v[4:5], 11, v[4:5]
	v_lshl_add_u64 v[8:9], v[2:3], 0, v[4:5]
	ds_read_b128 v[4:7], v6
	s_waitcnt lgkmcnt(0)
	global_store_dwordx4 v[8:9], v[4:7], off
	s_nop 1
	v_add_u32_e32 v4, 0x200, v90
	v_ashrrev_i32_e32 v4, 4, v4
	v_ashrrev_i32_e32 v5, 31, v4
	v_mad_u64_u32 v[6:7], s[10:11], v4, s30, v[0:1]
	v_lshlrev_b64 v[4:5], 11, v[4:5]
	v_lshl_add_u64 v[8:9], v[2:3], 0, v[4:5]
	ds_read_b128 v[4:7], v6
	s_waitcnt lgkmcnt(0)
	global_store_dwordx4 v[8:9], v[4:7], off
	s_nop 1
	v_add_u32_e32 v4, 0x300, v90
	v_ashrrev_i32_e32 v4, 4, v4
	v_ashrrev_i32_e32 v5, 31, v4
	v_mad_u64_u32 v[6:7], s[10:11], v4, s30, v[0:1]
	v_lshlrev_b64 v[4:5], 11, v[4:5]
	v_lshl_add_u64 v[8:9], v[2:3], 0, v[4:5]
	ds_read_b128 v[4:7], v6
	s_waitcnt lgkmcnt(0)
	global_store_dwordx4 v[8:9], v[4:7], off
	s_nop 1
	v_add_u32_e32 v4, 0x400, v90
	v_ashrrev_i32_e32 v4, 4, v4
	v_ashrrev_i32_e32 v5, 31, v4
	v_mad_u64_u32 v[6:7], s[10:11], v4, s30, v[0:1]
	v_lshlrev_b64 v[4:5], 11, v[4:5]
	v_lshl_add_u64 v[8:9], v[2:3], 0, v[4:5]
	ds_read_b128 v[4:7], v6
	s_waitcnt lgkmcnt(0)
	global_store_dwordx4 v[8:9], v[4:7], off
	s_nop 1
	v_add_u32_e32 v4, 0x500, v90
	v_ashrrev_i32_e32 v4, 4, v4
	v_ashrrev_i32_e32 v5, 31, v4
	v_mad_u64_u32 v[6:7], s[10:11], v4, s30, v[0:1]
	v_lshlrev_b64 v[4:5], 11, v[4:5]
	v_lshl_add_u64 v[8:9], v[2:3], 0, v[4:5]
	ds_read_b128 v[4:7], v6
	s_waitcnt lgkmcnt(0)
	global_store_dwordx4 v[8:9], v[4:7], off
	s_nop 1
	v_add_u32_e32 v4, 0x600, v90
	v_ashrrev_i32_e32 v4, 4, v4
	v_ashrrev_i32_e32 v5, 31, v4
	v_mad_u64_u32 v[6:7], s[10:11], v4, s30, v[0:1]
	v_lshlrev_b64 v[4:5], 11, v[4:5]
	v_lshl_add_u64 v[8:9], v[2:3], 0, v[4:5]
	ds_read_b128 v[4:7], v6
	s_waitcnt lgkmcnt(0)
	global_store_dwordx4 v[8:9], v[4:7], off
	s_nop 1
	v_add_u32_e32 v4, 0x700, v90
	v_ashrrev_i32_e32 v4, 4, v4
	v_ashrrev_i32_e32 v5, 31, v4
	v_mad_u64_u32 v[6:7], s[10:11], v4, s30, v[0:1]
	v_lshlrev_b64 v[4:5], 11, v[4:5]
	v_lshl_add_u64 v[8:9], v[2:3], 0, v[4:5]
	ds_read_b128 v[4:7], v6
	s_waitcnt lgkmcnt(0)
	global_store_dwordx4 v[8:9], v[4:7], off
	s_nop 1
	v_add_u32_e32 v4, 0x800, v90
	v_ashrrev_i32_e32 v4, 4, v4
	v_ashrrev_i32_e32 v5, 31, v4
	v_mad_u64_u32 v[6:7], s[10:11], v4, s30, v[0:1]
	v_lshlrev_b64 v[4:5], 11, v[4:5]
	v_lshl_add_u64 v[8:9], v[2:3], 0, v[4:5]
	ds_read_b128 v[4:7], v6
	s_waitcnt lgkmcnt(0)
	global_store_dwordx4 v[8:9], v[4:7], off
	s_nop 1
	v_add_u32_e32 v4, 0x900, v90
	v_ashrrev_i32_e32 v4, 4, v4
	v_ashrrev_i32_e32 v5, 31, v4
	v_mad_u64_u32 v[6:7], s[10:11], v4, s30, v[0:1]
	v_lshlrev_b64 v[4:5], 11, v[4:5]
	v_lshl_add_u64 v[8:9], v[2:3], 0, v[4:5]
	ds_read_b128 v[4:7], v6
	s_waitcnt lgkmcnt(0)
	global_store_dwordx4 v[8:9], v[4:7], off
	s_nop 1
	v_add_u32_e32 v4, 0xa00, v90
	v_ashrrev_i32_e32 v4, 4, v4
	v_ashrrev_i32_e32 v5, 31, v4
	v_mad_u64_u32 v[6:7], s[10:11], v4, s30, v[0:1]
	v_lshlrev_b64 v[4:5], 11, v[4:5]
	v_lshl_add_u64 v[8:9], v[2:3], 0, v[4:5]
	ds_read_b128 v[4:7], v6
	s_waitcnt lgkmcnt(0)
	global_store_dwordx4 v[8:9], v[4:7], off
	s_nop 1
	v_add_u32_e32 v4, 0xb00, v90
	v_ashrrev_i32_e32 v4, 4, v4
	v_ashrrev_i32_e32 v5, 31, v4
	v_mad_u64_u32 v[6:7], s[10:11], v4, s30, v[0:1]
	v_lshlrev_b64 v[4:5], 11, v[4:5]
	v_lshl_add_u64 v[8:9], v[2:3], 0, v[4:5]
	ds_read_b128 v[4:7], v6
	s_waitcnt lgkmcnt(0)
	global_store_dwordx4 v[8:9], v[4:7], off
	s_nop 1
	v_add_u32_e32 v4, 0xc00, v90
	v_ashrrev_i32_e32 v4, 4, v4
	v_ashrrev_i32_e32 v5, 31, v4
	v_mad_u64_u32 v[6:7], s[10:11], v4, s30, v[0:1]
	v_lshlrev_b64 v[4:5], 11, v[4:5]
	v_lshl_add_u64 v[8:9], v[2:3], 0, v[4:5]
	ds_read_b128 v[4:7], v6
	s_waitcnt lgkmcnt(0)
	global_store_dwordx4 v[8:9], v[4:7], off
	s_nop 1
	v_add_u32_e32 v4, 0xd00, v90
	v_ashrrev_i32_e32 v4, 4, v4
	v_ashrrev_i32_e32 v5, 31, v4
	v_mad_u64_u32 v[6:7], s[10:11], v4, s30, v[0:1]
	v_lshlrev_b64 v[4:5], 11, v[4:5]
	v_lshl_add_u64 v[8:9], v[2:3], 0, v[4:5]
	ds_read_b128 v[4:7], v6
	s_waitcnt lgkmcnt(0)
	global_store_dwordx4 v[8:9], v[4:7], off
	s_nop 1
	v_add_u32_e32 v4, 0xe00, v90
	v_ashrrev_i32_e32 v4, 4, v4
	v_ashrrev_i32_e32 v5, 31, v4
	v_mad_u64_u32 v[6:7], s[10:11], v4, s30, v[0:1]
	v_lshlrev_b64 v[4:5], 11, v[4:5]
	v_lshl_add_u64 v[8:9], v[2:3], 0, v[4:5]
	ds_read_b128 v[4:7], v6
	s_waitcnt lgkmcnt(0)
	global_store_dwordx4 v[8:9], v[4:7], off
	s_nop 1
	v_add_u32_e32 v4, 0xf00, v90
	v_ashrrev_i32_e32 v4, 4, v4
	v_ashrrev_i32_e32 v5, 31, v4
	v_mad_u64_u32 v[6:7], s[10:11], v4, s30, v[0:1]
	v_lshlrev_b64 v[4:5], 11, v[4:5]
	v_lshl_add_u64 v[8:9], v[2:3], 0, v[4:5]
	ds_read_b128 v[2:5], v6
	s_waitcnt lgkmcnt(0)
	global_store_dwordx4 v[8:9], v[2:5], off
	s_barrier
	s_branch .LBB0_172

.LBB0_191:
	v_lshl_add_u32 v156, s2, 14, v159
	v_add_u32_e32 v161, 0x1000, v156
	v_readfirstlane_b32 s37, v156
	s_waitcnt vmcnt(4) lgkmcnt(0)
	s_barrier
	v_add_u32_e32 v160, 0x2000, v156
	s_mov_b32 m0, s37
	v_readfirstlane_b32 s37, v161
	v_lshl_add_u64 v[152:153], v[148:149], 0, s[12:13]
	s_mov_b64 s[38:39], 0x5c0080
	v_add_u32_e32 v157, 0x3000, v156
	global_load_lds_dwordx4 v[146:147], off
	s_mov_b32 m0, s37
	v_readfirstlane_b32 s37, v160
	v_lshl_add_u64 v[150:151], v[152:153], 0, s[38:39]
	global_load_lds_dwordx4 v[144:145], off
	s_mov_b32 m0, s37
	v_readfirstlane_b32 s37, v157
	s_mov_b64 s[38:39], 0x5e0080
	global_load_lds_dwordx4 v[150:151], off
	s_mov_b32 m0, s37
	s_lshl_b32 s37, s36, 14
	v_lshl_add_u64 v[154:155], v[152:153], 0, s[38:39]
	s_add_i32 s37, s37, 0
	global_load_lds_dwordx4 v[154:155], off
	v_add3_u32 v168, s37, v158, v0
	v_add3_u32 v184, s37, v77, v0
	ds_read_b128 v[154:157], v168 offset:8192
	ds_read_b128 v[160:163], v168 offset:9216
	ds_read_b128 v[164:167], v168 offset:10240
	ds_read_b128 v[168:171], v168 offset:11264
	ds_read_b128 v[172:175], v184
	ds_read_b128 v[176:179], v184 offset:1024
	ds_read_b128 v[180:183], v184 offset:2048
	ds_read_b128 v[184:187], v184 offset:3072
	s_add_i32 s37, s36, 1
	s_cmp_lg_u32 s36, 2
	s_cselect_b32 s36, s37, 0
	s_add_i32 s37, s2, 1
	s_cmp_lg_u32 s2, 2
	s_cselect_b32 s2, s37, 0
	s_waitcnt lgkmcnt(0)
	s_setprio 1
	v_mfma_f32_16x16x32_bf16 v[62:65], v[154:157], v[172:175], v[62:65]
	s_mov_b64 s[38:39], 0x5e00c0
	v_lshl_add_u64 v[190:191], v[146:147], 0, 64
	s_setprio 0
	s_waitcnt vmcnt(4) lgkmcnt(0)
	s_setprio 1
	v_mfma_f32_16x16x32_bf16 v[46:49], v[154:157], v[176:179], v[46:49]
	s_setprio 0
	s_barrier
	v_lshl_add_u64 v[150:151], v[152:153], 0, s[38:39]
	s_setprio 1
	v_mfma_f32_16x16x32_bf16 v[34:37], v[154:157], v[180:183], v[34:37]
	s_mov_b64 s[38:39], 0x5c00c0
	v_lshl_add_u64 v[192:193], v[144:145], 0, 64
	v_lshl_add_u64 v[188:189], v[152:153], 0, s[38:39]
	v_mfma_f32_16x16x32_bf16 v[14:17], v[154:157], v[184:187], v[14:17]
	v_lshl_add_u32 v154, s2, 14, v159
	v_add_u32_e32 v157, 0x1000, v154
	v_readfirstlane_b32 s37, v154
	v_add_u32_e32 v156, 0x2000, v154
	s_mov_b32 m0, s37
	v_readfirstlane_b32 s37, v157
	v_add_u32_e32 v155, 0x3000, v154
	global_load_lds_dwordx4 v[190:191], off
	s_mov_b32 m0, s37
	v_readfirstlane_b32 s37, v156
	global_load_lds_dwordx4 v[192:193], off
	s_mov_b32 m0, s37
	v_readfirstlane_b32 s37, v155
	global_load_lds_dwordx4 v[188:189], off
	s_mov_b32 m0, s37
	s_lshl_b32 s37, s36, 14
	s_add_i32 s37, s37, 0
	v_mfma_f32_16x16x32_bf16 v[58:61], v[160:163], v[172:175], v[58:61]
	global_load_lds_dwordx4 v[150:151], off
	v_add3_u32 v188, s37, v77, v0
	v_mfma_f32_16x16x32_bf16 v[54:57], v[164:167], v[172:175], v[54:57]
	s_mov_b64 s[38:39], 0x5e0100
	v_lshl_add_u64 v[156:157], v[146:147], 0, s[78:79]
	v_lshl_add_u64 v[150:151], v[152:153], 0, s[38:39]
	v_mfma_f32_16x16x32_bf16 v[50:53], v[168:171], v[172:175], v[50:53]
	v_add3_u32 v172, s37, v158, v0
	s_add_i32 s37, s36, 1
	s_cmp_lg_u32 s36, 2
	v_mfma_f32_16x16x32_bf16 v[42:45], v[160:163], v[176:179], v[42:45]
	s_cselect_b32 s36, s37, 0
	s_add_i32 s37, s2, 1
	s_cmp_lg_u32 s2, 2
	v_mfma_f32_16x16x32_bf16 v[38:41], v[164:167], v[176:179], v[38:41]
	s_cselect_b32 s2, s37, 0
	s_mov_b64 s[38:39], 0x5c0100
	v_lshl_add_u64 v[154:155], v[144:145], 0, s[78:79]
	v_mfma_f32_16x16x32_bf16 v[30:33], v[168:171], v[176:179], v[30:33]
	v_lshl_add_u64 v[152:153], v[152:153], 0, s[38:39]
	v_lshl_add_u64 v[146:147], v[146:147], 0, s[84:85]
	v_lshl_add_u64 v[144:145], v[144:145], 0, s[84:85]
	v_mfma_f32_16x16x32_bf16 v[26:29], v[160:163], v[180:183], v[26:29]
	v_mfma_f32_16x16x32_bf16 v[22:25], v[164:167], v[180:183], v[22:25]
	v_mfma_f32_16x16x32_bf16 v[18:21], v[168:171], v[180:183], v[18:21]
	v_mfma_f32_16x16x32_bf16 v[10:13], v[160:163], v[184:187], v[10:13]
	v_mfma_f32_16x16x32_bf16 v[6:9], v[164:167], v[184:187], v[6:9]
	v_mfma_f32_16x16x32_bf16 v[2:5], v[168:171], v[184:187], v[2:5]
	s_setprio 0
	ds_read_b128 v[160:163], v172 offset:8192
	ds_read_b128 v[164:167], v172 offset:9216
	ds_read_b128 v[168:171], v172 offset:10240
	ds_read_b128 v[172:175], v172 offset:11264
	ds_read_b128 v[176:179], v188
	ds_read_b128 v[180:183], v188 offset:1024
	ds_read_b128 v[184:187], v188 offset:2048
	ds_read_b128 v[188:191], v188 offset:3072
	s_waitcnt vmcnt(4) lgkmcnt(0)
	s_waitcnt lgkmcnt(0)
	s_setprio 1
	v_mfma_f32_16x16x32_bf16 v[62:65], v[160:163], v[176:179], v[62:65]
	s_setprio 0
	s_barrier
	s_setprio 1
	v_mfma_f32_16x16x32_bf16 v[46:49], v[160:163], v[180:183], v[46:49]
	v_mfma_f32_16x16x32_bf16 v[34:37], v[160:163], v[184:187], v[34:37]
	v_mfma_f32_16x16x32_bf16 v[14:17], v[160:163], v[188:191], v[14:17]
	v_lshl_add_u32 v160, s2, 14, v159
	v_add_u32_e32 v163, 0x1000, v160
	v_readfirstlane_b32 s37, v160
	v_add_u32_e32 v162, 0x2000, v160
	s_mov_b32 m0, s37
	v_readfirstlane_b32 s37, v163
	v_add_u32_e32 v161, 0x3000, v160
	global_load_lds_dwordx4 v[156:157], off
	s_mov_b32 m0, s37
	v_readfirstlane_b32 s37, v162
	global_load_lds_dwordx4 v[154:155], off
	s_mov_b32 m0, s37
	v_readfirstlane_b32 s37, v161
	global_load_lds_dwordx4 v[152:153], off
	s_mov_b32 m0, s37
	s_lshl_b32 s37, s36, 14
	global_load_lds_dwordx4 v[150:151], off
	s_add_i32 s37, s37, 0
	v_mfma_f32_16x16x32_bf16 v[58:61], v[164:167], v[176:179], v[58:61]
	v_mfma_f32_16x16x32_bf16 v[42:45], v[164:167], v[180:183], v[42:45]
	v_mfma_f32_16x16x32_bf16 v[38:41], v[168:171], v[180:183], v[38:41]
	v_mfma_f32_16x16x32_bf16 v[30:33], v[172:175], v[180:183], v[30:33]
	v_add3_u32 v180, s37, v77, v0
	v_mfma_f32_16x16x32_bf16 v[26:29], v[164:167], v[184:187], v[26:29]
	v_mfma_f32_16x16x32_bf16 v[10:13], v[164:167], v[188:191], v[10:13]
	v_add3_u32 v164, s37, v158, v0
	s_setprio 0
	ds_read_b128 v[150:153], v164 offset:8192
	ds_read_b128 v[154:157], v164 offset:9216
	ds_read_b128 v[160:163], v164 offset:10240
	ds_read_b128 v[164:167], v164 offset:11264
	s_add_i32 s37, s36, 1
	s_setprio 1
	v_mfma_f32_16x16x32_bf16 v[54:57], v[168:171], v[176:179], v[54:57]
	s_cmp_lg_u32 s36, 2
	s_cselect_b32 s36, s37, 0
	s_add_i32 s37, s2, 1
	v_mfma_f32_16x16x32_bf16 v[50:53], v[172:175], v[176:179], v[50:53]
	s_cmp_lg_u32 s2, 2
	s_cselect_b32 s2, s37, 0
	s_add_u32 s12, s12, 0xc0
	v_mfma_f32_16x16x32_bf16 v[22:25], v[168:171], v[184:187], v[22:25]
	s_addc_u32 s13, s13, 0
	s_cmpk_eq_i32 s12, 0x780
	v_mfma_f32_16x16x32_bf16 v[18:21], v[172:175], v[184:187], v[18:21]
	v_mfma_f32_16x16x32_bf16 v[6:9], v[168:171], v[188:191], v[6:9]
	v_mfma_f32_16x16x32_bf16 v[2:5], v[172:175], v[188:191], v[2:5]
	s_setprio 0
	ds_read_b128 v[168:171], v180
	ds_read_b128 v[172:175], v180 offset:1024
	ds_read_b128 v[176:179], v180 offset:2048
	ds_read_b128 v[180:183], v180 offset:3072
	s_waitcnt lgkmcnt(0)
	s_setprio 1
	v_mfma_f32_16x16x32_bf16 v[62:65], v[150:153], v[168:171], v[62:65]
	v_mfma_f32_16x16x32_bf16 v[58:61], v[154:157], v[168:171], v[58:61]
	v_mfma_f32_16x16x32_bf16 v[54:57], v[160:163], v[168:171], v[54:57]
	v_mfma_f32_16x16x32_bf16 v[50:53], v[164:167], v[168:171], v[50:53]
	v_mfma_f32_16x16x32_bf16 v[46:49], v[150:153], v[172:175], v[46:49]
	v_mfma_f32_16x16x32_bf16 v[42:45], v[154:157], v[172:175], v[42:45]
	v_mfma_f32_16x16x32_bf16 v[38:41], v[160:163], v[172:175], v[38:41]
	v_mfma_f32_16x16x32_bf16 v[30:33], v[164:167], v[172:175], v[30:33]
	v_mfma_f32_16x16x32_bf16 v[34:37], v[150:153], v[176:179], v[34:37]
	v_mfma_f32_16x16x32_bf16 v[26:29], v[154:157], v[176:179], v[26:29]
	v_mfma_f32_16x16x32_bf16 v[22:25], v[160:163], v[176:179], v[22:25]
	v_mfma_f32_16x16x32_bf16 v[18:21], v[164:167], v[176:179], v[18:21]
	v_mfma_f32_16x16x32_bf16 v[14:17], v[150:153], v[180:183], v[14:17]
	v_mfma_f32_16x16x32_bf16 v[10:13], v[154:157], v[180:183], v[10:13]
	v_mfma_f32_16x16x32_bf16 v[6:9], v[160:163], v[180:183], v[6:9]
	v_mfma_f32_16x16x32_bf16 v[2:5], v[164:167], v[180:183], v[2:5]
	s_setprio 0
	s_cbranch_scc0 .LBB0_191
	s_waitcnt vmcnt(4) lgkmcnt(0)
	s_barrier
	v_add3_u32 v176, 0, v158, v0
	v_add3_u32 v0, 0, v77, v0
	ds_read_b128 v[144:147], v176 offset:8192
	ds_read_b128 v[148:151], v176 offset:9216
	ds_read_b128 v[152:155], v176 offset:10240
	ds_read_b128 v[156:159], v176 offset:11264
	ds_read_b128 v[160:163], v0
	ds_read_b128 v[164:167], v0 offset:1024
	ds_read_b128 v[168:171], v0 offset:2048
	ds_read_b128 v[172:175], v0 offset:3072
	s_waitcnt lgkmcnt(0)
	v_mfma_f32_16x16x32_bf16 v[58:61], v[148:151], v[160:163], v[58:61]
	s_waitcnt vmcnt(0) lgkmcnt(0)
	s_barrier
	v_mfma_f32_16x16x32_bf16 v[62:65], v[144:147], v[160:163], v[62:65]
	s_cmp_eq_u32 s26, 1
	s_cselect_b32 s2, s40, 0x1a81c000
	s_cmp_lg_u32 s26, 0
	v_mfma_f32_16x16x32_bf16 v[54:57], v[152:155], v[160:163], v[54:57]
	s_cselect_b32 s2, s2, 0xe21c000
	s_add_i32 s26, s26, 1
	s_add_u32 s10, s10, 0x200000
	v_mfma_f32_16x16x32_bf16 v[50:53], v[156:159], v[160:163], v[50:53]
	s_addc_u32 s11, s11, 0
	s_cmp_eq_u32 s26, 3
	v_mfma_f32_16x16x32_bf16 v[46:49], v[144:147], v[164:167], v[46:49]
	v_mfma_f32_16x16x32_bf16 v[42:45], v[148:151], v[164:167], v[42:45]
	v_mfma_f32_16x16x32_bf16 v[38:41], v[152:155], v[164:167], v[38:41]
	v_mfma_f32_16x16x32_bf16 v[30:33], v[156:159], v[164:167], v[30:33]
	v_mfma_f32_16x16x32_bf16 v[160:163], v[144:147], v[168:171], v[34:37]
	v_mfma_f32_16x16x32_bf16 v[26:29], v[148:151], v[168:171], v[26:29]
	v_mfma_f32_16x16x32_bf16 v[22:25], v[152:155], v[168:171], v[22:25]
	v_mfma_f32_16x16x32_bf16 v[18:21], v[156:159], v[168:171], v[18:21]
	v_mfma_f32_16x16x32_bf16 v[14:17], v[144:147], v[172:175], v[14:17]
	v_mfma_f32_16x16x32_bf16 v[10:13], v[148:151], v[172:175], v[10:13]
	v_mfma_f32_16x16x32_bf16 v[6:9], v[152:155], v[172:175], v[6:9]
	v_mfma_f32_16x16x32_bf16 v[2:5], v[156:159], v[172:175], v[2:5]
	ds_read_b128 v[144:147], v176 offset:24576
	ds_read_b128 v[148:151], v176 offset:25600
	ds_read_b128 v[152:155], v176 offset:26624
	ds_read_b128 v[156:159], v176 offset:27648
	ds_read_b128 v[34:37], v0 offset:16384
	ds_read_b128 v[164:167], v0 offset:17408
	ds_read_b128 v[168:171], v0 offset:18432
	ds_read_b128 v[172:175], v0 offset:19456
	s_waitcnt vmcnt(0) lgkmcnt(0)
	s_barrier
	v_mfma_f32_16x16x32_bf16 v[176:179], v[148:151], v[34:37], v[58:61]
	s_nop 2
	v_lshl_add_u64 v[58:59], v[114:115], 0, s[2:3]
	v_lshl_add_u64 v[60:61], v[58:59], 0, v[66:67]
	v_mfma_f32_16x16x32_bf16 v[62:65], v[144:147], v[34:37], v[62:65]
	v_mfma_f32_16x16x32_bf16 v[54:57], v[152:155], v[34:37], v[54:57]
	v_mfma_f32_16x16x32_bf16 v[50:53], v[156:159], v[34:37], v[50:53]
	s_nop 5
	v_mul_f32_e32 v0, 0xbfb8aa3b, v62
	v_exp_f32_e32 v0, v0
	v_mfma_f32_16x16x32_bf16 v[46:49], v[144:147], v[164:167], v[46:49]
	v_add_f32_e32 v0, 1.0, v0
	v_rcp_f32_e32 v62, v0
	v_mfma_f32_16x16x32_bf16 v[34:37], v[156:159], v[164:167], v[30:33]
	v_mul_f32_e32 v0, 0xbfb8aa3b, v63
	v_exp_f32_e32 v0, v0
	v_mfma_f32_16x16x32_bf16 v[30:33], v[144:147], v[168:171], v[160:163]
	v_add_f32_e32 v0, 1.0, v0
	v_rcp_f32_e32 v63, v0
	v_mfma_f32_16x16x32_bf16 v[14:17], v[144:147], v[172:175], v[14:17]
	global_load_dwordx2 v[144:145], v[60:61], off
	v_mul_f32_e32 v0, 0xbfb8aa3b, v64
	v_exp_f32_e32 v0, v0
	v_mfma_f32_16x16x32_bf16 v[42:45], v[148:151], v[164:167], v[42:45]
	v_add_f32_e32 v0, 1.0, v0
	v_mfma_f32_16x16x32_bf16 v[38:41], v[152:155], v[164:167], v[38:41]
	s_waitcnt vmcnt(0)
	v_lshlrev_b32_e32 v146, 16, v144
	v_and_b32_e32 v147, 0xffff0000, v144
	v_pk_fma_f32 v[140:141], v[62:63], v[146:147], v[140:141]
	v_rcp_f32_e32 v62, v0
	v_mul_f32_e32 v0, 0xbfb8aa3b, v65
	v_exp_f32_e32 v0, v0
	v_lshlrev_b32_e32 v144, 16, v145
	v_and_b32_e32 v145, 0xffff0000, v145
	v_mfma_f32_16x16x32_bf16 v[26:29], v[148:151], v[168:171], v[26:29]
	v_add_f32_e32 v0, 1.0, v0
	v_rcp_f32_e32 v63, v0
	v_mul_f32_e32 v0, 0xbfb8aa3b, v176
	v_exp_f32_e32 v0, v0
	v_mfma_f32_16x16x32_bf16 v[22:25], v[152:155], v[168:171], v[22:25]
	v_fma_f32 v142, v62, v144, v142
	v_fma_f32 v143, v63, v145, v143
	global_load_dwordx2 v[62:63], v[60:61], off offset:32
	v_add_f32_e32 v0, 1.0, v0
	v_rcp_f32_e32 v144, v0
	v_mul_f32_e32 v0, 0xbfb8aa3b, v177
	v_exp_f32_e32 v0, v0
	v_mfma_f32_16x16x32_bf16 v[18:21], v[156:159], v[168:171], v[18:21]
	v_add_f32_e32 v0, 1.0, v0
	v_rcp_f32_e32 v145, v0
	v_mul_f32_e32 v0, 0xbfb8aa3b, v178
	v_exp_f32_e32 v0, v0
	v_mfma_f32_16x16x32_bf16 v[10:13], v[148:151], v[172:175], v[10:13]
	v_add_f32_e32 v0, 1.0, v0
	v_mfma_f32_16x16x32_bf16 v[6:9], v[152:155], v[172:175], v[6:9]
	s_waitcnt vmcnt(0)
	v_lshlrev_b32_e32 v64, 16, v62
	v_and_b32_e32 v65, 0xffff0000, v62
	v_pk_fma_f32 v[136:137], v[144:145], v[64:65], v[136:137]
	v_rcp_f32_e32 v64, v0
	v_mul_f32_e32 v0, 0xbfb8aa3b, v179
	v_exp_f32_e32 v0, v0
	v_lshlrev_b32_e32 v62, 16, v63
	v_and_b32_e32 v63, 0xffff0000, v63
	v_mfma_f32_16x16x32_bf16 v[2:5], v[156:159], v[172:175], v[2:5]
	v_add_f32_e32 v0, 1.0, v0
	v_rcp_f32_e32 v65, v0
	v_mul_f32_e32 v0, 0xbfb8aa3b, v54
	v_exp_f32_e32 v0, v0
	v_pk_fma_f32 v[138:139], v[64:65], v[62:63], v[138:139]
	global_load_dwordx2 v[62:63], v[60:61], off offset:64
	v_add_f32_e32 v0, 1.0, v0
	v_rcp_f32_e32 v54, v0
	v_mul_f32_e32 v0, 0xbfb8aa3b, v55
	v_exp_f32_e32 v0, v0
	s_waitcnt vmcnt(0)
	v_lshlrev_b32_e32 v64, 16, v62
	v_add_f32_e32 v0, 1.0, v0
	v_rcp_f32_e32 v55, v0
	v_mul_f32_e32 v0, 0xbfb8aa3b, v56
	v_exp_f32_e32 v0, v0
	v_and_b32_e32 v65, 0xffff0000, v62
	v_pk_fma_f32 v[132:133], v[54:55], v[64:65], v[132:133]
	v_lshlrev_b32_e32 v62, 16, v63
	v_add_f32_e32 v0, 1.0, v0
	v_rcp_f32_e32 v54, v0
	v_mul_f32_e32 v0, 0xbfb8aa3b, v57
	v_exp_f32_e32 v0, v0
	v_and_b32_e32 v63, 0xffff0000, v63
	v_add_f32_e32 v0, 1.0, v0
	v_rcp_f32_e32 v55, v0
	v_mul_f32_e32 v0, 0xbfb8aa3b, v50
	v_exp_f32_e32 v0, v0
	v_pk_fma_f32 v[134:135], v[54:55], v[62:63], v[134:135]
	global_load_dwordx2 v[54:55], v[60:61], off offset:96
	v_add_f32_e32 v0, 1.0, v0
	v_rcp_f32_e32 v50, v0
	v_mul_f32_e32 v0, 0xbfb8aa3b, v51
	v_exp_f32_e32 v0, v0
	s_waitcnt vmcnt(0)
	v_lshlrev_b32_e32 v56, 16, v54
	v_add_f32_e32 v0, 1.0, v0
	v_rcp_f32_e32 v51, v0
	v_mul_f32_e32 v0, 0xbfb8aa3b, v52
	v_exp_f32_e32 v0, v0
	v_and_b32_e32 v57, 0xffff0000, v54
	v_pk_fma_f32 v[128:129], v[50:51], v[56:57], v[128:129]
	v_lshlrev_b32_e32 v54, 16, v55
	v_add_f32_e32 v0, 1.0, v0
	v_rcp_f32_e32 v50, v0
	v_mul_f32_e32 v0, 0xbfb8aa3b, v53
	v_exp_f32_e32 v0, v0
	v_and_b32_e32 v55, 0xffff0000, v55
	v_add_f32_e32 v0, 1.0, v0
	v_rcp_f32_e32 v51, v0
	v_mul_f32_e32 v0, 0xbfb8aa3b, v46
	v_exp_f32_e32 v0, v0
	v_pk_fma_f32 v[130:131], v[50:51], v[54:55], v[130:131]
	v_lshl_add_u64 v[50:51], v[58:59], 0, v[68:69]
	global_load_dwordx2 v[52:53], v[50:51], off
	v_add_f32_e32 v0, 1.0, v0
	v_rcp_f32_e32 v46, v0
	v_mul_f32_e32 v0, 0xbfb8aa3b, v47
	v_exp_f32_e32 v0, v0
	s_waitcnt vmcnt(0)
	v_lshlrev_b32_e32 v54, 16, v52
	v_add_f32_e32 v0, 1.0, v0
	v_rcp_f32_e32 v47, v0
	v_mul_f32_e32 v0, 0xbfb8aa3b, v48
	v_exp_f32_e32 v0, v0
	v_and_b32_e32 v55, 0xffff0000, v52
	v_pk_fma_f32 v[124:125], v[46:47], v[54:55], v[124:125]
	v_lshlrev_b32_e32 v52, 16, v53
	v_add_f32_e32 v0, 1.0, v0
	v_rcp_f32_e32 v46, v0
	v_mul_f32_e32 v0, 0xbfb8aa3b, v49
	v_exp_f32_e32 v0, v0
	v_and_b32_e32 v53, 0xffff0000, v53
	v_add_f32_e32 v0, 1.0, v0
	v_rcp_f32_e32 v47, v0
	v_mul_f32_e32 v0, 0xbfb8aa3b, v42
	v_exp_f32_e32 v0, v0
	v_pk_fma_f32 v[126:127], v[46:47], v[52:53], v[126:127]
	global_load_dwordx2 v[46:47], v[50:51], off offset:32
	v_add_f32_e32 v0, 1.0, v0
	v_rcp_f32_e32 v42, v0
	v_mul_f32_e32 v0, 0xbfb8aa3b, v43
	v_exp_f32_e32 v0, v0
	s_waitcnt vmcnt(0)
	v_lshlrev_b32_e32 v48, 16, v46
	v_add_f32_e32 v0, 1.0, v0
	v_rcp_f32_e32 v43, v0
	v_mul_f32_e32 v0, 0xbfb8aa3b, v44
	v_exp_f32_e32 v0, v0
	v_and_b32_e32 v49, 0xffff0000, v46
	v_pk_fma_f32 v[120:121], v[42:43], v[48:49], v[120:121]
	v_lshlrev_b32_e32 v46, 16, v47
	v_add_f32_e32 v0, 1.0, v0
	v_rcp_f32_e32 v42, v0
	v_mul_f32_e32 v0, 0xbfb8aa3b, v45
	v_exp_f32_e32 v0, v0
	v_and_b32_e32 v47, 0xffff0000, v47
	v_add_f32_e32 v0, 1.0, v0
	v_rcp_f32_e32 v43, v0
	v_mul_f32_e32 v0, 0xbfb8aa3b, v38
	v_exp_f32_e32 v0, v0
	v_pk_fma_f32 v[122:123], v[42:43], v[46:47], v[122:123]
	global_load_dwordx2 v[42:43], v[50:51], off offset:64
	v_add_f32_e32 v0, 1.0, v0
	v_rcp_f32_e32 v38, v0
	v_mul_f32_e32 v0, 0xbfb8aa3b, v39
	v_exp_f32_e32 v0, v0
	s_waitcnt vmcnt(0)
	v_lshlrev_b32_e32 v44, 16, v42
	v_add_f32_e32 v0, 1.0, v0
	v_rcp_f32_e32 v39, v0
	v_mul_f32_e32 v0, 0xbfb8aa3b, v40
	v_exp_f32_e32 v0, v0
	v_and_b32_e32 v45, 0xffff0000, v42
	v_pk_fma_f32 v[116:117], v[38:39], v[44:45], v[116:117]
	v_lshlrev_b32_e32 v42, 16, v43
	v_add_f32_e32 v0, 1.0, v0
	v_rcp_f32_e32 v38, v0
	v_mul_f32_e32 v0, 0xbfb8aa3b, v41
	v_exp_f32_e32 v0, v0
	v_and_b32_e32 v43, 0xffff0000, v43
	v_add_f32_e32 v0, 1.0, v0
	v_rcp_f32_e32 v39, v0
	v_mul_f32_e32 v0, 0xbfb8aa3b, v34
	v_exp_f32_e32 v0, v0
	v_pk_fma_f32 v[118:119], v[38:39], v[42:43], v[118:119]
	global_load_dwordx2 v[38:39], v[50:51], off offset:96
	v_add_f32_e32 v0, 1.0, v0
	v_rcp_f32_e32 v34, v0
	v_mul_f32_e32 v0, 0xbfb8aa3b, v35
	v_exp_f32_e32 v0, v0
	s_waitcnt vmcnt(0)
	v_lshlrev_b32_e32 v40, 16, v38
	v_add_f32_e32 v0, 1.0, v0
	v_rcp_f32_e32 v35, v0
	v_mul_f32_e32 v0, 0xbfb8aa3b, v36
	v_exp_f32_e32 v0, v0
	v_and_b32_e32 v41, 0xffff0000, v38
	v_pk_fma_f32 v[110:111], v[34:35], v[40:41], v[110:111]
	v_lshlrev_b32_e32 v38, 16, v39
	v_add_f32_e32 v0, 1.0, v0
	v_rcp_f32_e32 v34, v0
	v_mul_f32_e32 v0, 0xbfb8aa3b, v37
	v_exp_f32_e32 v0, v0
	v_and_b32_e32 v39, 0xffff0000, v39
	v_add_f32_e32 v0, 1.0, v0
	v_rcp_f32_e32 v35, v0
	v_mul_f32_e32 v0, 0xbfb8aa3b, v30
	v_exp_f32_e32 v0, v0
	v_pk_fma_f32 v[112:113], v[34:35], v[38:39], v[112:113]
	v_lshl_add_u64 v[34:35], v[58:59], 0, v[70:71]
	global_load_dwordx2 v[36:37], v[34:35], off
	v_add_f32_e32 v0, 1.0, v0
	v_rcp_f32_e32 v30, v0
	v_mul_f32_e32 v0, 0xbfb8aa3b, v31
	v_exp_f32_e32 v0, v0
	s_waitcnt vmcnt(0)
	v_lshlrev_b32_e32 v38, 16, v36
	v_add_f32_e32 v0, 1.0, v0
	v_rcp_f32_e32 v31, v0
	v_mul_f32_e32 v0, 0xbfb8aa3b, v32
	v_exp_f32_e32 v0, v0
	v_and_b32_e32 v39, 0xffff0000, v36
	v_pk_fma_f32 v[106:107], v[30:31], v[38:39], v[106:107]
	v_lshlrev_b32_e32 v36, 16, v37
	v_add_f32_e32 v0, 1.0, v0
	v_rcp_f32_e32 v30, v0
	v_mul_f32_e32 v0, 0xbfb8aa3b, v33
	v_exp_f32_e32 v0, v0
	v_and_b32_e32 v37, 0xffff0000, v37
	v_add_f32_e32 v0, 1.0, v0
	v_rcp_f32_e32 v31, v0
	v_mul_f32_e32 v0, 0xbfb8aa3b, v26
	v_exp_f32_e32 v0, v0
	v_pk_fma_f32 v[108:109], v[30:31], v[36:37], v[108:109]
	global_load_dwordx2 v[30:31], v[34:35], off offset:32
	v_add_f32_e32 v0, 1.0, v0
	v_rcp_f32_e32 v26, v0
	v_mul_f32_e32 v0, 0xbfb8aa3b, v27
	v_exp_f32_e32 v0, v0
	s_waitcnt vmcnt(0)
	v_lshlrev_b32_e32 v32, 16, v30
	v_add_f32_e32 v0, 1.0, v0
	v_rcp_f32_e32 v27, v0
	v_mul_f32_e32 v0, 0xbfb8aa3b, v28
	v_exp_f32_e32 v0, v0
	v_and_b32_e32 v33, 0xffff0000, v30
	v_pk_fma_f32 v[102:103], v[26:27], v[32:33], v[102:103]
	v_lshlrev_b32_e32 v30, 16, v31
	v_add_f32_e32 v0, 1.0, v0
	v_rcp_f32_e32 v26, v0
	v_mul_f32_e32 v0, 0xbfb8aa3b, v29
	v_exp_f32_e32 v0, v0
	v_and_b32_e32 v31, 0xffff0000, v31
	v_add_f32_e32 v0, 1.0, v0
	v_rcp_f32_e32 v27, v0
	v_mul_f32_e32 v0, 0xbfb8aa3b, v22
	v_exp_f32_e32 v0, v0
	v_pk_fma_f32 v[104:105], v[26:27], v[30:31], v[104:105]
	global_load_dwordx2 v[26:27], v[34:35], off offset:64
	v_add_f32_e32 v0, 1.0, v0
	v_rcp_f32_e32 v22, v0
	v_mul_f32_e32 v0, 0xbfb8aa3b, v23
	v_exp_f32_e32 v0, v0
	s_waitcnt vmcnt(0)
	v_lshlrev_b32_e32 v28, 16, v26
	v_add_f32_e32 v0, 1.0, v0
	v_rcp_f32_e32 v23, v0
	v_mul_f32_e32 v0, 0xbfb8aa3b, v24
	v_exp_f32_e32 v0, v0
	v_and_b32_e32 v29, 0xffff0000, v26
	v_pk_fma_f32 v[98:99], v[22:23], v[28:29], v[98:99]
	v_lshlrev_b32_e32 v26, 16, v27
	v_add_f32_e32 v0, 1.0, v0
	v_rcp_f32_e32 v22, v0
	v_mul_f32_e32 v0, 0xbfb8aa3b, v25
	v_exp_f32_e32 v0, v0
	v_and_b32_e32 v27, 0xffff0000, v27
	v_add_f32_e32 v0, 1.0, v0
	v_rcp_f32_e32 v23, v0
	v_mul_f32_e32 v0, 0xbfb8aa3b, v18
	v_exp_f32_e32 v0, v0
	v_pk_fma_f32 v[100:101], v[22:23], v[26:27], v[100:101]
	global_load_dwordx2 v[22:23], v[34:35], off offset:96
	v_add_f32_e32 v0, 1.0, v0
	v_rcp_f32_e32 v18, v0
	v_mul_f32_e32 v0, 0xbfb8aa3b, v19
	v_exp_f32_e32 v0, v0
	s_waitcnt vmcnt(0)
	v_lshlrev_b32_e32 v24, 16, v22
	v_add_f32_e32 v0, 1.0, v0
	v_rcp_f32_e32 v19, v0
	v_mul_f32_e32 v0, 0xbfb8aa3b, v20
	v_exp_f32_e32 v0, v0
	v_and_b32_e32 v25, 0xffff0000, v22
	v_pk_fma_f32 v[94:95], v[18:19], v[24:25], v[94:95]
	v_lshlrev_b32_e32 v22, 16, v23
	v_add_f32_e32 v0, 1.0, v0
	v_rcp_f32_e32 v18, v0
	v_mul_f32_e32 v0, 0xbfb8aa3b, v21
	v_exp_f32_e32 v0, v0
	v_and_b32_e32 v23, 0xffff0000, v23
	v_add_f32_e32 v0, 1.0, v0
	v_rcp_f32_e32 v19, v0
	v_mul_f32_e32 v0, 0xbfb8aa3b, v14
	v_exp_f32_e32 v0, v0
	v_pk_fma_f32 v[96:97], v[18:19], v[22:23], v[96:97]
	v_lshl_add_u64 v[18:19], v[58:59], 0, v[72:73]
	global_load_dwordx2 v[20:21], v[18:19], off
	v_add_f32_e32 v0, 1.0, v0
	v_rcp_f32_e32 v14, v0
	v_mul_f32_e32 v0, 0xbfb8aa3b, v15
	v_exp_f32_e32 v0, v0
	s_waitcnt vmcnt(0)
	v_lshlrev_b32_e32 v22, 16, v20
	v_add_f32_e32 v0, 1.0, v0
	v_rcp_f32_e32 v15, v0
	v_mul_f32_e32 v0, 0xbfb8aa3b, v16
	v_exp_f32_e32 v0, v0
	v_and_b32_e32 v23, 0xffff0000, v20
	v_pk_fma_f32 v[90:91], v[14:15], v[22:23], v[90:91]
	v_lshlrev_b32_e32 v20, 16, v21
	v_add_f32_e32 v0, 1.0, v0
	v_rcp_f32_e32 v14, v0
	v_mul_f32_e32 v0, 0xbfb8aa3b, v17
	v_exp_f32_e32 v0, v0
	v_and_b32_e32 v21, 0xffff0000, v21
	v_add_f32_e32 v0, 1.0, v0
	v_rcp_f32_e32 v15, v0
	v_mul_f32_e32 v0, 0xbfb8aa3b, v10
	v_exp_f32_e32 v0, v0
	v_pk_fma_f32 v[92:93], v[14:15], v[20:21], v[92:93]
	global_load_dwordx2 v[14:15], v[18:19], off offset:32
	v_add_f32_e32 v0, 1.0, v0
	v_rcp_f32_e32 v10, v0
	v_mul_f32_e32 v0, 0xbfb8aa3b, v11
	v_exp_f32_e32 v0, v0
	s_waitcnt vmcnt(0)
	v_lshlrev_b32_e32 v16, 16, v14
	v_add_f32_e32 v0, 1.0, v0
	v_rcp_f32_e32 v11, v0
	v_mul_f32_e32 v0, 0xbfb8aa3b, v12
	v_exp_f32_e32 v0, v0
	v_and_b32_e32 v17, 0xffff0000, v14
	v_pk_fma_f32 v[86:87], v[10:11], v[16:17], v[86:87]
	v_lshlrev_b32_e32 v14, 16, v15
	v_add_f32_e32 v0, 1.0, v0
	v_rcp_f32_e32 v10, v0
	v_mul_f32_e32 v0, 0xbfb8aa3b, v13
	v_exp_f32_e32 v0, v0
	v_and_b32_e32 v15, 0xffff0000, v15
	v_add_f32_e32 v0, 1.0, v0
	v_rcp_f32_e32 v11, v0
	v_mul_f32_e32 v0, 0xbfb8aa3b, v6
	v_exp_f32_e32 v0, v0
	v_pk_fma_f32 v[88:89], v[10:11], v[14:15], v[88:89]
	global_load_dwordx2 v[10:11], v[18:19], off offset:64
	v_add_f32_e32 v0, 1.0, v0
	v_rcp_f32_e32 v6, v0
	v_mul_f32_e32 v0, 0xbfb8aa3b, v7
	v_exp_f32_e32 v0, v0
	s_waitcnt vmcnt(0)
	v_lshlrev_b32_e32 v12, 16, v10
	v_add_f32_e32 v0, 1.0, v0
	v_rcp_f32_e32 v7, v0
	v_mul_f32_e32 v0, 0xbfb8aa3b, v8
	v_exp_f32_e32 v0, v0
	v_and_b32_e32 v13, 0xffff0000, v10
	v_pk_fma_f32 v[82:83], v[6:7], v[12:13], v[82:83]
	v_lshlrev_b32_e32 v10, 16, v11
	v_add_f32_e32 v0, 1.0, v0
	v_rcp_f32_e32 v6, v0
	v_mul_f32_e32 v0, 0xbfb8aa3b, v9
	v_exp_f32_e32 v0, v0
	v_and_b32_e32 v11, 0xffff0000, v11
	v_add_f32_e32 v0, 1.0, v0
	v_rcp_f32_e32 v7, v0
	v_mul_f32_e32 v0, 0xbfb8aa3b, v2
	v_exp_f32_e32 v0, v0
	v_pk_fma_f32 v[84:85], v[6:7], v[10:11], v[84:85]
	global_load_dwordx2 v[6:7], v[18:19], off offset:96
	v_add_f32_e32 v0, 1.0, v0
	v_rcp_f32_e32 v2, v0
	v_mul_f32_e32 v0, 0xbfb8aa3b, v3
	v_exp_f32_e32 v0, v0
	s_waitcnt vmcnt(0)
	v_lshlrev_b32_e32 v8, 16, v6
	v_add_f32_e32 v0, 1.0, v0
	v_rcp_f32_e32 v3, v0
	v_mul_f32_e32 v0, 0xbfb8aa3b, v4
	v_exp_f32_e32 v0, v0
	v_and_b32_e32 v9, 0xffff0000, v6
	v_pk_fma_f32 v[78:79], v[2:3], v[8:9], v[78:79]
	v_lshlrev_b32_e32 v6, 16, v7
	v_add_f32_e32 v0, 1.0, v0
	v_rcp_f32_e32 v2, v0
	v_mul_f32_e32 v0, 0xbfb8aa3b, v5
	v_exp_f32_e32 v0, v0
	v_and_b32_e32 v7, 0xffff0000, v7
	v_add_f32_e32 v0, 1.0, v0
	v_rcp_f32_e32 v3, v0
	s_nop 0
	v_pk_fma_f32 v[80:81], v[2:3], v[6:7], v[80:81]
	s_cbranch_scc0 .LBB0_190
	s_add_u32 s0, s19, s0
	s_addc_u32 s1, s20, s1
	s_lshl_b32 s2, s25, 1
	v_mov_b32_e32 v16, v196
	s_add_u32 s0, s0, s2
	s_mov_b32 s2, 0xfffffc0
	v_and_b32_e32 v6, 15, v16
	v_lshrrev_b32_e32 v2, 1, v16
	v_and_b32_e32 v0, 64, v16
	v_and_or_b32 v3, v2, s2, v6
	v_lshl_add_u32 v0, v0, 1, 0
	v_and_b32_e32 v2, 24, v2
	v_mul_lo_u32 v3, v3, s30
	v_add3_u32 v0, v0, v2, v3
	v_cvt_pk_bf16_f32 v2, v140, v141
	v_cvt_pk_bf16_f32 v3, v142, v143
	v_cvt_pk_bf16_f32 v4, v136, v137
	v_cvt_pk_bf16_f32 v5, v138, v139
	ds_write2_b64 v0, v[2:3], v[4:5] offset1:4
	v_cvt_pk_bf16_f32 v2, v132, v133
	v_cvt_pk_bf16_f32 v3, v134, v135
	v_cvt_pk_bf16_f32 v4, v128, v129
	v_cvt_pk_bf16_f32 v5, v130, v131
	ds_write2_b64 v0, v[2:3], v[4:5] offset0:8 offset1:12
	v_cvt_pk_bf16_f32 v2, v124, v125
	v_cvt_pk_bf16_f32 v3, v126, v127
	v_cvt_pk_bf16_f32 v4, v120, v121
	v_cvt_pk_bf16_f32 v5, v122, v123
	v_add_u32_e32 v7, 0x1000, v0
	ds_write2_b64 v7, v[2:3], v[4:5] offset0:32 offset1:36
	v_cvt_pk_bf16_f32 v2, v116, v117
	v_cvt_pk_bf16_f32 v3, v118, v119
	v_cvt_pk_bf16_f32 v4, v110, v111
	v_cvt_pk_bf16_f32 v5, v112, v113
	ds_write2_b64 v7, v[2:3], v[4:5] offset0:40 offset1:44
	v_cvt_pk_bf16_f32 v2, v106, v107
	v_cvt_pk_bf16_f32 v3, v108, v109
	v_cvt_pk_bf16_f32 v4, v102, v103
	v_cvt_pk_bf16_f32 v5, v104, v105
	v_add_u32_e32 v7, 0x2000, v0
	ds_write2_b64 v7, v[2:3], v[4:5] offset0:64 offset1:68
	v_cvt_pk_bf16_f32 v2, v98, v99
	v_cvt_pk_bf16_f32 v3, v100, v101
	v_cvt_pk_bf16_f32 v4, v94, v95
	v_cvt_pk_bf16_f32 v5, v96, v97
	ds_write2_b64 v7, v[2:3], v[4:5] offset0:72 offset1:76
	v_cvt_pk_bf16_f32 v2, v90, v91
	v_cvt_pk_bf16_f32 v3, v92, v93
	v_cvt_pk_bf16_f32 v4, v86, v87
	v_cvt_pk_bf16_f32 v5, v88, v89
	v_add_u32_e32 v0, 0x3000, v0
	ds_write2_b64 v0, v[2:3], v[4:5] offset0:96 offset1:100
	v_cvt_pk_bf16_f32 v2, v82, v83
	v_cvt_pk_bf16_f32 v3, v84, v85
	v_cvt_pk_bf16_f32 v4, v78, v79
	v_cvt_pk_bf16_f32 v5, v80, v81
	s_addc_u32 s1, s1, 0
	ds_write2_b64 v0, v[2:3], v[4:5] offset0:104 offset1:108
	v_lshlrev_b32_e32 v0, 4, v6
	v_ashrrev_i32_e32 v2, 4, v16
	v_lshl_add_u64 v[10:11], s[0:1], 0, v[0:1]
	v_add_u32_e32 v0, 0, v0
	v_ashrrev_i32_e32 v3, 31, v2
	v_mad_u64_u32 v[4:5], s[0:1], v2, s30, v[0:1]
	v_lshlrev_b64 v[2:3], 11, v[2:3]
	v_add_u32_e32 v6, 0x100, v16
	s_waitcnt lgkmcnt(0)
	s_barrier
	v_lshl_add_u64 v[12:13], v[10:11], 0, v[2:3]
	ds_read_b128 v[2:5], v4
	v_ashrrev_i32_e32 v14, 4, v6
	v_mad_u64_u32 v[6:7], s[0:1], v14, s30, v[0:1]
	ds_read_b128 v[6:9], v6
	v_ashrrev_i32_e32 v15, 31, v14
	s_waitcnt lgkmcnt(1)
	global_store_dwordx4 v[12:13], v[2:5], off
	s_nop 1
	v_lshlrev_b64 v[2:3], 11, v[14:15]
	v_lshl_add_u64 v[2:3], v[10:11], 0, v[2:3]
	s_waitcnt lgkmcnt(0)
	global_store_dwordx4 v[2:3], v[6:9], off
	v_add_u32_e32 v2, 0x200, v16
	v_ashrrev_i32_e32 v2, 4, v2
	v_ashrrev_i32_e32 v3, 31, v2
	v_mad_u64_u32 v[4:5], s[0:1], v2, s30, v[0:1]
	v_lshlrev_b64 v[2:3], 11, v[2:3]
	v_add_u32_e32 v6, 0x300, v16
	v_lshl_add_u64 v[12:13], v[10:11], 0, v[2:3]
	ds_read_b128 v[2:5], v4
	v_ashrrev_i32_e32 v14, 4, v6
	v_mad_u64_u32 v[6:7], s[0:1], v14, s30, v[0:1]
	ds_read_b128 v[6:9], v6
	v_ashrrev_i32_e32 v15, 31, v14
	s_waitcnt lgkmcnt(1)
	global_store_dwordx4 v[12:13], v[2:5], off
	s_nop 1
	v_lshlrev_b64 v[2:3], 11, v[14:15]
	v_lshl_add_u64 v[2:3], v[10:11], 0, v[2:3]
	s_waitcnt lgkmcnt(0)
	global_store_dwordx4 v[2:3], v[6:9], off
	v_add_u32_e32 v2, 0x400, v16
	v_ashrrev_i32_e32 v2, 4, v2
	v_ashrrev_i32_e32 v3, 31, v2
	v_mad_u64_u32 v[4:5], s[0:1], v2, s30, v[0:1]
	v_lshlrev_b64 v[2:3], 11, v[2:3]
	v_add_u32_e32 v6, 0x500, v16
	v_lshl_add_u64 v[12:13], v[10:11], 0, v[2:3]
	ds_read_b128 v[2:5], v4
	v_ashrrev_i32_e32 v14, 4, v6
	v_mad_u64_u32 v[6:7], s[0:1], v14, s30, v[0:1]
	ds_read_b128 v[6:9], v6
	v_ashrrev_i32_e32 v15, 31, v14
	s_waitcnt lgkmcnt(1)
	global_store_dwordx4 v[12:13], v[2:5], off
	s_nop 1
	v_lshlrev_b64 v[2:3], 11, v[14:15]
	v_lshl_add_u64 v[2:3], v[10:11], 0, v[2:3]
	s_waitcnt lgkmcnt(0)
	global_store_dwordx4 v[2:3], v[6:9], off
	v_add_u32_e32 v2, 0x600, v16
	v_ashrrev_i32_e32 v2, 4, v2
	v_ashrrev_i32_e32 v3, 31, v2
	v_mad_u64_u32 v[4:5], s[0:1], v2, s30, v[0:1]
	v_lshlrev_b64 v[2:3], 11, v[2:3]
	v_add_u32_e32 v6, 0x700, v16
	v_lshl_add_u64 v[12:13], v[10:11], 0, v[2:3]
	ds_read_b128 v[2:5], v4
	v_ashrrev_i32_e32 v14, 4, v6
	v_mad_u64_u32 v[6:7], s[0:1], v14, s30, v[0:1]
	ds_read_b128 v[6:9], v6
	v_ashrrev_i32_e32 v15, 31, v14
	s_waitcnt lgkmcnt(1)
	global_store_dwordx4 v[12:13], v[2:5], off
	v_readlane_b32 s0, v225, 42
	v_readlane_b32 s1, v225, 43
	v_lshlrev_b64 v[2:3], 11, v[14:15]
	v_lshl_add_u64 v[2:3], v[10:11], 0, v[2:3]
	s_waitcnt lgkmcnt(0)
	global_store_dwordx4 v[2:3], v[6:9], off
	s_barrier
	s_load_dword s0, s[0:1], 0x0
	s_waitcnt lgkmcnt(0)
	s_add_i32 s24, s0, s24
	s_cmp_ge_i32 s24, s14
	s_cbranch_scc0 .LBB0_189

.LBB0_199:
	s_abs_i32 s1, s15
	s_mul_hi_u32 s2, s1, s14
	s_mul_i32 s8, s2, s10
	s_sub_i32 s1, s1, s8
	s_ashr_i32 s0, s15, 31
	s_add_i32 s8, s2, 1
	s_sub_i32 s9, s1, s10
	s_cmp_ge_u32 s1, s10
	s_cselect_b32 s2, s8, s2
	s_cselect_b32 s1, s9, s1
	s_add_i32 s8, s2, 1
	s_cmp_ge_u32 s1, s10
	s_cselect_b32 s1, s8, s2
	s_xor_b32 s1, s1, s0
	s_sub_i32 s0, s1, s0
	s_mul_i32 s1, s0, s10
	s_sub_i32 s18, s15, s1
	s_cmp_eq_u32 s0, 1
	s_mov_b32 s1, 0x8b7c000
	s_cselect_b32 s1, s1, 0xac7c000
	s_cselect_b32 s2, s81, 0x1a81c000
	s_cmp_eq_u32 s0, 0
	s_cselect_b32 s1, 0x1871c000, s1
	v_readlane_b32 s22, v225, 48
	s_cselect_b32 s2, 0xe21c000, s2
	v_readlane_b32 s23, v225, 49
	s_add_u32 s8, s22, s1
	s_addc_u32 s9, s23, 0
	s_ashr_i32 s1, s0, 31
	s_lshl_b64 s[0:1], s[0:1], 20
	s_add_u32 s19, s12, s0
	s_addc_u32 s20, s13, s1
	s_add_u32 s17, s22, s2
	s_addc_u32 s16, s23, 0
	s_cmpk_gt_i32 s18, 0x3ff
	s_mov_b64 s[0:1], -1
	s_cbranch_scc0 .LBB0_201
	s_lshl_b32 s0, s18, 4
	s_add_i32 s0, s0, 0x7fffc000
	s_and_b32 s0, s0, 0x7fffff80
	s_add_i32 s2, s0, 0x8000
	s_lshl_b32 s0, s15, 7
	v_mov_b32_e32 v10, v196
	s_and_b32 s0, s0, 0x380
	s_lshl_b64 s[22:23], s[2:3], 10
	s_add_u32 s22, s8, s22
	v_lshrrev_b32_e32 v0, 2, v10
	v_and_b32_e32 v0, 12, v0
	s_addc_u32 s23, s9, s23
	s_lshl_b32 s1, s0, 10
	v_lshrrev_b32_e64 v0, v0, s57
	s_add_u32 s24, s19, s1
	v_xor_b32_e32 v0, v0, v10
	v_and_b32_e32 v13, 15, v10
	v_lshrrev_b32_e32 v14, 1, v10
	s_mov_b32 s1, 0x3ffffc0
	v_ashrrev_i32_e32 v2, 2, v10
	v_lshlrev_b32_e32 v0, 4, v0
	v_and_or_b32 v15, v14, s1, v13
	v_and_b32_e32 v13, 12, v10
	v_lshrrev_b32_e32 v12, 4, v10
	v_and_b32_e32 v0, 48, v0
	v_ashrrev_i32_e32 v3, 31, v2
	v_lshl_add_u32 v11, v10, 4, 0
	v_lshrrev_b32_e64 v13, v13, s57
	v_lshl_add_u64 v[4:5], s[22:23], 0, v[0:1]
	v_lshlrev_b64 v[6:7], 10, v[2:3]
	s_mov_b64 s[22:23], 0x10000
	v_xor_b32_e32 v12, v13, v12
	v_readfirstlane_b32 s36, v11
	v_add_u32_e32 v13, 0x1000, v11
	s_addc_u32 s25, s20, 0
	v_lshl_add_u64 v[2:3], v[4:5], 0, v[6:7]
	v_lshl_add_u64 v[8:9], v[6:7], 0, s[22:23]
	v_lshlrev_b32_e32 v12, 4, v12
	s_waitcnt vmcnt(0)
	s_mov_b32 m0, s36
	v_readfirstlane_b32 s37, v13
	v_add_u32_e32 v14, 0x2000, v11
	v_lshl_add_u64 v[4:5], v[4:5], 0, v[8:9]
	v_lshl_add_u64 v[8:9], s[24:25], 0, v[8:9]
	global_load_lds_dwordx4 v[2:3], off
	s_mov_b32 m0, s37
	v_lshl_add_u64 v[6:7], s[24:25], 0, v[6:7]
	v_and_b32_e32 v32, 48, v12
	v_readfirstlane_b32 s38, v14
	v_add_u32_e32 v12, 0x3000, v11
	global_load_lds_dwordx4 v[4:5], off
	v_lshl_add_u64 v[6:7], v[6:7], 0, v[0:1]
	v_lshl_add_u64 v[8:9], v[8:9], 0, v[0:1]
	s_mov_b32 m0, s38
	v_readfirstlane_b32 s39, v12
	v_add_u32_e32 v0, 0x4000, v11
	global_load_lds_dwordx4 v[6:7], off
	s_mov_b32 m0, s39
	v_readfirstlane_b32 s24, v0
	v_add_u32_e32 v0, 0x5000, v11
	v_lshl_add_u64 v[16:17], v[2:3], 0, 64
	global_load_lds_dwordx4 v[8:9], off
	s_mov_b32 m0, s24
	v_readfirstlane_b32 s25, v0
	v_add_u32_e32 v0, 0x6000, v11
	v_lshl_add_u64 v[18:19], v[4:5], 0, 64
	global_load_lds_dwordx4 v[16:17], off
	s_mov_b32 m0, s25
	v_readfirstlane_b32 s26, v0
	v_add_u32_e32 v0, 0x7000, v11
	v_lshl_add_u64 v[20:21], v[6:7], 0, 64
	global_load_lds_dwordx4 v[18:19], off
	s_mov_b32 m0, s26
	v_readfirstlane_b32 s27, v0
	v_lshl_add_u64 v[16:17], v[8:9], 0, 64
	global_load_lds_dwordx4 v[20:21], off
	s_mov_b32 m0, s27
	v_add_u32_e32 v0, 0x8000, v11
	global_load_lds_dwordx4 v[16:17], off
	v_add_u32_e32 v26, 0x9000, v11
	v_readfirstlane_b32 s23, v0
	v_lshl_add_u64 v[22:23], v[2:3], 0, s[78:79]
	s_waitcnt vmcnt(4) lgkmcnt(0)
	s_barrier
	v_add_u32_e32 v25, 0xa000, v11
	s_mov_b32 m0, s23
	v_readfirstlane_b32 s22, v26
	v_lshl_add_u64 v[20:21], v[4:5], 0, s[78:79]
	v_add_u32_e32 v24, 0xb000, v11
	global_load_lds_dwordx4 v[22:23], off
	s_mov_b32 m0, s22
	v_readfirstlane_b32 s21, v25
	v_lshlrev_b32_e32 v10, 6, v10
	v_lshl_add_u64 v[16:17], v[6:7], 0, s[78:79]
	global_load_lds_dwordx4 v[20:21], off
	s_mov_b32 m0, s21
	v_readfirstlane_b32 s1, v24
	v_and_b32_e32 v10, 0x13c0, v10
	v_lshlrev_b32_e32 v15, 6, v15
	v_lshl_add_u64 v[18:19], v[8:9], 0, s[78:79]
	global_load_lds_dwordx4 v[16:17], off
	s_mov_b32 m0, s1
	v_add3_u32 v0, 0, v10, v32
	global_load_lds_dwordx4 v[18:19], off
	v_add3_u32 v10, 0, v15, v32
	v_lshl_add_u64 v[88:89], v[2:3], 0, s[84:85]
	ds_read_b128 v[16:19], v0 offset:8192
	ds_read_b128 v[20:23], v0 offset:9216
	ds_read_b128 v[24:27], v0 offset:10240
	ds_read_b128 v[28:31], v0 offset:11264
	ds_read_b128 v[32:35], v10
	ds_read_b128 v[36:39], v10 offset:1024
	ds_read_b128 v[40:43], v10 offset:2048
	ds_read_b128 v[44:47], v10 offset:3072
	s_waitcnt vmcnt(4) lgkmcnt(0)
	s_barrier
	s_mov_b32 m0, s36
	v_lshl_add_u64 v[90:91], v[4:5], 0, s[84:85]
	global_load_lds_dwordx4 v[88:89], off
	s_mov_b32 m0, s37
	v_lshl_add_u64 v[86:87], v[6:7], 0, s[84:85]
	global_load_lds_dwordx4 v[90:91], off
	s_mov_b32 m0, s38
	v_lshl_add_u64 v[84:85], v[8:9], 0, s[84:85]
	global_load_lds_dwordx4 v[86:87], off
	s_mov_b32 m0, s39
	s_mov_b64 s[40:41], 0x100
	global_load_lds_dwordx4 v[84:85], off
	s_waitcnt lgkmcnt(0)
	s_setprio 1
	v_mfma_f32_16x16x32_bf16 v[48:51], v[16:19], v[32:35], 0
	v_lshl_add_u64 v[116:117], v[2:3], 0, s[40:41]
	s_mov_b32 m0, s24
	v_lshl_add_u64 v[118:119], v[4:5], 0, s[40:41]
	v_mfma_f32_16x16x32_bf16 v[52:55], v[20:23], v[32:35], 0
	v_lshl_add_u64 v[114:115], v[6:7], 0, s[40:41]
	v_lshl_add_u64 v[112:113], v[8:9], 0, s[40:41]
	s_mov_b64 s[40:41], 0x140
	v_mfma_f32_16x16x32_bf16 v[56:59], v[24:27], v[32:35], 0
	v_lshl_add_u64 v[124:125], v[2:3], 0, s[40:41]
	v_lshl_add_u64 v[126:127], v[4:5], 0, s[40:41]
	v_lshl_add_u64 v[122:123], v[6:7], 0, s[40:41]
	v_mfma_f32_16x16x32_bf16 v[32:35], v[28:31], v[32:35], 0
	v_lshl_add_u64 v[120:121], v[8:9], 0, s[40:41]
	s_mov_b64 s[40:41], 0x180
	v_readlane_b32 s88, v225, 56
	v_mfma_f32_16x16x32_bf16 v[60:63], v[16:19], v[36:39], 0
	v_mfma_f32_16x16x32_bf16 v[64:67], v[20:23], v[36:39], 0
	v_mfma_f32_16x16x32_bf16 v[68:71], v[24:27], v[36:39], 0
	v_mfma_f32_16x16x32_bf16 v[36:39], v[28:31], v[36:39], 0
	v_mfma_f32_16x16x32_bf16 v[72:75], v[16:19], v[40:43], 0
	v_mfma_f32_16x16x32_bf16 v[76:79], v[20:23], v[40:43], 0
	v_mfma_f32_16x16x32_bf16 v[80:83], v[24:27], v[40:43], 0
	v_mfma_f32_16x16x32_bf16 v[40:43], v[28:31], v[40:43], 0
	v_mfma_f32_16x16x32_bf16 v[16:19], v[16:19], v[44:47], 0
	v_mfma_f32_16x16x32_bf16 v[20:23], v[20:23], v[44:47], 0
	v_mfma_f32_16x16x32_bf16 v[24:27], v[24:27], v[44:47], 0
	v_mfma_f32_16x16x32_bf16 v[28:31], v[28:31], v[44:47], 0
	s_setprio 0
	ds_read_b128 v[44:47], v0 offset:24576
	ds_read_b128 v[84:87], v0 offset:25600
	ds_read_b128 v[88:91], v0 offset:26624
	ds_read_b128 v[92:95], v0 offset:27648
	ds_read_b128 v[96:99], v10 offset:16384
	ds_read_b128 v[100:103], v10 offset:17408
	ds_read_b128 v[104:107], v10 offset:18432
	ds_read_b128 v[108:111], v10 offset:19456
	s_waitcnt vmcnt(4) lgkmcnt(0)
	s_barrier
	global_load_lds_dwordx4 v[116:117], off
	s_mov_b32 m0, s25
	s_waitcnt lgkmcnt(0)
	s_setprio 1
	v_mfma_f32_16x16x32_bf16 v[48:51], v[44:47], v[96:99], v[48:51]
	global_load_lds_dwordx4 v[118:119], off
	s_mov_b32 m0, s26
	v_mfma_f32_16x16x32_bf16 v[52:55], v[84:87], v[96:99], v[52:55]
	global_load_lds_dwordx4 v[114:115], off
	s_mov_b32 m0, s27
	v_mfma_f32_16x16x32_bf16 v[56:59], v[88:91], v[96:99], v[56:59]
	global_load_lds_dwordx4 v[112:113], off
	s_mov_b32 m0, s23
	v_mfma_f32_16x16x32_bf16 v[32:35], v[92:95], v[96:99], v[32:35]
	v_lshl_add_u64 v[116:117], v[2:3], 0, s[40:41]
	v_lshl_add_u64 v[118:119], v[4:5], 0, s[40:41]
	v_lshl_add_u64 v[114:115], v[6:7], 0, s[40:41]
	v_mfma_f32_16x16x32_bf16 v[60:63], v[44:47], v[100:103], v[60:63]
	v_lshl_add_u64 v[112:113], v[8:9], 0, s[40:41]
	s_mov_b64 s[40:41], 0x1c0
	v_mfma_f32_16x16x32_bf16 v[64:67], v[84:87], v[100:103], v[64:67]
	v_mfma_f32_16x16x32_bf16 v[68:71], v[88:91], v[100:103], v[68:71]
	v_mfma_f32_16x16x32_bf16 v[36:39], v[92:95], v[100:103], v[36:39]
	v_mfma_f32_16x16x32_bf16 v[72:75], v[44:47], v[104:107], v[72:75]
	v_mfma_f32_16x16x32_bf16 v[76:79], v[84:87], v[104:107], v[76:79]
	v_mfma_f32_16x16x32_bf16 v[80:83], v[88:91], v[104:107], v[80:83]
	v_mfma_f32_16x16x32_bf16 v[40:43], v[92:95], v[104:107], v[40:43]
	v_mfma_f32_16x16x32_bf16 v[16:19], v[44:47], v[108:111], v[16:19]
	v_mfma_f32_16x16x32_bf16 v[20:23], v[84:87], v[108:111], v[20:23]
	v_mfma_f32_16x16x32_bf16 v[24:27], v[88:91], v[108:111], v[24:27]
	v_mfma_f32_16x16x32_bf16 v[28:31], v[92:95], v[108:111], v[28:31]
	s_setprio 0
	ds_read_b128 v[44:47], v0 offset:40960
	ds_read_b128 v[84:87], v0 offset:41984
	ds_read_b128 v[88:91], v0 offset:43008
	ds_read_b128 v[92:95], v0 offset:44032
	ds_read_b128 v[96:99], v10 offset:32768
	ds_read_b128 v[100:103], v10 offset:33792
	ds_read_b128 v[104:107], v10 offset:34816
	ds_read_b128 v[108:111], v10 offset:35840
	s_waitcnt vmcnt(4) lgkmcnt(0)
	s_barrier
	global_load_lds_dwordx4 v[124:125], off
	s_mov_b32 m0, s22
	s_waitcnt lgkmcnt(0)
	s_setprio 1
	v_mfma_f32_16x16x32_bf16 v[48:51], v[44:47], v[96:99], v[48:51]
	global_load_lds_dwordx4 v[126:127], off
	s_mov_b32 m0, s21
	v_mfma_f32_16x16x32_bf16 v[52:55], v[84:87], v[96:99], v[52:55]
	global_load_lds_dwordx4 v[122:123], off
	s_mov_b32 m0, s1
	v_mfma_f32_16x16x32_bf16 v[56:59], v[88:91], v[96:99], v[56:59]
	global_load_lds_dwordx4 v[120:121], off
	s_mov_b32 m0, s36
	v_mfma_f32_16x16x32_bf16 v[32:35], v[92:95], v[96:99], v[32:35]
	v_lshl_add_u64 v[124:125], v[2:3], 0, s[40:41]
	v_lshl_add_u64 v[126:127], v[4:5], 0, s[40:41]
	v_lshl_add_u64 v[122:123], v[6:7], 0, s[40:41]
	v_mfma_f32_16x16x32_bf16 v[60:63], v[44:47], v[100:103], v[60:63]
	v_lshl_add_u64 v[120:121], v[8:9], 0, s[40:41]
	s_mov_b64 s[40:41], 0x200
	v_mfma_f32_16x16x32_bf16 v[64:67], v[84:87], v[100:103], v[64:67]
	v_mfma_f32_16x16x32_bf16 v[68:71], v[88:91], v[100:103], v[68:71]
	v_mfma_f32_16x16x32_bf16 v[36:39], v[92:95], v[100:103], v[36:39]
	v_mfma_f32_16x16x32_bf16 v[72:75], v[44:47], v[104:107], v[72:75]
	v_mfma_f32_16x16x32_bf16 v[76:79], v[84:87], v[104:107], v[76:79]
	v_mfma_f32_16x16x32_bf16 v[80:83], v[88:91], v[104:107], v[80:83]
	v_mfma_f32_16x16x32_bf16 v[40:43], v[92:95], v[104:107], v[40:43]
	v_mfma_f32_16x16x32_bf16 v[16:19], v[44:47], v[108:111], v[16:19]
	v_mfma_f32_16x16x32_bf16 v[20:23], v[84:87], v[108:111], v[20:23]
	v_mfma_f32_16x16x32_bf16 v[24:27], v[88:91], v[108:111], v[24:27]
	v_mfma_f32_16x16x32_bf16 v[28:31], v[92:95], v[108:111], v[28:31]
	s_setprio 0
	ds_read_b128 v[44:47], v0 offset:8192
	ds_read_b128 v[84:87], v0 offset:9216
	ds_read_b128 v[88:91], v0 offset:10240
	ds_read_b128 v[92:95], v0 offset:11264
	ds_read_b128 v[96:99], v10
	ds_read_b128 v[100:103], v10 offset:1024
	ds_read_b128 v[104:107], v10 offset:2048
	ds_read_b128 v[108:111], v10 offset:3072
	s_waitcnt vmcnt(4) lgkmcnt(0)
	s_barrier
	global_load_lds_dwordx4 v[116:117], off
	s_mov_b32 m0, s37
	s_waitcnt lgkmcnt(0)
	s_setprio 1
	v_mfma_f32_16x16x32_bf16 v[48:51], v[44:47], v[96:99], v[48:51]
	global_load_lds_dwordx4 v[118:119], off
	s_mov_b32 m0, s38
	v_mfma_f32_16x16x32_bf16 v[52:55], v[84:87], v[96:99], v[52:55]
	global_load_lds_dwordx4 v[114:115], off
	s_mov_b32 m0, s39
	v_mfma_f32_16x16x32_bf16 v[56:59], v[88:91], v[96:99], v[56:59]
	global_load_lds_dwordx4 v[112:113], off
	s_mov_b32 m0, s24
	v_mfma_f32_16x16x32_bf16 v[32:35], v[92:95], v[96:99], v[32:35]
	v_lshl_add_u64 v[116:117], v[2:3], 0, s[40:41]
	v_lshl_add_u64 v[118:119], v[4:5], 0, s[40:41]
	v_lshl_add_u64 v[114:115], v[6:7], 0, s[40:41]
	v_mfma_f32_16x16x32_bf16 v[60:63], v[44:47], v[100:103], v[60:63]
	v_lshl_add_u64 v[112:113], v[8:9], 0, s[40:41]
	s_mov_b64 s[40:41], 0x240
	v_mfma_f32_16x16x32_bf16 v[64:67], v[84:87], v[100:103], v[64:67]
	v_mfma_f32_16x16x32_bf16 v[68:71], v[88:91], v[100:103], v[68:71]
	v_mfma_f32_16x16x32_bf16 v[36:39], v[92:95], v[100:103], v[36:39]
	v_mfma_f32_16x16x32_bf16 v[72:75], v[44:47], v[104:107], v[72:75]
	v_mfma_f32_16x16x32_bf16 v[76:79], v[84:87], v[104:107], v[76:79]
	v_mfma_f32_16x16x32_bf16 v[80:83], v[88:91], v[104:107], v[80:83]
	v_mfma_f32_16x16x32_bf16 v[40:43], v[92:95], v[104:107], v[40:43]
	v_mfma_f32_16x16x32_bf16 v[16:19], v[44:47], v[108:111], v[16:19]
	v_mfma_f32_16x16x32_bf16 v[20:23], v[84:87], v[108:111], v[20:23]
	v_mfma_f32_16x16x32_bf16 v[24:27], v[88:91], v[108:111], v[24:27]
	v_mfma_f32_16x16x32_bf16 v[28:31], v[92:95], v[108:111], v[28:31]
	s_setprio 0
	ds_read_b128 v[44:47], v0 offset:24576
	ds_read_b128 v[84:87], v0 offset:25600
	ds_read_b128 v[88:91], v0 offset:26624
	ds_read_b128 v[92:95], v0 offset:27648
	ds_read_b128 v[96:99], v10 offset:16384
	ds_read_b128 v[100:103], v10 offset:17408
	ds_read_b128 v[104:107], v10 offset:18432
	ds_read_b128 v[108:111], v10 offset:19456
	s_waitcnt vmcnt(4) lgkmcnt(0)
	s_barrier
	global_load_lds_dwordx4 v[124:125], off
	s_mov_b32 m0, s25
	s_waitcnt lgkmcnt(0)
	s_setprio 1
	v_mfma_f32_16x16x32_bf16 v[48:51], v[44:47], v[96:99], v[48:51]
	global_load_lds_dwordx4 v[126:127], off
	s_mov_b32 m0, s26
	v_mfma_f32_16x16x32_bf16 v[52:55], v[84:87], v[96:99], v[52:55]
	global_load_lds_dwordx4 v[122:123], off
	s_mov_b32 m0, s27
	v_mfma_f32_16x16x32_bf16 v[56:59], v[88:91], v[96:99], v[56:59]
	global_load_lds_dwordx4 v[120:121], off
	s_mov_b32 m0, s23
	v_mfma_f32_16x16x32_bf16 v[32:35], v[92:95], v[96:99], v[32:35]
	v_lshl_add_u64 v[124:125], v[2:3], 0, s[40:41]
	v_lshl_add_u64 v[126:127], v[4:5], 0, s[40:41]
	v_lshl_add_u64 v[122:123], v[6:7], 0, s[40:41]
	v_mfma_f32_16x16x32_bf16 v[60:63], v[44:47], v[100:103], v[60:63]
	v_lshl_add_u64 v[120:121], v[8:9], 0, s[40:41]
	s_mov_b64 s[40:41], 0x280
	v_mfma_f32_16x16x32_bf16 v[64:67], v[84:87], v[100:103], v[64:67]
	v_mfma_f32_16x16x32_bf16 v[68:71], v[88:91], v[100:103], v[68:71]
	v_mfma_f32_16x16x32_bf16 v[36:39], v[92:95], v[100:103], v[36:39]
	v_mfma_f32_16x16x32_bf16 v[72:75], v[44:47], v[104:107], v[72:75]
	v_mfma_f32_16x16x32_bf16 v[76:79], v[84:87], v[104:107], v[76:79]
	v_mfma_f32_16x16x32_bf16 v[80:83], v[88:91], v[104:107], v[80:83]
	v_mfma_f32_16x16x32_bf16 v[40:43], v[92:95], v[104:107], v[40:43]
	v_mfma_f32_16x16x32_bf16 v[16:19], v[44:47], v[108:111], v[16:19]
	v_mfma_f32_16x16x32_bf16 v[20:23], v[84:87], v[108:111], v[20:23]
	v_mfma_f32_16x16x32_bf16 v[24:27], v[88:91], v[108:111], v[24:27]
	v_mfma_f32_16x16x32_bf16 v[28:31], v[92:95], v[108:111], v[28:31]
	s_setprio 0
	ds_read_b128 v[44:47], v0 offset:40960
	ds_read_b128 v[84:87], v0 offset:41984
	ds_read_b128 v[88:91], v0 offset:43008
	ds_read_b128 v[92:95], v0 offset:44032
	ds_read_b128 v[96:99], v10 offset:32768
	ds_read_b128 v[100:103], v10 offset:33792
	ds_read_b128 v[104:107], v10 offset:34816
	ds_read_b128 v[108:111], v10 offset:35840
	s_waitcnt vmcnt(4) lgkmcnt(0)
	s_barrier
	global_load_lds_dwordx4 v[116:117], off
	s_mov_b32 m0, s22
	s_waitcnt lgkmcnt(0)
	s_setprio 1
	v_mfma_f32_16x16x32_bf16 v[48:51], v[44:47], v[96:99], v[48:51]
	global_load_lds_dwordx4 v[118:119], off
	s_mov_b32 m0, s21
	v_mfma_f32_16x16x32_bf16 v[52:55], v[84:87], v[96:99], v[52:55]
	global_load_lds_dwordx4 v[114:115], off
	s_mov_b32 m0, s1
	v_mfma_f32_16x16x32_bf16 v[56:59], v[88:91], v[96:99], v[56:59]
	global_load_lds_dwordx4 v[112:113], off
	s_mov_b32 m0, s36
	v_mfma_f32_16x16x32_bf16 v[32:35], v[92:95], v[96:99], v[32:35]
	v_lshl_add_u64 v[116:117], v[2:3], 0, s[40:41]
	v_lshl_add_u64 v[118:119], v[4:5], 0, s[40:41]
	v_lshl_add_u64 v[114:115], v[6:7], 0, s[40:41]
	v_mfma_f32_16x16x32_bf16 v[60:63], v[44:47], v[100:103], v[60:63]
	v_lshl_add_u64 v[112:113], v[8:9], 0, s[40:41]
	s_mov_b64 s[40:41], 0x2c0
	v_mfma_f32_16x16x32_bf16 v[64:67], v[84:87], v[100:103], v[64:67]
	v_mfma_f32_16x16x32_bf16 v[68:71], v[88:91], v[100:103], v[68:71]
	v_mfma_f32_16x16x32_bf16 v[36:39], v[92:95], v[100:103], v[36:39]
	v_mfma_f32_16x16x32_bf16 v[72:75], v[44:47], v[104:107], v[72:75]
	v_mfma_f32_16x16x32_bf16 v[76:79], v[84:87], v[104:107], v[76:79]
	v_mfma_f32_16x16x32_bf16 v[80:83], v[88:91], v[104:107], v[80:83]
	v_mfma_f32_16x16x32_bf16 v[40:43], v[92:95], v[104:107], v[40:43]
	v_mfma_f32_16x16x32_bf16 v[16:19], v[44:47], v[108:111], v[16:19]
	v_mfma_f32_16x16x32_bf16 v[20:23], v[84:87], v[108:111], v[20:23]
	v_mfma_f32_16x16x32_bf16 v[24:27], v[88:91], v[108:111], v[24:27]
	v_mfma_f32_16x16x32_bf16 v[28:31], v[92:95], v[108:111], v[28:31]
	s_setprio 0
	ds_read_b128 v[44:47], v0 offset:8192
	ds_read_b128 v[84:87], v0 offset:9216
	ds_read_b128 v[88:91], v0 offset:10240
	ds_read_b128 v[92:95], v0 offset:11264
	ds_read_b128 v[96:99], v10
	ds_read_b128 v[100:103], v10 offset:1024
	ds_read_b128 v[104:107], v10 offset:2048
	ds_read_b128 v[108:111], v10 offset:3072
	s_waitcnt vmcnt(4) lgkmcnt(0)
	s_barrier
	global_load_lds_dwordx4 v[124:125], off
	s_mov_b32 m0, s37
	s_waitcnt lgkmcnt(0)
	s_setprio 1
	v_mfma_f32_16x16x32_bf16 v[48:51], v[44:47], v[96:99], v[48:51]
	global_load_lds_dwordx4 v[126:127], off
	s_mov_b32 m0, s38
	v_mfma_f32_16x16x32_bf16 v[52:55], v[84:87], v[96:99], v[52:55]
	global_load_lds_dwordx4 v[122:123], off
	s_mov_b32 m0, s39
	v_mfma_f32_16x16x32_bf16 v[56:59], v[88:91], v[96:99], v[56:59]
	global_load_lds_dwordx4 v[120:121], off
	s_mov_b32 m0, s24
	v_mfma_f32_16x16x32_bf16 v[32:35], v[92:95], v[96:99], v[32:35]
	v_lshl_add_u64 v[124:125], v[2:3], 0, s[40:41]
	v_lshl_add_u64 v[126:127], v[4:5], 0, s[40:41]
	v_lshl_add_u64 v[122:123], v[6:7], 0, s[40:41]
	v_mfma_f32_16x16x32_bf16 v[60:63], v[44:47], v[100:103], v[60:63]
	v_lshl_add_u64 v[120:121], v[8:9], 0, s[40:41]
	s_mov_b64 s[40:41], 0x300
	v_mfma_f32_16x16x32_bf16 v[64:67], v[84:87], v[100:103], v[64:67]
	v_mfma_f32_16x16x32_bf16 v[68:71], v[88:91], v[100:103], v[68:71]
	v_mfma_f32_16x16x32_bf16 v[36:39], v[92:95], v[100:103], v[36:39]
	v_mfma_f32_16x16x32_bf16 v[72:75], v[44:47], v[104:107], v[72:75]
	v_mfma_f32_16x16x32_bf16 v[76:79], v[84:87], v[104:107], v[76:79]
	v_mfma_f32_16x16x32_bf16 v[80:83], v[88:91], v[104:107], v[80:83]
	v_mfma_f32_16x16x32_bf16 v[40:43], v[92:95], v[104:107], v[40:43]
	v_mfma_f32_16x16x32_bf16 v[16:19], v[44:47], v[108:111], v[16:19]
	v_mfma_f32_16x16x32_bf16 v[20:23], v[84:87], v[108:111], v[20:23]
	v_mfma_f32_16x16x32_bf16 v[24:27], v[88:91], v[108:111], v[24:27]
	v_mfma_f32_16x16x32_bf16 v[28:31], v[92:95], v[108:111], v[28:31]
	s_setprio 0
	ds_read_b128 v[44:47], v0 offset:24576
	ds_read_b128 v[84:87], v0 offset:25600
	ds_read_b128 v[88:91], v0 offset:26624
	ds_read_b128 v[92:95], v0 offset:27648
	ds_read_b128 v[96:99], v10 offset:16384
	ds_read_b128 v[100:103], v10 offset:17408
	ds_read_b128 v[104:107], v10 offset:18432
	ds_read_b128 v[108:111], v10 offset:19456
	s_waitcnt vmcnt(4) lgkmcnt(0)
	s_barrier
	global_load_lds_dwordx4 v[116:117], off
	s_mov_b32 m0, s25
	s_waitcnt lgkmcnt(0)
	s_setprio 1
	v_mfma_f32_16x16x32_bf16 v[48:51], v[44:47], v[96:99], v[48:51]
	global_load_lds_dwordx4 v[118:119], off
	s_mov_b32 m0, s26
	v_mfma_f32_16x16x32_bf16 v[52:55], v[84:87], v[96:99], v[52:55]
	global_load_lds_dwordx4 v[114:115], off
	s_mov_b32 m0, s27
	v_mfma_f32_16x16x32_bf16 v[56:59], v[88:91], v[96:99], v[56:59]
	global_load_lds_dwordx4 v[112:113], off
	s_mov_b32 m0, s23
	v_mfma_f32_16x16x32_bf16 v[32:35], v[92:95], v[96:99], v[32:35]
	v_lshl_add_u64 v[116:117], v[2:3], 0, s[40:41]
	v_lshl_add_u64 v[118:119], v[4:5], 0, s[40:41]
	v_lshl_add_u64 v[114:115], v[6:7], 0, s[40:41]
	v_mfma_f32_16x16x32_bf16 v[60:63], v[44:47], v[100:103], v[60:63]
	v_lshl_add_u64 v[112:113], v[8:9], 0, s[40:41]
	s_mov_b64 s[40:41], 0x340
	v_mfma_f32_16x16x32_bf16 v[64:67], v[84:87], v[100:103], v[64:67]
	v_mfma_f32_16x16x32_bf16 v[68:71], v[88:91], v[100:103], v[68:71]
	v_mfma_f32_16x16x32_bf16 v[36:39], v[92:95], v[100:103], v[36:39]
	v_mfma_f32_16x16x32_bf16 v[72:75], v[44:47], v[104:107], v[72:75]
	v_mfma_f32_16x16x32_bf16 v[76:79], v[84:87], v[104:107], v[76:79]
	v_mfma_f32_16x16x32_bf16 v[80:83], v[88:91], v[104:107], v[80:83]
	v_mfma_f32_16x16x32_bf16 v[40:43], v[92:95], v[104:107], v[40:43]
	v_mfma_f32_16x16x32_bf16 v[16:19], v[44:47], v[108:111], v[16:19]
	v_mfma_f32_16x16x32_bf16 v[20:23], v[84:87], v[108:111], v[20:23]
	v_mfma_f32_16x16x32_bf16 v[24:27], v[88:91], v[108:111], v[24:27]
	v_mfma_f32_16x16x32_bf16 v[28:31], v[92:95], v[108:111], v[28:31]
	s_setprio 0
	ds_read_b128 v[44:47], v0 offset:40960
	ds_read_b128 v[84:87], v0 offset:41984
	ds_read_b128 v[88:91], v0 offset:43008
	ds_read_b128 v[92:95], v0 offset:44032
	ds_read_b128 v[96:99], v10 offset:32768
	ds_read_b128 v[100:103], v10 offset:33792
	ds_read_b128 v[104:107], v10 offset:34816
	ds_read_b128 v[108:111], v10 offset:35840
	s_waitcnt vmcnt(4) lgkmcnt(0)
	s_barrier
	global_load_lds_dwordx4 v[124:125], off
	s_mov_b32 m0, s22
	s_waitcnt lgkmcnt(0)
	s_setprio 1
	v_mfma_f32_16x16x32_bf16 v[48:51], v[44:47], v[96:99], v[48:51]
	global_load_lds_dwordx4 v[126:127], off
	s_mov_b32 m0, s21
	v_mfma_f32_16x16x32_bf16 v[52:55], v[84:87], v[96:99], v[52:55]
	global_load_lds_dwordx4 v[122:123], off
	s_mov_b32 m0, s1
	v_mfma_f32_16x16x32_bf16 v[56:59], v[88:91], v[96:99], v[56:59]
	global_load_lds_dwordx4 v[120:121], off
	s_mov_b32 m0, s36
	v_mfma_f32_16x16x32_bf16 v[32:35], v[92:95], v[96:99], v[32:35]
	v_lshl_add_u64 v[124:125], v[2:3], 0, s[40:41]
	v_lshl_add_u64 v[126:127], v[4:5], 0, s[40:41]
	v_lshl_add_u64 v[122:123], v[6:7], 0, s[40:41]
	v_mfma_f32_16x16x32_bf16 v[60:63], v[44:47], v[100:103], v[60:63]
	v_lshl_add_u64 v[120:121], v[8:9], 0, s[40:41]
	v_mfma_f32_16x16x32_bf16 v[64:67], v[84:87], v[100:103], v[64:67]
	v_mfma_f32_16x16x32_bf16 v[68:71], v[88:91], v[100:103], v[68:71]
	v_mfma_f32_16x16x32_bf16 v[36:39], v[92:95], v[100:103], v[36:39]
	v_mfma_f32_16x16x32_bf16 v[72:75], v[44:47], v[104:107], v[72:75]
	v_mfma_f32_16x16x32_bf16 v[76:79], v[84:87], v[104:107], v[76:79]
	v_mfma_f32_16x16x32_bf16 v[80:83], v[88:91], v[104:107], v[80:83]
	v_mfma_f32_16x16x32_bf16 v[40:43], v[92:95], v[104:107], v[40:43]
	v_mfma_f32_16x16x32_bf16 v[16:19], v[44:47], v[108:111], v[16:19]
	v_mfma_f32_16x16x32_bf16 v[20:23], v[84:87], v[108:111], v[20:23]
	v_mfma_f32_16x16x32_bf16 v[24:27], v[88:91], v[108:111], v[24:27]
	v_mfma_f32_16x16x32_bf16 v[28:31], v[92:95], v[108:111], v[28:31]
	s_setprio 0
	ds_read_b128 v[44:47], v0 offset:8192
	ds_read_b128 v[84:87], v0 offset:9216
	ds_read_b128 v[88:91], v0 offset:10240
	ds_read_b128 v[92:95], v0 offset:11264
	ds_read_b128 v[96:99], v10
	ds_read_b128 v[100:103], v10 offset:1024
	ds_read_b128 v[104:107], v10 offset:2048
	ds_read_b128 v[108:111], v10 offset:3072
	s_waitcnt vmcnt(4) lgkmcnt(0)
	s_barrier
	global_load_lds_dwordx4 v[116:117], off
	s_mov_b32 m0, s37
	s_waitcnt lgkmcnt(0)
	s_setprio 1
	v_mfma_f32_16x16x32_bf16 v[48:51], v[44:47], v[96:99], v[48:51]
	global_load_lds_dwordx4 v[118:119], off
	s_mov_b32 m0, s38
	v_mfma_f32_16x16x32_bf16 v[52:55], v[84:87], v[96:99], v[52:55]
	global_load_lds_dwordx4 v[114:115], off
	s_mov_b32 m0, s39
	v_mfma_f32_16x16x32_bf16 v[56:59], v[88:91], v[96:99], v[56:59]
	global_load_lds_dwordx4 v[112:113], off
	s_mov_b32 m0, s24
	v_mfma_f32_16x16x32_bf16 v[32:35], v[92:95], v[96:99], v[32:35]
	s_mov_b64 s[36:37], 0x380
	v_lshl_add_u64 v[116:117], v[2:3], 0, s[36:37]
	v_lshl_add_u64 v[118:119], v[4:5], 0, s[36:37]
	v_mfma_f32_16x16x32_bf16 v[60:63], v[44:47], v[100:103], v[60:63]
	v_lshl_add_u64 v[114:115], v[6:7], 0, s[36:37]
	v_lshl_add_u64 v[112:113], v[8:9], 0, s[36:37]
	v_mfma_f32_16x16x32_bf16 v[64:67], v[84:87], v[100:103], v[64:67]
	v_mfma_f32_16x16x32_bf16 v[68:71], v[88:91], v[100:103], v[68:71]
	v_mfma_f32_16x16x32_bf16 v[36:39], v[92:95], v[100:103], v[36:39]
	v_mfma_f32_16x16x32_bf16 v[72:75], v[44:47], v[104:107], v[72:75]
	v_mfma_f32_16x16x32_bf16 v[76:79], v[84:87], v[104:107], v[76:79]
	v_mfma_f32_16x16x32_bf16 v[80:83], v[88:91], v[104:107], v[80:83]
	v_mfma_f32_16x16x32_bf16 v[40:43], v[92:95], v[104:107], v[40:43]
	v_mfma_f32_16x16x32_bf16 v[16:19], v[44:47], v[108:111], v[16:19]
	v_mfma_f32_16x16x32_bf16 v[20:23], v[84:87], v[108:111], v[20:23]
	v_mfma_f32_16x16x32_bf16 v[24:27], v[88:91], v[108:111], v[24:27]
	v_mfma_f32_16x16x32_bf16 v[28:31], v[92:95], v[108:111], v[28:31]
	s_setprio 0
	ds_read_b128 v[44:47], v0 offset:24576
	ds_read_b128 v[84:87], v0 offset:25600
	ds_read_b128 v[88:91], v0 offset:26624
	ds_read_b128 v[92:95], v0 offset:27648
	ds_read_b128 v[96:99], v10 offset:16384
	ds_read_b128 v[100:103], v10 offset:17408
	ds_read_b128 v[104:107], v10 offset:18432
	ds_read_b128 v[108:111], v10 offset:19456
	s_waitcnt vmcnt(4) lgkmcnt(0)
	s_barrier
	global_load_lds_dwordx4 v[124:125], off
	s_mov_b32 m0, s25
	s_waitcnt lgkmcnt(0)
	s_setprio 1
	v_mfma_f32_16x16x32_bf16 v[48:51], v[44:47], v[96:99], v[48:51]
	global_load_lds_dwordx4 v[126:127], off
	s_mov_b32 m0, s26
	v_mfma_f32_16x16x32_bf16 v[52:55], v[84:87], v[96:99], v[52:55]
	global_load_lds_dwordx4 v[122:123], off
	s_mov_b32 m0, s27
	v_mfma_f32_16x16x32_bf16 v[56:59], v[88:91], v[96:99], v[56:59]
	global_load_lds_dwordx4 v[120:121], off
	s_mov_b32 m0, s23
	v_mfma_f32_16x16x32_bf16 v[32:35], v[92:95], v[96:99], v[32:35]
	s_mov_b64 s[26:27], 0x3c0
	s_mov_b64 s[24:25], 0x3000
	v_mfma_f32_16x16x32_bf16 v[60:63], v[44:47], v[100:103], v[60:63]
	v_mfma_f32_16x16x32_bf16 v[64:67], v[84:87], v[100:103], v[64:67]
	v_mfma_f32_16x16x32_bf16 v[68:71], v[88:91], v[100:103], v[68:71]
	v_mfma_f32_16x16x32_bf16 v[36:39], v[92:95], v[100:103], v[36:39]
	v_mfma_f32_16x16x32_bf16 v[72:75], v[44:47], v[104:107], v[72:75]
	v_mfma_f32_16x16x32_bf16 v[76:79], v[84:87], v[104:107], v[76:79]
	v_mfma_f32_16x16x32_bf16 v[80:83], v[88:91], v[104:107], v[80:83]
	v_mfma_f32_16x16x32_bf16 v[40:43], v[92:95], v[104:107], v[40:43]
	v_mfma_f32_16x16x32_bf16 v[16:19], v[44:47], v[108:111], v[16:19]
	v_mfma_f32_16x16x32_bf16 v[20:23], v[84:87], v[108:111], v[20:23]
	v_mfma_f32_16x16x32_bf16 v[24:27], v[88:91], v[108:111], v[24:27]
	v_mfma_f32_16x16x32_bf16 v[28:31], v[92:95], v[108:111], v[28:31]
	s_setprio 0
	ds_read_b128 v[44:47], v0 offset:40960
	ds_read_b128 v[84:87], v0 offset:41984
	ds_read_b128 v[88:91], v0 offset:43008
	ds_read_b128 v[92:95], v0 offset:44032
	ds_read_b128 v[96:99], v10 offset:32768
	ds_read_b128 v[100:103], v10 offset:33792
	ds_read_b128 v[104:107], v10 offset:34816
	ds_read_b128 v[108:111], v10 offset:35840
	s_waitcnt vmcnt(4) lgkmcnt(0)
	s_barrier
	global_load_lds_dwordx4 v[116:117], off
	s_mov_b32 m0, s22
	s_waitcnt lgkmcnt(0)
	s_setprio 1
	v_mfma_f32_16x16x32_bf16 v[48:51], v[44:47], v[96:99], v[48:51]
	global_load_lds_dwordx4 v[118:119], off
	s_mov_b32 m0, s21
	v_mfma_f32_16x16x32_bf16 v[52:55], v[84:87], v[96:99], v[52:55]
	global_load_lds_dwordx4 v[114:115], off
	s_mov_b32 m0, s1
	v_readfirstlane_b32 s1, v11
	global_load_lds_dwordx4 v[112:113], off
	v_mfma_f32_16x16x32_bf16 v[56:59], v[88:91], v[96:99], v[56:59]
	s_mov_b32 m0, s1
	v_readfirstlane_b32 s1, v13
	s_lshl_b64 s[22:23], s[2:3], 11
	v_mfma_f32_16x16x32_bf16 v[32:35], v[92:95], v[96:99], v[32:35]
	v_mfma_f32_16x16x32_bf16 v[60:63], v[44:47], v[100:103], v[60:63]
	v_mfma_f32_16x16x32_bf16 v[64:67], v[84:87], v[100:103], v[64:67]
	v_mfma_f32_16x16x32_bf16 v[68:71], v[88:91], v[100:103], v[68:71]
	v_mfma_f32_16x16x32_bf16 v[36:39], v[92:95], v[100:103], v[36:39]
	v_mfma_f32_16x16x32_bf16 v[72:75], v[44:47], v[104:107], v[72:75]
	v_mfma_f32_16x16x32_bf16 v[76:79], v[84:87], v[104:107], v[76:79]
	v_mfma_f32_16x16x32_bf16 v[80:83], v[88:91], v[104:107], v[80:83]
	v_mfma_f32_16x16x32_bf16 v[40:43], v[92:95], v[104:107], v[40:43]
	v_lshl_add_u64 v[104:105], v[8:9], 0, s[26:27]
	v_lshl_add_u64 v[106:107], v[6:7], 0, s[26:27]
	v_mfma_f32_16x16x32_bf16 v[16:19], v[44:47], v[108:111], v[16:19]
	v_mfma_f32_16x16x32_bf16 v[20:23], v[84:87], v[108:111], v[20:23]
	v_mfma_f32_16x16x32_bf16 v[24:27], v[88:91], v[108:111], v[24:27]
	v_mfma_f32_16x16x32_bf16 v[28:31], v[92:95], v[108:111], v[28:31]
	v_lshl_add_u64 v[108:109], v[2:3], 0, s[26:27]
	v_lshl_add_u64 v[110:111], v[4:5], 0, s[26:27]
	s_setprio 0
	ds_read_b128 v[2:5], v0 offset:8192
	ds_read_b128 v[6:9], v0 offset:9216
	ds_read_b128 v[44:47], v0 offset:10240
	ds_read_b128 v[84:87], v0 offset:11264
	ds_read_b128 v[88:91], v10
	ds_read_b128 v[92:95], v10 offset:1024
	ds_read_b128 v[96:99], v10 offset:2048
	ds_read_b128 v[100:103], v10 offset:3072
	s_waitcnt vmcnt(4) lgkmcnt(0)
	s_barrier
	global_load_lds_dwordx4 v[108:109], off
	s_mov_b32 m0, s1
	v_readfirstlane_b32 s1, v14
	global_load_lds_dwordx4 v[110:111], off
	s_mov_b32 m0, s1
	v_readfirstlane_b32 s1, v12
	global_load_lds_dwordx4 v[106:107], off
	s_mov_b32 m0, s1
	s_waitcnt lgkmcnt(0)
	s_setprio 1
	v_mfma_f32_16x16x32_bf16 v[48:51], v[2:5], v[88:91], v[48:51]
	global_load_lds_dwordx4 v[104:105], off
	s_add_u32 s1, s17, s22
	v_mfma_f32_16x16x32_bf16 v[52:55], v[6:9], v[88:91], v[52:55]
	s_addc_u32 s2, s16, s23
	s_lshl_b32 s0, s0, 1
	s_add_u32 s0, s1, s0
	v_mfma_f32_16x16x32_bf16 v[56:59], v[44:47], v[88:91], v[56:59]
	s_addc_u32 s1, s2, 0
	s_mov_b32 s2, 0xfffffc0
	v_mfma_f32_16x16x32_bf16 v[32:35], v[84:87], v[88:91], v[32:35]
	v_mfma_f32_16x16x32_bf16 v[60:63], v[2:5], v[92:95], v[60:63]
	v_mfma_f32_16x16x32_bf16 v[64:67], v[6:9], v[92:95], v[64:67]
	v_mfma_f32_16x16x32_bf16 v[68:71], v[44:47], v[92:95], v[68:71]
	v_mfma_f32_16x16x32_bf16 v[36:39], v[84:87], v[92:95], v[36:39]
	v_mfma_f32_16x16x32_bf16 v[72:75], v[2:5], v[96:99], v[72:75]
	v_mfma_f32_16x16x32_bf16 v[76:79], v[6:9], v[96:99], v[76:79]
	v_mfma_f32_16x16x32_bf16 v[80:83], v[44:47], v[96:99], v[80:83]
	v_mfma_f32_16x16x32_bf16 v[40:43], v[84:87], v[96:99], v[40:43]
	v_mfma_f32_16x16x32_bf16 v[2:5], v[2:5], v[100:103], v[16:19]
	v_mfma_f32_16x16x32_bf16 v[6:9], v[6:9], v[100:103], v[20:23]
	v_mfma_f32_16x16x32_bf16 v[16:19], v[44:47], v[100:103], v[24:27]
	v_mfma_f32_16x16x32_bf16 v[20:23], v[84:87], v[100:103], v[28:31]
	s_setprio 0
	ds_read_b128 v[12:15], v0 offset:24576
	s_nop 0
	ds_read_b128 v[24:27], v0 offset:25600
	ds_read_b128 v[28:31], v0 offset:26624
	ds_read_b128 v[44:47], v0 offset:27648
	ds_read_b128 v[84:87], v10 offset:16384
	ds_read_b128 v[88:91], v10 offset:17408
	ds_read_b128 v[92:95], v10 offset:18432
	ds_read_b128 v[96:99], v10 offset:19456
	s_waitcnt vmcnt(4) lgkmcnt(0)
	s_barrier
	s_waitcnt lgkmcnt(0)
	s_setprio 1
	v_mfma_f32_16x16x32_bf16 v[48:51], v[12:15], v[84:87], v[48:51]
	v_mfma_f32_16x16x32_bf16 v[52:55], v[24:27], v[84:87], v[52:55]
	v_mfma_f32_16x16x32_bf16 v[56:59], v[28:31], v[84:87], v[56:59]
	v_mfma_f32_16x16x32_bf16 v[32:35], v[44:47], v[84:87], v[32:35]
	v_mfma_f32_16x16x32_bf16 v[60:63], v[12:15], v[88:91], v[60:63]
	v_mfma_f32_16x16x32_bf16 v[64:67], v[24:27], v[88:91], v[64:67]
	v_mfma_f32_16x16x32_bf16 v[68:71], v[28:31], v[88:91], v[68:71]
	v_mfma_f32_16x16x32_bf16 v[36:39], v[44:47], v[88:91], v[36:39]
	v_mfma_f32_16x16x32_bf16 v[72:75], v[12:15], v[92:95], v[72:75]
	v_mfma_f32_16x16x32_bf16 v[76:79], v[24:27], v[92:95], v[76:79]
	v_mfma_f32_16x16x32_bf16 v[80:83], v[28:31], v[92:95], v[80:83]
	v_mfma_f32_16x16x32_bf16 v[40:43], v[44:47], v[92:95], v[40:43]
	v_mfma_f32_16x16x32_bf16 v[2:5], v[12:15], v[96:99], v[2:5]
	v_mfma_f32_16x16x32_bf16 v[6:9], v[24:27], v[96:99], v[6:9]
	v_mfma_f32_16x16x32_bf16 v[12:15], v[28:31], v[96:99], v[16:19]
	v_mfma_f32_16x16x32_bf16 v[16:19], v[44:47], v[96:99], v[20:23]
	s_nop 2
	s_setprio 0
	ds_read_b128 v[20:23], v0 offset:40960
	ds_read_b128 v[24:27], v0 offset:41984
	ds_read_b128 v[28:31], v0 offset:43008
	ds_read_b128 v[44:47], v0 offset:44032
	ds_read_b128 v[84:87], v10 offset:32768
	ds_read_b128 v[88:91], v10 offset:33792
	ds_read_b128 v[92:95], v10 offset:34816
	ds_read_b128 v[96:99], v10 offset:35840
	s_waitcnt vmcnt(0) lgkmcnt(0)
	s_barrier
	s_waitcnt lgkmcnt(0)
	s_setprio 1
	v_mfma_f32_16x16x32_bf16 v[48:51], v[20:23], v[84:87], v[48:51]
	v_mfma_f32_16x16x32_bf16 v[52:55], v[24:27], v[84:87], v[52:55]
	v_mfma_f32_16x16x32_bf16 v[56:59], v[28:31], v[84:87], v[56:59]
	v_mfma_f32_16x16x32_bf16 v[32:35], v[44:47], v[84:87], v[32:35]
	v_mfma_f32_16x16x32_bf16 v[60:63], v[20:23], v[88:91], v[60:63]
	v_mfma_f32_16x16x32_bf16 v[64:67], v[24:27], v[88:91], v[64:67]
	v_mfma_f32_16x16x32_bf16 v[68:71], v[28:31], v[88:91], v[68:71]
	v_mfma_f32_16x16x32_bf16 v[36:39], v[44:47], v[88:91], v[36:39]
	v_mfma_f32_16x16x32_bf16 v[72:75], v[20:23], v[92:95], v[72:75]
	v_mfma_f32_16x16x32_bf16 v[76:79], v[24:27], v[92:95], v[76:79]
	v_mfma_f32_16x16x32_bf16 v[80:83], v[28:31], v[92:95], v[80:83]
	v_mfma_f32_16x16x32_bf16 v[40:43], v[44:47], v[92:95], v[40:43]
	v_mfma_f32_16x16x32_bf16 v[2:5], v[20:23], v[96:99], v[2:5]
	v_mfma_f32_16x16x32_bf16 v[6:9], v[24:27], v[96:99], v[6:9]
	v_mfma_f32_16x16x32_bf16 v[12:15], v[28:31], v[96:99], v[12:15]
	v_mfma_f32_16x16x32_bf16 v[16:19], v[44:47], v[96:99], v[16:19]
	s_setprio 0
	ds_read_b128 v[20:23], v0 offset:8192
	ds_read_b128 v[24:27], v0 offset:9216
	ds_read_b128 v[28:31], v0 offset:10240
	ds_read_b128 v[44:47], v0 offset:11264
	ds_read_b128 v[84:87], v10
	ds_read_b128 v[88:91], v10 offset:1024
	ds_read_b128 v[92:95], v10 offset:2048
	ds_read_b128 v[96:99], v10 offset:3072
	s_waitcnt vmcnt(0) lgkmcnt(0)
	s_barrier
	s_setprio 1
	v_mfma_f32_16x16x32_bf16 v[48:51], v[20:23], v[84:87], v[48:51]
	v_mfma_f32_16x16x32_bf16 v[52:55], v[24:27], v[84:87], v[52:55]
	v_mfma_f32_16x16x32_bf16 v[60:63], v[20:23], v[88:91], v[60:63]
	v_mfma_f32_16x16x32_bf16 v[72:75], v[20:23], v[92:95], v[72:75]
	v_mfma_f32_16x16x32_bf16 v[2:5], v[20:23], v[96:99], v[2:5]
	v_mov_b32_e32 v22, v196
	s_setprio 0
	s_nop 3
	v_cvt_pk_bf16_f32 v20, v52, v53
	s_setprio 1
	v_mfma_f32_16x16x32_bf16 v[56:59], v[28:31], v[84:87], v[56:59]
	v_and_b32_e32 v23, 15, v22
	v_and_b32_e32 v0, 64, v22
	v_lshl_add_u32 v0, v0, 1, 0
	v_mfma_f32_16x16x32_bf16 v[32:35], v[44:47], v[84:87], v[32:35]
	v_cvt_pk_bf16_f32 v21, v54, v55
	v_cvt_pk_bf16_f32 v2, v2, v3
	v_cvt_pk_bf16_f32 v3, v4, v5
	v_mfma_f32_16x16x32_bf16 v[10:13], v[28:31], v[96:99], v[12:15]
	v_mfma_f32_16x16x32_bf16 v[14:17], v[44:47], v[96:99], v[16:19]
	s_nop 2
	v_lshrrev_b32_e32 v18, 1, v22
	v_mfma_f32_16x16x32_bf16 v[64:67], v[24:27], v[88:91], v[64:67]
	v_and_or_b32 v19, v18, s2, v23
	v_and_b32_e32 v18, 24, v18
	v_mul_lo_u32 v19, v19, s30
	v_mfma_f32_16x16x32_bf16 v[68:71], v[28:31], v[88:91], v[68:71]
	v_add3_u32 v0, v0, v18, v19
	v_cvt_pk_bf16_f32 v18, v48, v49
	v_cvt_pk_bf16_f32 v19, v50, v51
	v_mfma_f32_16x16x32_bf16 v[36:39], v[44:47], v[88:91], v[36:39]
	ds_write2_b64 v0, v[18:19], v[20:21] offset1:4
	v_cvt_pk_bf16_f32 v18, v56, v57
	v_cvt_pk_bf16_f32 v19, v58, v59
	v_mfma_f32_16x16x32_bf16 v[6:9], v[24:27], v[96:99], v[6:9]
	v_cvt_pk_bf16_f32 v20, v32, v33
	v_cvt_pk_bf16_f32 v21, v34, v35
	ds_write2_b64 v0, v[18:19], v[20:21] offset0:8 offset1:12
	v_mfma_f32_16x16x32_bf16 v[76:79], v[24:27], v[92:95], v[76:79]
	v_cvt_pk_bf16_f32 v18, v60, v61
	v_cvt_pk_bf16_f32 v19, v62, v63
	v_cvt_pk_bf16_f32 v20, v64, v65
	v_cvt_pk_bf16_f32 v21, v66, v67
	v_add_u32_e32 v24, 0x1000, v0
	ds_write2_b64 v24, v[18:19], v[20:21] offset0:32 offset1:36
	v_cvt_pk_bf16_f32 v18, v68, v69
	v_cvt_pk_bf16_f32 v19, v70, v71
	v_cvt_pk_bf16_f32 v20, v36, v37
	v_cvt_pk_bf16_f32 v21, v38, v39
	v_mfma_f32_16x16x32_bf16 v[80:83], v[28:31], v[92:95], v[80:83]
	ds_write2_b64 v24, v[18:19], v[20:21] offset0:40 offset1:44
	v_add_u32_e32 v24, 0x2000, v0
	v_cvt_pk_bf16_f32 v4, v6, v7
	v_mfma_f32_16x16x32_bf16 v[40:43], v[44:47], v[92:95], v[40:43]
	v_cvt_pk_bf16_f32 v5, v8, v9
	v_add_u32_e32 v0, 0x3000, v0
	ds_write2_b64 v0, v[2:3], v[4:5] offset0:96 offset1:100
	v_cvt_pk_bf16_f32 v2, v10, v11
	v_cvt_pk_bf16_f32 v3, v12, v13
	v_cvt_pk_bf16_f32 v4, v14, v15
	v_cvt_pk_bf16_f32 v5, v16, v17
	ds_write2_b64 v0, v[2:3], v[4:5] offset0:104 offset1:108
	v_lshlrev_b32_e32 v0, 4, v23
	v_ashrrev_i32_e32 v2, 4, v22
	v_cvt_pk_bf16_f32 v18, v72, v73
	v_cvt_pk_bf16_f32 v19, v74, v75
	v_cvt_pk_bf16_f32 v20, v76, v77
	v_cvt_pk_bf16_f32 v21, v78, v79
	v_lshl_add_u64 v[6:7], s[0:1], 0, v[0:1]
	v_add_u32_e32 v0, 0, v0
	v_ashrrev_i32_e32 v3, 31, v2
	ds_write2_b64 v24, v[18:19], v[20:21] offset0:64 offset1:68
	v_cvt_pk_bf16_f32 v18, v80, v81
	v_cvt_pk_bf16_f32 v19, v82, v83
	v_cvt_pk_bf16_f32 v20, v40, v41
	v_cvt_pk_bf16_f32 v21, v42, v43
	v_mad_u64_u32 v[4:5], s[0:1], v2, s30, v[0:1]
	v_lshlrev_b64 v[2:3], 11, v[2:3]
	ds_write2_b64 v24, v[18:19], v[20:21] offset0:72 offset1:76
	s_setprio 0
	s_waitcnt lgkmcnt(0)
	s_barrier
	v_lshl_add_u64 v[8:9], v[6:7], 0, v[2:3]
	ds_read_b128 v[2:5], v4
	s_waitcnt lgkmcnt(0)
	global_store_dwordx4 v[8:9], v[2:5], off
	s_nop 1
	v_add_u32_e32 v2, 0x100, v22
	v_ashrrev_i32_e32 v2, 4, v2
	v_ashrrev_i32_e32 v3, 31, v2
	v_mad_u64_u32 v[4:5], s[0:1], v2, s30, v[0:1]
	v_lshlrev_b64 v[2:3], 11, v[2:3]
	v_lshl_add_u64 v[8:9], v[6:7], 0, v[2:3]
	ds_read_b128 v[2:5], v4
	s_waitcnt lgkmcnt(0)
	global_store_dwordx4 v[8:9], v[2:5], off
	s_nop 1
	v_add_u32_e32 v2, 0x200, v22
	v_ashrrev_i32_e32 v2, 4, v2
	v_ashrrev_i32_e32 v3, 31, v2
	v_mad_u64_u32 v[4:5], s[0:1], v2, s30, v[0:1]
	v_lshlrev_b64 v[2:3], 11, v[2:3]
	v_lshl_add_u64 v[8:9], v[6:7], 0, v[2:3]
	ds_read_b128 v[2:5], v4
	s_waitcnt lgkmcnt(0)
	global_store_dwordx4 v[8:9], v[2:5], off
	s_nop 1
	v_add_u32_e32 v2, 0x300, v22
	v_ashrrev_i32_e32 v2, 4, v2
	v_ashrrev_i32_e32 v3, 31, v2
	v_mad_u64_u32 v[4:5], s[0:1], v2, s30, v[0:1]
	v_lshlrev_b64 v[2:3], 11, v[2:3]
	v_lshl_add_u64 v[8:9], v[6:7], 0, v[2:3]
	ds_read_b128 v[2:5], v4
	s_waitcnt lgkmcnt(0)
	global_store_dwordx4 v[8:9], v[2:5], off
	s_nop 1
	v_add_u32_e32 v2, 0x400, v22
	v_ashrrev_i32_e32 v2, 4, v2
	v_ashrrev_i32_e32 v3, 31, v2
	v_mad_u64_u32 v[4:5], s[0:1], v2, s30, v[0:1]
	v_lshlrev_b64 v[2:3], 11, v[2:3]
	v_lshl_add_u64 v[8:9], v[6:7], 0, v[2:3]
	ds_read_b128 v[2:5], v4
	s_waitcnt lgkmcnt(0)
	global_store_dwordx4 v[8:9], v[2:5], off
	s_nop 1
	v_add_u32_e32 v2, 0x500, v22
	v_ashrrev_i32_e32 v2, 4, v2
	v_ashrrev_i32_e32 v3, 31, v2
	v_mad_u64_u32 v[4:5], s[0:1], v2, s30, v[0:1]
	v_lshlrev_b64 v[2:3], 11, v[2:3]
	v_lshl_add_u64 v[8:9], v[6:7], 0, v[2:3]
	ds_read_b128 v[2:5], v4
	s_waitcnt lgkmcnt(0)
	global_store_dwordx4 v[8:9], v[2:5], off
	s_nop 1
	v_add_u32_e32 v2, 0x600, v22
	v_ashrrev_i32_e32 v2, 4, v2
	v_ashrrev_i32_e32 v3, 31, v2
	v_mad_u64_u32 v[4:5], s[0:1], v2, s30, v[0:1]
	v_lshlrev_b64 v[2:3], 11, v[2:3]
	v_lshl_add_u64 v[8:9], v[6:7], 0, v[2:3]
	ds_read_b128 v[2:5], v4
	s_waitcnt lgkmcnt(0)
	global_store_dwordx4 v[8:9], v[2:5], off
	s_nop 1
	v_add_u32_e32 v2, 0x700, v22
	v_ashrrev_i32_e32 v2, 4, v2
	v_ashrrev_i32_e32 v3, 31, v2
	v_mad_u64_u32 v[4:5], s[0:1], v2, s30, v[0:1]
	v_lshlrev_b64 v[2:3], 11, v[2:3]
	v_lshl_add_u64 v[6:7], v[6:7], 0, v[2:3]
	ds_read_b128 v[2:5], v4
	s_mov_b64 s[0:1], 0
	s_waitcnt lgkmcnt(0)
	global_store_dwordx4 v[6:7], v[2:5], off
	s_barrier

.LBB0_209:
	s_cmp_ge_i32 s20, s14
	s_mov_b64 s[0:1], -1
	s_cbranch_scc0 .LBB0_211
	s_sub_i32 s0, s20, s14
	s_lshl_b32 s0, s0, 5
	v_mov_b32_e32 v10, v196
	s_and_b32 s2, s0, 0x7fffff80
	s_and_b32 s5, s20, 3
	v_lshrrev_b32_e32 v0, 2, v10
	s_lshl_b64 s[0:1], s[2:3], 10
	v_and_b32_e32 v0, 12, v0
	s_add_u32 s2, s15, s0
	v_lshrrev_b32_e64 v0, v0, s57
	s_addc_u32 s7, s21, s1
	s_lshl_b32 s4, s5, 8
	v_xor_b32_e32 v0, v0, v10
	s_add_u32 s6, s2, s4
	v_ashrrev_i32_e32 v2, 2, v10
	v_lshlrev_b32_e32 v0, 4, v0
	s_addc_u32 s7, s7, 0
	v_and_b32_e32 v0, 48, v0
	v_ashrrev_i32_e32 v3, 31, v2
	v_lshl_add_u64 v[4:5], s[6:7], 0, v[0:1]
	v_lshlrev_b64 v[6:7], 10, v[2:3]
	v_lshl_add_u64 v[70:71], v[4:5], 0, v[6:7]
	v_add_u32_e32 v6, 64, v2
	s_lshl_b32 s2, s5, 15
	v_readlane_b32 s8, v224, 11
	v_ashrrev_i32_e32 v7, 31, v6
	s_add_u32 s8, s8, s2
	v_readlane_b32 s2, v224, 12
	v_lshlrev_b64 v[8:9], 10, v[6:7]
	s_addc_u32 s9, s2, 0
	v_lshl_add_u64 v[72:73], v[4:5], 0, v[8:9]
	v_and_b32_e32 v8, 15, v10
	v_lshlrev_b64 v[4:5], 8, v[6:7]
	v_lshl_add_u32 v12, v10, 4, 0
	v_lshrrev_b32_e32 v6, 1, v10
	s_mov_b32 s2, 0x3ffffc0
	v_lshlrev_b64 v[2:3], 8, v[2:3]
	v_and_or_b32 v13, v6, s2, v8
	v_readfirstlane_b32 s2, v12
	v_add_u32_e32 v8, 0x1000, v12
	v_lshl_add_u64 v[2:3], s[8:9], 0, v[2:3]
	v_and_b32_e32 v6, 12, v10
	s_waitcnt vmcnt(0)
	s_mov_b32 m0, s2
	v_readfirstlane_b32 s6, v8
	v_lshl_add_u64 v[74:75], v[2:3], 0, v[0:1]
	v_add_u32_e32 v2, 0x2000, v12
	v_lshrrev_b32_e32 v11, 4, v10
	v_lshl_add_u64 v[4:5], s[8:9], 0, v[4:5]
	v_lshrrev_b32_e64 v6, v6, s57
	global_load_lds_dwordx4 v[70:71], off
	s_mov_b32 m0, s6
	v_readfirstlane_b32 s7, v2
	v_add_u32_e32 v2, 0x3000, v12
	v_xor_b32_e32 v6, v6, v11
	global_load_lds_dwordx4 v[72:73], off
	v_lshl_add_u64 v[76:77], v[4:5], 0, v[0:1]
	s_mov_b32 m0, s7
	v_readfirstlane_b32 s8, v2
	v_add_u32_e32 v4, 0x4000, v12
	v_lshlrev_b32_e32 v11, 4, v6
	v_lshlrev_b32_e32 v6, 6, v10
	global_load_lds_dwordx4 v[74:75], off
	s_mov_b32 m0, s8
	v_readfirstlane_b32 s9, v4
	v_and_b32_e32 v10, 0x13c0, v6
	v_lshl_add_u64 v[6:7], v[70:71], 0, 64
	global_load_lds_dwordx4 v[76:77], off
	s_mov_b32 m0, s9
	v_add_u32_e32 v4, 0x5000, v12
	global_load_lds_dwordx4 v[6:7], off
	v_readfirstlane_b32 s9, v4
	v_add_u32_e32 v6, 0x6000, v12
	v_lshl_add_u64 v[8:9], v[72:73], 0, 64
	s_mov_b32 m0, s9
	v_readfirstlane_b32 s9, v6
	v_lshl_add_u64 v[2:3], v[74:75], 0, 64
	global_load_lds_dwordx4 v[8:9], off
	s_mov_b32 m0, s9
	v_and_b32_e32 v0, 48, v11
	global_load_lds_dwordx4 v[2:3], off
	v_add_u32_e32 v2, 0x7000, v12
	v_lshl_add_u64 v[4:5], v[76:77], 0, 64
	v_readfirstlane_b32 s9, v2
	s_mov_b32 m0, s9
	v_add_u32_e32 v11, 0x8000, v12
	global_load_lds_dwordx4 v[4:5], off
	v_add_u32_e32 v14, 0xb000, v12
	v_add_u32_e32 v15, 0xa000, v12
	v_add_u32_e32 v12, 0x9000, v12
	v_readfirstlane_b32 s9, v11
	s_waitcnt vmcnt(4) lgkmcnt(0)
	s_barrier
	v_lshl_add_u64 v[2:3], v[70:71], 0, s[78:79]
	s_mov_b32 m0, s9
	v_readfirstlane_b32 s9, v12
	v_lshl_add_u64 v[4:5], v[72:73], 0, s[78:79]
	global_load_lds_dwordx4 v[2:3], off
	s_mov_b32 m0, s9
	v_readfirstlane_b32 s9, v15
	v_lshl_add_u64 v[8:9], v[74:75], 0, s[78:79]
	global_load_lds_dwordx4 v[4:5], off
	s_mov_b32 m0, s9
	v_readfirstlane_b32 s9, v14
	v_lshl_add_u64 v[6:7], v[76:77], 0, s[78:79]
	global_load_lds_dwordx4 v[8:9], off
	s_mov_b32 m0, s9
	v_add3_u32 v90, 0, v10, v0
	v_lshlrev_b32_e32 v10, 6, v13
	global_load_lds_dwordx4 v[6:7], off
	v_add3_u32 v0, 0, v10, v0
	ds_read_b128 v[2:5], v90 offset:8192
	ds_read_b128 v[6:9], v90 offset:9216
	ds_read_b128 v[10:13], v0
	ds_read_b128 v[14:17], v0 offset:1024
	ds_read_b128 v[22:25], v90 offset:10240
	ds_read_b128 v[30:33], v90 offset:11264
	ds_read_b128 v[50:53], v0 offset:2048
	ds_read_b128 v[54:57], v0 offset:3072
	v_lshl_add_u64 v[70:71], v[70:71], 0, s[84:85]
	s_waitcnt vmcnt(4) lgkmcnt(0)
	s_barrier
	s_mov_b32 m0, s2
	v_lshl_add_u64 v[72:73], v[72:73], 0, s[84:85]
	global_load_lds_dwordx4 v[70:71], off
	s_mov_b32 m0, s6
	v_lshl_add_u64 v[74:75], v[74:75], 0, s[84:85]
	global_load_lds_dwordx4 v[72:73], off
	s_mov_b32 m0, s7
	v_lshl_add_u64 v[76:77], v[76:77], 0, s[84:85]
	global_load_lds_dwordx4 v[74:75], off
	s_mov_b32 m0, s8
	s_waitcnt lgkmcnt(0)
	s_setprio 1
	v_mfma_f32_16x16x32_bf16 v[18:21], v[2:5], v[10:13], 0
	global_load_lds_dwordx4 v[76:77], off
	s_setprio 0
	ds_read_b128 v[70:73], v90 offset:24576
	s_setprio 1
	v_mfma_f32_16x16x32_bf16 v[26:29], v[6:9], v[10:13], 0
	s_lshl_b32 s2, s5, 9
	v_lshl_add_u64 v[94:95], v[146:147], 0, s[2:3]
	v_readlane_b32 s2, v224, 1
	v_mfma_f32_16x16x32_bf16 v[34:37], v[22:25], v[10:13], 0
	s_add_u32 s0, s2, s0
	v_readlane_b32 s2, v224, 2
	s_addc_u32 s1, s2, s1
	v_mfma_f32_16x16x32_bf16 v[10:13], v[30:33], v[10:13], 0
	s_mov_b32 s2, 0xfffffc0
	s_add_u32 s0, s0, s4
	s_addc_u32 s1, s1, 0
	v_mfma_f32_16x16x32_bf16 v[38:41], v[2:5], v[14:17], 0
	v_mfma_f32_16x16x32_bf16 v[42:45], v[6:9], v[14:17], 0
	v_mfma_f32_16x16x32_bf16 v[46:49], v[22:25], v[14:17], 0
	v_mfma_f32_16x16x32_bf16 v[14:17], v[30:33], v[14:17], 0
	v_mfma_f32_16x16x32_bf16 v[58:61], v[2:5], v[50:53], 0
	v_mfma_f32_16x16x32_bf16 v[62:65], v[6:9], v[50:53], 0
	v_mfma_f32_16x16x32_bf16 v[66:69], v[22:25], v[50:53], 0
	v_mfma_f32_16x16x32_bf16 v[50:53], v[30:33], v[50:53], 0
	v_mfma_f32_16x16x32_bf16 v[2:5], v[2:5], v[54:57], 0
	v_mfma_f32_16x16x32_bf16 v[6:9], v[6:9], v[54:57], 0
	v_mfma_f32_16x16x32_bf16 v[22:25], v[22:25], v[54:57], 0
	v_mfma_f32_16x16x32_bf16 v[30:33], v[30:33], v[54:57], 0
	s_setprio 0
	ds_read_b128 v[54:57], v90 offset:25600
	ds_read_b128 v[74:77], v0 offset:16384
	ds_read_b128 v[78:81], v0 offset:17408
	ds_read_b128 v[82:85], v90 offset:26624
	ds_read_b128 v[86:89], v90 offset:27648
	s_waitcnt lgkmcnt(0)
	s_setprio 1
	v_mfma_f32_16x16x32_bf16 v[18:21], v[70:73], v[74:77], v[18:21]
	v_mfma_f32_16x16x32_bf16 v[26:29], v[54:57], v[74:77], v[26:29]
	v_mfma_f32_16x16x32_bf16 v[34:37], v[82:85], v[74:77], v[34:37]
	v_mfma_f32_16x16x32_bf16 v[10:13], v[86:89], v[74:77], v[10:13]
	v_mfma_f32_16x16x32_bf16 v[38:41], v[70:73], v[78:81], v[38:41]
	v_mfma_f32_16x16x32_bf16 v[42:45], v[54:57], v[78:81], v[42:45]
	v_mfma_f32_16x16x32_bf16 v[46:49], v[82:85], v[78:81], v[46:49]
	v_mfma_f32_16x16x32_bf16 v[14:17], v[86:89], v[78:81], v[14:17]
	s_setprio 0
	ds_read_b128 v[74:77], v0 offset:18432
	ds_read_b128 v[78:81], v0 offset:19456
	s_waitcnt vmcnt(4) lgkmcnt(0)
	s_barrier
	s_waitcnt lgkmcnt(0)
	s_setprio 1
	v_mfma_f32_16x16x32_bf16 v[58:61], v[70:73], v[74:77], v[58:61]
	v_mfma_f32_16x16x32_bf16 v[62:65], v[54:57], v[74:77], v[62:65]
	v_mfma_f32_16x16x32_bf16 v[66:69], v[82:85], v[74:77], v[66:69]
	v_mfma_f32_16x16x32_bf16 v[50:53], v[86:89], v[74:77], v[50:53]
	v_mfma_f32_16x16x32_bf16 v[2:5], v[70:73], v[78:81], v[2:5]
	v_mfma_f32_16x16x32_bf16 v[6:9], v[54:57], v[78:81], v[6:9]
	s_setprio 0
	ds_read_b128 v[54:57], v90 offset:40960
	s_setprio 1
	v_mfma_f32_16x16x32_bf16 v[22:25], v[82:85], v[78:81], v[22:25]
	v_mfma_f32_16x16x32_bf16 v[30:33], v[86:89], v[78:81], v[30:33]
	s_setprio 0
	ds_read_b128 v[70:73], v90 offset:41984
	ds_read_b128 v[74:77], v0 offset:32768
	ds_read_b128 v[78:81], v0 offset:33792
	ds_read_b128 v[82:85], v90 offset:43008
	ds_read_b128 v[86:89], v90 offset:44032
	s_waitcnt lgkmcnt(0)
	s_setprio 1
	v_mfma_f32_16x16x32_bf16 v[18:21], v[54:57], v[74:77], v[18:21]
	v_mfma_f32_16x16x32_bf16 v[26:29], v[70:73], v[74:77], v[26:29]
	v_mfma_f32_16x16x32_bf16 v[34:37], v[82:85], v[74:77], v[34:37]
	v_mfma_f32_16x16x32_bf16 v[10:13], v[86:89], v[74:77], v[10:13]
	v_mfma_f32_16x16x32_bf16 v[38:41], v[54:57], v[78:81], v[38:41]
	v_mfma_f32_16x16x32_bf16 v[42:45], v[70:73], v[78:81], v[42:45]
	v_mfma_f32_16x16x32_bf16 v[46:49], v[82:85], v[78:81], v[46:49]
	v_mfma_f32_16x16x32_bf16 v[14:17], v[86:89], v[78:81], v[14:17]
	s_setprio 0
	ds_read_b128 v[74:77], v0 offset:34816
	ds_read_b128 v[78:81], v0 offset:35840
	s_waitcnt vmcnt(0) lgkmcnt(0)
	s_barrier
	s_waitcnt lgkmcnt(0)
	s_setprio 1
	v_mfma_f32_16x16x32_bf16 v[58:61], v[54:57], v[74:77], v[58:61]
	v_mfma_f32_16x16x32_bf16 v[62:65], v[70:73], v[74:77], v[62:65]
	v_mfma_f32_16x16x32_bf16 v[66:69], v[82:85], v[74:77], v[66:69]
	v_mfma_f32_16x16x32_bf16 v[50:53], v[86:89], v[74:77], v[50:53]
	v_mfma_f32_16x16x32_bf16 v[2:5], v[54:57], v[78:81], v[2:5]
	s_setprio 0
	ds_read_b128 v[54:57], v90 offset:8192
	s_setprio 1
	v_mfma_f32_16x16x32_bf16 v[6:9], v[70:73], v[78:81], v[6:9]
	v_mfma_f32_16x16x32_bf16 v[22:25], v[82:85], v[78:81], v[22:25]
	v_mfma_f32_16x16x32_bf16 v[30:33], v[86:89], v[78:81], v[30:33]
	s_setprio 0
	ds_read_b128 v[70:73], v90 offset:9216
	ds_read_b128 v[74:77], v0
	ds_read_b128 v[78:81], v0 offset:1024
	ds_read_b128 v[82:85], v90 offset:10240
	ds_read_b128 v[86:89], v90 offset:11264
	s_waitcnt lgkmcnt(0)
	s_setprio 1
	v_mfma_f32_16x16x32_bf16 v[18:21], v[54:57], v[74:77], v[18:21]
	v_mfma_f32_16x16x32_bf16 v[26:29], v[70:73], v[74:77], v[26:29]
	v_mfma_f32_16x16x32_bf16 v[34:37], v[82:85], v[74:77], v[34:37]
	v_mfma_f32_16x16x32_bf16 v[10:13], v[86:89], v[74:77], v[10:13]
	v_mfma_f32_16x16x32_bf16 v[38:41], v[54:57], v[78:81], v[38:41]
	v_mfma_f32_16x16x32_bf16 v[42:45], v[70:73], v[78:81], v[42:45]
	v_mfma_f32_16x16x32_bf16 v[46:49], v[82:85], v[78:81], v[46:49]
	v_mfma_f32_16x16x32_bf16 v[14:17], v[86:89], v[78:81], v[14:17]
	s_setprio 0
	ds_read_b128 v[74:77], v0 offset:2048
	ds_read_b128 v[78:81], v0 offset:3072
	s_waitcnt vmcnt(0) lgkmcnt(0)
	s_barrier
	s_setprio 1
	v_mfma_f32_16x16x32_bf16 v[58:61], v[54:57], v[74:77], v[58:61]
	global_load_dwordx4 v[90:93], v[94:95], off
	v_mfma_f32_16x16x32_bf16 v[2:5], v[54:57], v[78:81], v[2:5]
	global_load_dwordx4 v[54:57], v[94:95], off offset:128
	v_mfma_f32_16x16x32_bf16 v[62:65], v[70:73], v[74:77], v[62:65]
	v_mfma_f32_16x16x32_bf16 v[66:69], v[82:85], v[74:77], v[66:69]
	v_mfma_f32_16x16x32_bf16 v[50:53], v[86:89], v[74:77], v[50:53]
	global_load_dwordx4 v[74:77], v[94:95], off offset:64
	s_setprio 0
	s_waitcnt vmcnt(2)
	v_pk_mul_f32 v[18:19], v[18:19], v[90:91]
	s_setprio 1
	v_mfma_f32_16x16x32_bf16 v[6:9], v[70:73], v[78:81], v[6:9]
	global_load_dwordx4 v[70:73], v[94:95], off offset:192
	s_setprio 0
	s_waitcnt vmcnt(2)
	v_pk_mul_f32 v[34:35], v[34:35], v[54:55]
	v_pk_mul_f32 v[46:47], v[46:47], v[54:55]
	s_setprio 1
	v_mfma_f32_16x16x32_bf16 v[22:25], v[82:85], v[78:81], v[22:25]
	v_mul_f32_e64 v66, v66, v54
	v_mul_f32_e64 v67, v67, v55
	v_pk_mul_f32 v[36:37], v[36:37], v[56:57]
	v_pk_mul_f32 v[48:49], v[48:49], v[56:57]
	v_mfma_f32_16x16x32_bf16 v[30:33], v[86:89], v[78:81], v[30:33]
	v_mul_f32_e64 v20, v20, v92
	v_mul_f32_e64 v21, v21, v93
	s_nop 0
	v_pk_mul_f32 v[22:23], v[22:23], v[54:55]
	v_pk_mul_f32 v[54:55], v[68:69], v[56:57]
	v_pk_mul_f32 v[24:25], v[24:25], v[56:57]
	v_mov_b32_e32 v56, v196
	s_setprio 0
	s_waitcnt vmcnt(1)
	v_pk_mul_f32 v[26:27], v[26:27], v[74:75]
	v_and_b32_e32 v57, 15, v56
	v_lshrrev_b32_e32 v68, 1, v56
	v_and_b32_e32 v0, 64, v56
	v_and_or_b32 v69, v68, s2, v57
	v_pk_mul_f32 v[28:29], v[28:29], v[76:77]
	v_lshl_add_u32 v0, v0, 1, 0
	v_and_b32_e32 v68, 24, v68
	v_mul_lo_u32 v69, v69, s30
	v_add3_u32 v0, v0, v68, v69
	v_cvt_pk_bf16_f32 v18, v18, v19
	v_cvt_pk_bf16_f32 v19, v20, v21
	v_cvt_pk_bf16_f32 v20, v26, v27
	v_cvt_pk_bf16_f32 v21, v28, v29
	v_pk_mul_f32 v[38:39], v[38:39], v[90:91]
	v_pk_mul_f32 v[40:41], v[40:41], v[92:93]
	v_pk_mul_f32 v[42:43], v[42:43], v[74:75]
	v_pk_mul_f32 v[44:45], v[44:45], v[76:77]
	ds_write2_b64 v0, v[18:19], v[20:21] offset1:4
	v_cvt_pk_bf16_f32 v18, v34, v35
	v_cvt_pk_bf16_f32 v19, v36, v37
	v_pk_mul_f32 v[2:3], v[2:3], v[90:91]
	v_pk_mul_f32 v[4:5], v[4:5], v[92:93]
	v_pk_mul_f32 v[6:7], v[6:7], v[74:75]
	v_pk_mul_f32 v[8:9], v[8:9], v[76:77]
	v_pk_mul_f32 v[58:59], v[58:59], v[90:91]
	v_pk_mul_f32 v[60:61], v[60:61], v[92:93]
	v_pk_mul_f32 v[62:63], v[62:63], v[74:75]
	v_pk_mul_f32 v[64:65], v[64:65], v[76:77]
	v_cvt_pk_bf16_f32 v2, v2, v3
	v_cvt_pk_bf16_f32 v3, v4, v5
	v_cvt_pk_bf16_f32 v4, v6, v7
	v_cvt_pk_bf16_f32 v5, v8, v9
	v_add_u32_e32 v6, 0x100, v56
	s_waitcnt vmcnt(0)
	v_pk_mul_f32 v[10:11], v[10:11], v[70:71]
	v_pk_mul_f32 v[12:13], v[12:13], v[72:73]
	v_cvt_pk_bf16_f32 v10, v10, v11
	v_cvt_pk_bf16_f32 v11, v12, v13
	v_pk_mul_f32 v[14:15], v[14:15], v[70:71]
	v_pk_mul_f32 v[16:17], v[16:17], v[72:73]
	ds_write2_b64 v0, v[18:19], v[10:11] offset0:8 offset1:12
	v_cvt_pk_bf16_f32 v10, v38, v39
	v_cvt_pk_bf16_f32 v11, v40, v41
	v_cvt_pk_bf16_f32 v12, v42, v43
	v_cvt_pk_bf16_f32 v13, v44, v45
	v_add_u32_e32 v18, 0x1000, v0
	v_pk_mul_f32 v[30:31], v[30:31], v[70:71]
	v_pk_mul_f32 v[32:33], v[32:33], v[72:73]
	ds_write2_b64 v18, v[10:11], v[12:13] offset0:32 offset1:36
	v_cvt_pk_bf16_f32 v10, v46, v47
	v_cvt_pk_bf16_f32 v11, v48, v49
	v_cvt_pk_bf16_f32 v12, v14, v15
	v_cvt_pk_bf16_f32 v13, v16, v17
	v_add_u32_e32 v14, 0x2000, v0
	v_add_u32_e32 v0, 0x3000, v0
	v_pk_mul_f32 v[50:51], v[50:51], v[70:71]
	v_pk_mul_f32 v[52:53], v[52:53], v[72:73]
	ds_write2_b64 v18, v[10:11], v[12:13] offset0:40 offset1:44
	v_cvt_pk_bf16_f32 v10, v58, v59
	v_cvt_pk_bf16_f32 v11, v60, v61
	v_cvt_pk_bf16_f32 v12, v62, v63
	v_cvt_pk_bf16_f32 v13, v64, v65
	ds_write2_b64 v0, v[2:3], v[4:5] offset0:96 offset1:100
	v_cvt_pk_bf16_f32 v2, v22, v23
	v_cvt_pk_bf16_f32 v3, v24, v25
	v_cvt_pk_bf16_f32 v4, v30, v31
	v_cvt_pk_bf16_f32 v5, v32, v33
	ds_write2_b64 v14, v[10:11], v[12:13] offset0:64 offset1:68
	v_cvt_pk_bf16_f32 v10, v66, v67
	v_cvt_pk_bf16_f32 v11, v54, v55
	v_cvt_pk_bf16_f32 v12, v50, v51
	v_cvt_pk_bf16_f32 v13, v52, v53
	ds_write2_b64 v0, v[2:3], v[4:5] offset0:104 offset1:108
	v_lshlrev_b32_e32 v0, 4, v57
	v_ashrrev_i32_e32 v2, 4, v56
	ds_write2_b64 v14, v[10:11], v[12:13] offset0:72 offset1:76
	v_lshl_add_u64 v[10:11], s[0:1], 0, v[0:1]
	v_add_u32_e32 v0, 0, v0
	v_ashrrev_i32_e32 v3, 31, v2
	v_mad_u64_u32 v[4:5], s[0:1], v2, s30, v[0:1]
	v_lshlrev_b64 v[2:3], 10, v[2:3]
	s_waitcnt lgkmcnt(0)
	s_barrier
	v_lshl_add_u64 v[12:13], v[10:11], 0, v[2:3]
	ds_read_b128 v[2:5], v4
	v_ashrrev_i32_e32 v14, 4, v6
	v_mad_u64_u32 v[6:7], s[0:1], v14, s30, v[0:1]
	ds_read_b128 v[6:9], v6
	v_ashrrev_i32_e32 v15, 31, v14
	s_waitcnt lgkmcnt(1)
	global_store_dwordx4 v[12:13], v[2:5], off
	s_nop 1
	v_lshlrev_b64 v[2:3], 10, v[14:15]
	v_lshl_add_u64 v[2:3], v[10:11], 0, v[2:3]
	s_waitcnt lgkmcnt(0)
	global_store_dwordx4 v[2:3], v[6:9], off
	v_add_u32_e32 v2, 0x200, v56
	v_ashrrev_i32_e32 v2, 4, v2
	v_ashrrev_i32_e32 v3, 31, v2
	v_mad_u64_u32 v[4:5], s[0:1], v2, s30, v[0:1]
	v_lshlrev_b64 v[2:3], 10, v[2:3]
	v_add_u32_e32 v6, 0x300, v56
	v_lshl_add_u64 v[12:13], v[10:11], 0, v[2:3]
	ds_read_b128 v[2:5], v4
	v_ashrrev_i32_e32 v14, 4, v6
	v_mad_u64_u32 v[6:7], s[0:1], v14, s30, v[0:1]
	ds_read_b128 v[6:9], v6
	v_ashrrev_i32_e32 v15, 31, v14
	s_waitcnt lgkmcnt(1)
	global_store_dwordx4 v[12:13], v[2:5], off
	s_nop 1
	v_lshlrev_b64 v[2:3], 10, v[14:15]
	v_lshl_add_u64 v[2:3], v[10:11], 0, v[2:3]
	s_waitcnt lgkmcnt(0)
	global_store_dwordx4 v[2:3], v[6:9], off
	v_add_u32_e32 v2, 0x400, v56
	v_ashrrev_i32_e32 v2, 4, v2
	v_ashrrev_i32_e32 v3, 31, v2
	v_mad_u64_u32 v[4:5], s[0:1], v2, s30, v[0:1]
	v_lshlrev_b64 v[2:3], 10, v[2:3]
	v_add_u32_e32 v6, 0x500, v56
	v_lshl_add_u64 v[12:13], v[10:11], 0, v[2:3]
	ds_read_b128 v[2:5], v4
	v_ashrrev_i32_e32 v14, 4, v6
	v_mad_u64_u32 v[6:7], s[0:1], v14, s30, v[0:1]
	ds_read_b128 v[6:9], v6
	v_ashrrev_i32_e32 v15, 31, v14
	s_waitcnt lgkmcnt(1)
	global_store_dwordx4 v[12:13], v[2:5], off
	s_nop 1
	v_lshlrev_b64 v[2:3], 10, v[14:15]
	v_lshl_add_u64 v[2:3], v[10:11], 0, v[2:3]
	s_waitcnt lgkmcnt(0)
	global_store_dwordx4 v[2:3], v[6:9], off
	v_add_u32_e32 v2, 0x600, v56
	v_ashrrev_i32_e32 v2, 4, v2
	v_ashrrev_i32_e32 v3, 31, v2
	v_mad_u64_u32 v[4:5], s[0:1], v2, s30, v[0:1]
	v_lshlrev_b64 v[2:3], 10, v[2:3]
	v_add_u32_e32 v6, 0x700, v56
	v_lshl_add_u64 v[12:13], v[10:11], 0, v[2:3]
	ds_read_b128 v[2:5], v4
	v_ashrrev_i32_e32 v14, 4, v6
	v_mad_u64_u32 v[6:7], s[0:1], v14, s30, v[0:1]
	ds_read_b128 v[6:9], v6
	v_ashrrev_i32_e32 v15, 31, v14
	s_waitcnt lgkmcnt(1)
	global_store_dwordx4 v[12:13], v[2:5], off
	s_mov_b64 s[0:1], 0
	s_nop 0
	v_lshlrev_b64 v[2:3], 10, v[14:15]
	v_lshl_add_u64 v[2:3], v[10:11], 0, v[2:3]
	s_waitcnt lgkmcnt(0)
	global_store_dwordx4 v[2:3], v[6:9], off
	s_barrier

.LBB0_358:
	v_lshl_add_u32 v143, s16, 14, v142
	v_add_u32_e32 v146, 0x1000, v143
	v_readfirstlane_b32 s18, v143
	s_waitcnt vmcnt(4) lgkmcnt(0)
	s_barrier
	v_add_u32_e32 v145, 0x2000, v143
	s_mov_b32 m0, s18
	v_readfirstlane_b32 s18, v146
	v_add_u32_e32 v144, 0x3000, v143
	global_load_lds_dwordx4 v[84:85], off
	s_mov_b32 m0, s18
	v_readfirstlane_b32 s18, v145
	global_load_lds_dwordx4 v[86:87], off
	s_mov_b32 m0, s18
	v_readfirstlane_b32 s18, v144
	global_load_lds_dwordx4 v[74:75], off
	s_mov_b32 m0, s18
	s_lshl_b32 s18, s11, 14
	global_load_lds_dwordx4 v[72:73], off
	s_add_i32 s18, s18, 0
	v_add3_u32 v143, s18, v141, v0
	v_lshl_add_u64 v[80:81], v[72:73], 0, 64
	v_lshl_add_u64 v[82:83], v[74:75], 0, 64
	v_lshl_add_u64 v[78:79], v[84:85], 0, 64
	v_lshl_add_u64 v[76:77], v[86:87], 0, 64
	ds_read_b128 v[72:75], v143 offset:8192
	ds_read_b128 v[84:87], v143 offset:9216
	ds_read_b128 v[144:147], v143 offset:10240
	ds_read_b128 v[148:151], v143 offset:11264
	v_add3_u32 v143, s18, v71, v0
	ds_read_b128 v[152:155], v143
	ds_read_b128 v[156:159], v143 offset:1024
	ds_read_b128 v[160:163], v143 offset:2048
	ds_read_b128 v[164:167], v143 offset:3072
	s_add_i32 s18, s11, 1
	s_cmp_lg_u32 s11, 2
	s_waitcnt lgkmcnt(0)
	s_setprio 1
	v_mfma_f32_16x16x32_bf16 v[62:65], v[152:155], v[72:75], v[62:65]
	s_cselect_b32 s11, s18, 0
	s_add_i32 s18, s16, 1
	s_cmp_lg_u32 s16, 2
	v_mfma_f32_16x16x32_bf16 v[58:61], v[152:155], v[84:87], v[58:61]
	s_cselect_b32 s16, s18, 0
	s_add_i32 s17, s17, -1
	s_cmp_eq_u32 s17, 0
	v_mfma_f32_16x16x32_bf16 v[54:57], v[152:155], v[144:147], v[54:57]
	v_mfma_f32_16x16x32_bf16 v[50:53], v[152:155], v[148:151], v[50:53]
	v_mfma_f32_16x16x32_bf16 v[46:49], v[156:159], v[72:75], v[46:49]
	v_mfma_f32_16x16x32_bf16 v[42:45], v[156:159], v[84:87], v[42:45]
	v_mfma_f32_16x16x32_bf16 v[38:41], v[156:159], v[144:147], v[38:41]
	v_mfma_f32_16x16x32_bf16 v[34:37], v[156:159], v[148:151], v[34:37]
	v_mfma_f32_16x16x32_bf16 v[30:33], v[160:163], v[72:75], v[30:33]
	v_mfma_f32_16x16x32_bf16 v[26:29], v[160:163], v[84:87], v[26:29]
	v_mfma_f32_16x16x32_bf16 v[22:25], v[160:163], v[144:147], v[22:25]
	v_mfma_f32_16x16x32_bf16 v[18:21], v[160:163], v[148:151], v[18:21]
	v_mfma_f32_16x16x32_bf16 v[14:17], v[164:167], v[72:75], v[14:17]
	v_mov_b64_e32 v[74:75], v[82:83]
	v_mov_b64_e32 v[72:73], v[80:81]
	v_mfma_f32_16x16x32_bf16 v[10:13], v[164:167], v[84:87], v[10:13]
	v_mov_b64_e32 v[84:85], v[78:79]
	v_mov_b64_e32 v[86:87], v[76:77]
	v_mfma_f32_16x16x32_bf16 v[6:9], v[164:167], v[144:147], v[6:9]
	v_mfma_f32_16x16x32_bf16 v[2:5], v[164:167], v[148:151], v[2:5]
	s_setprio 0
	s_cbranch_scc0 .LBB0_358
	s_lshl_b32 s16, s11, 14
	s_add_i32 s17, s16, 0
	s_waitcnt vmcnt(4) lgkmcnt(0)
	s_barrier
	v_add3_u32 v84, s17, v141, v0
	v_add3_u32 v154, s17, v71, v0
	ds_read_b128 v[72:75], v84 offset:8192
	ds_read_b128 v[76:79], v84 offset:9216
	ds_read_b128 v[80:83], v84 offset:10240
	ds_read_b128 v[84:87], v84 offset:11264
	ds_read_b128 v[142:145], v154
	ds_read_b128 v[146:149], v154 offset:1024
	ds_read_b128 v[150:153], v154 offset:2048
	ds_read_b128 v[154:157], v154 offset:3072
	s_addk_i32 s16, 0x4000
	s_cmp_lg_u32 s11, 2
	s_cselect_b32 s11, s16, 0
	s_add_i32 s11, s11, 0
	s_waitcnt lgkmcnt(0)
	v_mfma_f32_16x16x32_bf16 v[62:65], v[142:145], v[72:75], v[62:65]
	s_waitcnt vmcnt(0) lgkmcnt(0)
	s_barrier
	v_mfma_f32_16x16x32_bf16 v[46:49], v[146:149], v[72:75], v[46:49]
	s_lshl_b32 s16, s36, 1
	v_mfma_f32_16x16x32_bf16 v[30:33], v[150:153], v[72:75], v[30:33]
	v_mfma_f32_16x16x32_bf16 v[14:17], v[154:157], v[72:75], v[14:17]
	v_mfma_f32_16x16x32_bf16 v[72:75], v[154:157], v[76:79], v[10:13]
	s_nop 2
	v_add3_u32 v10, s11, v141, v0
	v_add3_u32 v0, s11, v71, v0
	v_mfma_f32_16x16x32_bf16 v[58:61], v[142:145], v[76:79], v[58:61]
	v_mov_b32_e32 v71, v196
	s_lshl_b32 s11, s37, 3
	s_add_i32 s11, s16, s11
	v_mfma_f32_16x16x32_bf16 v[54:57], v[142:145], v[80:83], v[54:57]
	s_add_i32 s11, s11, -8
	s_mul_hi_i32 s16, s11, 0x108000
	s_mul_i32 s11, s11, 0x108000
	v_mfma_f32_16x16x32_bf16 v[50:53], v[142:145], v[84:87], v[50:53]
	s_add_u32 s11, s22, s11
	s_addc_u32 s18, s23, s16
	s_lshl_b64 s[16:17], s[2:3], 1
	v_mfma_f32_16x16x32_bf16 v[42:45], v[146:149], v[76:79], v[42:45]
	s_add_u32 s16, s11, s16
	s_addc_u32 s17, s18, s17
	s_movk_i32 s11, 0x4200
	v_mfma_f32_16x16x32_bf16 v[38:41], v[146:149], v[80:83], v[38:41]
	v_mfma_f32_16x16x32_bf16 v[34:37], v[146:149], v[84:87], v[34:37]
	v_mfma_f32_16x16x32_bf16 v[26:29], v[150:153], v[76:79], v[26:29]
	v_mfma_f32_16x16x32_bf16 v[22:25], v[150:153], v[80:83], v[22:25]
	v_mfma_f32_16x16x32_bf16 v[18:21], v[150:153], v[84:87], v[18:21]
	v_mfma_f32_16x16x32_bf16 v[76:79], v[154:157], v[80:83], v[6:9]
	v_mfma_f32_16x16x32_bf16 v[80:83], v[154:157], v[84:87], v[2:5]
	s_nop 2
	ds_read_b128 v[2:5], v10 offset:8192
	ds_read_b128 v[6:9], v10 offset:9216
	ds_read_b128 v[84:87], v10 offset:10240
	ds_read_b128 v[142:145], v10 offset:11264
	ds_read_b128 v[10:13], v0
	ds_read_b128 v[146:149], v0 offset:1024
	ds_read_b128 v[150:153], v0 offset:2048
	ds_read_b128 v[154:157], v0 offset:3072
	s_waitcnt vmcnt(0) lgkmcnt(0)
	v_mfma_f32_16x16x32_bf16 v[58:61], v[10:13], v[6:9], v[58:61]
	s_barrier
	v_mfma_f32_16x16x32_bf16 v[42:45], v[146:149], v[6:9], v[42:45]
	v_mfma_f32_16x16x32_bf16 v[26:29], v[150:153], v[6:9], v[26:29]
	v_mfma_f32_16x16x32_bf16 v[6:9], v[154:157], v[6:9], v[72:75]
	s_nop 2
	ds_read_b128 v[72:75], v139
	v_mfma_f32_16x16x32_bf16 v[50:53], v[10:13], v[142:145], v[50:53]
	s_waitcnt lgkmcnt(0)
	v_pk_mul_f32 v[58:59], v[58:59], v[72:73]
	v_mfma_f32_16x16x32_bf16 v[46:49], v[146:149], v[2:5], v[46:49]
	v_mul_f32_e64 v60, v60, v74
	v_mul_f32_e64 v61, v61, v75
	v_mfma_f32_16x16x32_bf16 v[38:41], v[146:149], v[84:87], v[38:41]
	v_mfma_f32_16x16x32_bf16 v[34:37], v[146:149], v[142:145], v[34:37]
	v_mfma_f32_16x16x32_bf16 v[146:149], v[150:153], v[142:145], v[18:21]
	s_nop 2
	v_mul_f32_e64 v18, v50, v72
	v_mul_f32_e64 v19, v51, v73
	v_pk_mul_f32 v[20:21], v[52:53], v[74:75]
	ds_read_b128 v[50:53], v139 offset:64
	v_mfma_f32_16x16x32_bf16 v[62:65], v[10:13], v[2:5], v[62:65]
	v_cvt_pk_bf16_f32 v18, v18, v19
	v_cvt_pk_bf16_f32 v19, v20, v21
	s_waitcnt lgkmcnt(0)
	v_pk_mul_f32 v[46:47], v[46:47], v[50:51]
	v_mfma_f32_16x16x32_bf16 v[54:57], v[10:13], v[84:87], v[54:57]
	s_nop 2
	v_mul_f32_e64 v62, v62, v72
	v_mul_f32_e64 v63, v63, v73
	v_pk_mul_f32 v[42:43], v[42:43], v[50:51]
	v_pk_mul_f32 v[38:39], v[38:39], v[50:51]
	v_mfma_f32_16x16x32_bf16 v[30:33], v[150:153], v[2:5], v[30:33]
	v_mul_f32_e64 v64, v64, v74
	v_mul_f32_e64 v65, v65, v75
	v_pk_mul_f32 v[54:55], v[54:55], v[72:73]
	v_pk_mul_f32 v[72:73], v[34:35], v[50:51]
	v_pk_mul_f32 v[50:51], v[36:37], v[52:53]
	ds_read_b128 v[34:37], v139 offset:128
	v_mfma_f32_16x16x32_bf16 v[22:25], v[150:153], v[84:87], v[22:25]
	v_mul_f32_e64 v56, v56, v74
	v_mul_f32_e64 v57, v57, v75
	v_pk_mul_f32 v[48:49], v[48:49], v[52:53]
	v_pk_mul_f32 v[44:45], v[44:45], v[52:53]
	v_pk_mul_f32 v[40:41], v[40:41], v[52:53]
	s_waitcnt lgkmcnt(0)
	v_pk_mul_f32 v[52:53], v[146:147], v[34:35]
	v_pk_mul_f32 v[30:31], v[30:31], v[34:35]
	v_pk_mul_f32 v[26:27], v[26:27], v[34:35]
	v_pk_mul_f32 v[34:35], v[22:23], v[34:35]
	v_pk_mul_f32 v[74:75], v[148:149], v[36:37]
	v_pk_mul_f32 v[32:33], v[32:33], v[36:37]
	v_pk_mul_f32 v[28:29], v[28:29], v[36:37]
	v_pk_mul_f32 v[36:37], v[24:25], v[36:37]
	ds_read_b128 v[22:25], v139 offset:192
	v_mfma_f32_16x16x32_bf16 v[10:13], v[154:157], v[2:5], v[14:17]
	v_cvt_pk_bf16_f32 v20, v46, v47
	v_and_b32_e32 v0, 0x4f, v71
	v_mfma_f32_16x16x32_bf16 v[2:5], v[154:157], v[84:87], v[76:79]
	s_waitcnt lgkmcnt(0)
	v_pk_mul_f32 v[6:7], v[6:7], v[22:23]
	s_nop 2
	v_pk_mul_f32 v[10:11], v[10:11], v[22:23]
	v_pk_mul_f32 v[12:13], v[12:13], v[24:25]
	v_mfma_f32_16x16x32_bf16 v[14:17], v[154:157], v[142:145], v[80:83]
	v_mul_f32_e64 v8, v8, v24
	v_mul_f32_e64 v9, v9, v25
	v_pk_mul_f32 v[2:3], v[2:3], v[22:23]
	v_pk_mul_f32 v[4:5], v[4:5], v[24:25]
	v_mul_u32_u24_e32 v0, 0x110, v0
	v_cvt_pk_bf16_f32 v21, v48, v49
	s_nop 1
	v_pk_mul_f32 v[14:15], v[14:15], v[22:23]
	v_lshrrev_b32_e32 v22, 1, v71
	v_and_b32_e32 v23, 0xffffff80, v71
	v_pk_mul_f32 v[16:17], v[16:17], v[24:25]
	v_add_u32_e32 v24, 0, v23
	v_and_b32_e32 v25, 24, v22
	v_cvt_pk_bf16_f32 v22, v62, v63
	v_cvt_pk_bf16_f32 v23, v64, v65
	v_add3_u32 v0, v24, v25, v0
	v_cvt_pk_bf16_f32 v24, v58, v59
	v_cvt_pk_bf16_f32 v25, v60, v61
	ds_write2_b64 v0, v[22:23], v[20:21] offset1:4
	v_cvt_pk_bf16_f32 v20, v42, v43
	v_cvt_pk_bf16_f32 v21, v44, v45
	v_add_u32_e32 v42, 0x1000, v0
	v_cvt_pk_bf16_f32 v54, v54, v55
	v_cvt_pk_bf16_f32 v55, v56, v57
	ds_write2_b64 v42, v[24:25], v[20:21] offset0:32 offset1:36
	v_cvt_pk_bf16_f32 v20, v38, v39
	v_cvt_pk_bf16_f32 v21, v40, v41
	v_add_u32_e32 v38, 0x2000, v0
	ds_write2_b64 v38, v[54:55], v[20:21] offset0:64 offset1:68
	v_cvt_pk_bf16_f32 v20, v72, v73
	v_cvt_pk_bf16_f32 v21, v50, v51
	v_add_u32_e32 v39, 0x3000, v0
	ds_write2_b64 v39, v[18:19], v[20:21] offset0:96 offset1:100
	v_cvt_pk_bf16_f32 v18, v30, v31
	v_cvt_pk_bf16_f32 v19, v32, v33
	v_cvt_pk_bf16_f32 v10, v10, v11
	v_cvt_pk_bf16_f32 v11, v12, v13
	ds_write2_b64 v0, v[18:19], v[10:11] offset0:8 offset1:12
	v_lshlrev_b32_e32 v0, 4, v71
	v_cvt_pk_bf16_f32 v20, v26, v27
	v_cvt_pk_bf16_f32 v21, v28, v29
	v_cvt_pk_bf16_f32 v22, v34, v35
	v_cvt_pk_bf16_f32 v23, v36, v37
	v_cvt_pk_bf16_f32 v6, v6, v7
	v_cvt_pk_bf16_f32 v7, v8, v9
	v_cvt_pk_bf16_f32 v2, v2, v3
	v_cvt_pk_bf16_f32 v3, v4, v5
	v_and_b32_e32 v0, 0xf0, v0
	v_cvt_pk_bf16_f32 v24, v52, v53
	v_cvt_pk_bf16_f32 v25, v74, v75
	ds_write2_b64 v42, v[20:21], v[6:7] offset0:40 offset1:44
	ds_write2_b64 v38, v[22:23], v[2:3] offset0:72 offset1:76
	v_cvt_pk_bf16_f32 v2, v14, v15
	v_cvt_pk_bf16_f32 v3, v16, v17
	v_lshl_add_u64 v[6:7], s[16:17], 0, v[0:1]
	v_add_u32_e32 v0, 0, v0
	v_ashrrev_i32_e32 v4, 4, v71
	ds_write2_b64 v39, v[24:25], v[2:3] offset0:104 offset1:108
	v_mad_u64_u32 v[2:3], s[16:17], v4, s30, v[0:1]
	s_waitcnt lgkmcnt(0)
	s_barrier
	v_mad_i64_i32 v[8:9], s[16:17], v4, s11, v[6:7]
	ds_read_b128 v[2:5], v2
	s_waitcnt lgkmcnt(0)
	global_store_dwordx4 v[8:9], v[2:5], off
	s_nop 1
	v_add_u32_e32 v2, 0x100, v71
	v_ashrrev_i32_e32 v4, 4, v2
	v_mad_u64_u32 v[2:3], s[16:17], v4, s30, v[0:1]
	v_mad_i64_i32 v[8:9], s[16:17], v4, s11, v[6:7]
	ds_read_b128 v[2:5], v2
	s_waitcnt lgkmcnt(0)
	global_store_dwordx4 v[8:9], v[2:5], off
	s_nop 1
	v_add_u32_e32 v2, 0x200, v71
	v_ashrrev_i32_e32 v4, 4, v2
	v_mad_u64_u32 v[2:3], s[16:17], v4, s30, v[0:1]
	v_mad_i64_i32 v[8:9], s[16:17], v4, s11, v[6:7]
	ds_read_b128 v[2:5], v2
	s_waitcnt lgkmcnt(0)
	global_store_dwordx4 v[8:9], v[2:5], off
	s_nop 1
	v_add_u32_e32 v2, 0x300, v71
	v_ashrrev_i32_e32 v4, 4, v2
	v_mad_u64_u32 v[2:3], s[16:17], v4, s30, v[0:1]
	v_mad_i64_i32 v[8:9], s[16:17], v4, s11, v[6:7]
	ds_read_b128 v[2:5], v2
	s_waitcnt lgkmcnt(0)
	global_store_dwordx4 v[8:9], v[2:5], off
	s_nop 1
	v_add_u32_e32 v2, 0x400, v71
	v_ashrrev_i32_e32 v4, 4, v2
	v_mad_u64_u32 v[2:3], s[16:17], v4, s30, v[0:1]
	v_mad_i64_i32 v[8:9], s[16:17], v4, s11, v[6:7]
	ds_read_b128 v[2:5], v2
	s_waitcnt lgkmcnt(0)
	global_store_dwordx4 v[8:9], v[2:5], off
	s_nop 1
	v_add_u32_e32 v2, 0x500, v71
	v_ashrrev_i32_e32 v4, 4, v2
	v_mad_u64_u32 v[2:3], s[16:17], v4, s30, v[0:1]
	v_mad_i64_i32 v[8:9], s[16:17], v4, s11, v[6:7]
	ds_read_b128 v[2:5], v2
	s_waitcnt lgkmcnt(0)
	global_store_dwordx4 v[8:9], v[2:5], off
	s_nop 1
	v_add_u32_e32 v2, 0x600, v71
	v_ashrrev_i32_e32 v4, 4, v2
	v_mad_u64_u32 v[2:3], s[16:17], v4, s30, v[0:1]
	v_mad_i64_i32 v[8:9], s[16:17], v4, s11, v[6:7]
	ds_read_b128 v[2:5], v2
	s_waitcnt lgkmcnt(0)
	global_store_dwordx4 v[8:9], v[2:5], off
	s_nop 1
	v_add_u32_e32 v2, 0x700, v71
	v_ashrrev_i32_e32 v4, 4, v2
	v_mad_u64_u32 v[2:3], s[16:17], v4, s30, v[0:1]
	v_mad_i64_i32 v[6:7], s[16:17], v4, s11, v[6:7]
	ds_read_b128 v[2:5], v2
	s_mov_b64 s[16:17], 0
	s_waitcnt lgkmcnt(0)
	global_store_dwordx4 v[6:7], v[2:5], off
	s_barrier

.LBB0_362:
	v_lshl_add_u32 v143, s11, 14, v141
	v_add_u32_e32 v146, 0x1000, v143
	v_readfirstlane_b32 s18, v143
	s_waitcnt vmcnt(4) lgkmcnt(0)
	s_barrier
	v_add_u32_e32 v145, 0x2000, v143
	s_mov_b32 m0, s18
	v_readfirstlane_b32 s18, v146
	v_add_u32_e32 v144, 0x3000, v143
	global_load_lds_dwordx4 v[84:85], off
	s_mov_b32 m0, s18
	v_readfirstlane_b32 s18, v145
	global_load_lds_dwordx4 v[86:87], off
	s_mov_b32 m0, s18
	v_readfirstlane_b32 s18, v144
	global_load_lds_dwordx4 v[74:75], off
	s_mov_b32 m0, s18
	s_lshl_b32 s18, s16, 14
	global_load_lds_dwordx4 v[72:73], off
	s_add_i32 s18, s18, 0
	v_add3_u32 v143, s18, v142, v0
	v_lshl_add_u64 v[80:81], v[72:73], 0, 64
	v_lshl_add_u64 v[82:83], v[74:75], 0, 64
	v_lshl_add_u64 v[78:79], v[84:85], 0, 64
	v_lshl_add_u64 v[76:77], v[86:87], 0, 64
	ds_read_b128 v[72:75], v143 offset:8192
	ds_read_b128 v[84:87], v143 offset:9216
	ds_read_b128 v[144:147], v143 offset:10240
	ds_read_b128 v[148:151], v143 offset:11264
	v_add3_u32 v143, s18, v71, v0
	ds_read_b128 v[152:155], v143
	ds_read_b128 v[156:159], v143 offset:1024
	ds_read_b128 v[160:163], v143 offset:2048
	ds_read_b128 v[164:167], v143 offset:3072
	s_add_i32 s18, s16, 1
	s_cmp_lg_u32 s16, 2
	s_waitcnt lgkmcnt(0)
	s_setprio 1
	v_mfma_f32_16x16x32_bf16 v[62:65], v[72:75], v[152:155], v[62:65]
	s_cselect_b32 s16, s18, 0
	s_add_i32 s18, s11, 1
	s_cmp_lg_u32 s11, 2
	v_mfma_f32_16x16x32_bf16 v[58:61], v[84:87], v[152:155], v[58:61]
	s_cselect_b32 s11, s18, 0
	s_add_i32 s17, s17, -1
	s_cmp_eq_u32 s17, 0
	v_mfma_f32_16x16x32_bf16 v[54:57], v[144:147], v[152:155], v[54:57]
	v_mfma_f32_16x16x32_bf16 v[50:53], v[148:151], v[152:155], v[50:53]
	v_mfma_f32_16x16x32_bf16 v[46:49], v[72:75], v[156:159], v[46:49]
	v_mfma_f32_16x16x32_bf16 v[42:45], v[84:87], v[156:159], v[42:45]
	v_mfma_f32_16x16x32_bf16 v[38:41], v[144:147], v[156:159], v[38:41]
	v_mfma_f32_16x16x32_bf16 v[34:37], v[148:151], v[156:159], v[34:37]
	v_mfma_f32_16x16x32_bf16 v[30:33], v[72:75], v[160:163], v[30:33]
	v_mfma_f32_16x16x32_bf16 v[26:29], v[84:87], v[160:163], v[26:29]
	v_mfma_f32_16x16x32_bf16 v[22:25], v[144:147], v[160:163], v[22:25]
	v_mfma_f32_16x16x32_bf16 v[18:21], v[148:151], v[160:163], v[18:21]
	v_mfma_f32_16x16x32_bf16 v[14:17], v[72:75], v[164:167], v[14:17]
	v_mov_b64_e32 v[74:75], v[82:83]
	v_mov_b64_e32 v[72:73], v[80:81]
	v_mfma_f32_16x16x32_bf16 v[10:13], v[84:87], v[164:167], v[10:13]
	v_mov_b64_e32 v[84:85], v[78:79]
	v_mov_b64_e32 v[86:87], v[76:77]
	v_mfma_f32_16x16x32_bf16 v[6:9], v[144:147], v[164:167], v[6:9]
	v_mfma_f32_16x16x32_bf16 v[2:5], v[148:151], v[164:167], v[2:5]
	s_setprio 0
	s_cbranch_scc0 .LBB0_362
	s_lshl_b32 s11, s16, 14
	s_add_i32 s17, s11, 0
	s_waitcnt vmcnt(4) lgkmcnt(0)
	s_barrier
	v_add3_u32 v141, s17, v142, v0
	v_add3_u32 v143, s17, v71, v0
	ds_read_b128 v[72:75], v141 offset:8192
	ds_read_b128 v[76:79], v141 offset:9216
	ds_read_b128 v[80:83], v143
	ds_read_b128 v[84:87], v143 offset:1024
	ds_read_b128 v[144:147], v141 offset:10240
	ds_read_b128 v[148:151], v141 offset:11264
	s_waitcnt lgkmcnt(0)
	v_mfma_f32_16x16x32_bf16 v[62:65], v[72:75], v[80:83], v[62:65]
	s_addk_i32 s11, 0x4000
	s_cmp_lg_u32 s16, 2
	s_cselect_b32 s11, s11, 0
	v_mfma_f32_16x16x32_bf16 v[58:61], v[76:79], v[80:83], v[58:61]
	s_add_i32 s11, s11, 0
	v_add3_u32 v141, s11, v142, v0
	v_add3_u32 v0, s11, v71, v0
	v_mfma_f32_16x16x32_bf16 v[54:57], v[144:147], v[80:83], v[54:57]
	s_lshl_b32 s11, s37, 3
	s_lshl_b32 s16, s36, 1
	s_add_i32 s11, s11, s16
	v_mfma_f32_16x16x32_bf16 v[50:53], v[148:151], v[80:83], v[50:53]
	s_mul_hi_i32 s16, s11, 0x2100
	s_mulk_i32 s11, 0x2100
	s_add_u32 s2, s11, s2
	v_mfma_f32_16x16x32_bf16 v[46:49], v[72:75], v[84:87], v[46:49]
	s_addc_u32 s11, s16, 0
	s_mulk_i32 s11, 0xc0
	s_mul_hi_u32 s16, s2, 0xc0
	v_mfma_f32_16x16x32_bf16 v[42:45], v[76:79], v[84:87], v[42:45]
	s_add_i32 s11, s16, s11
	s_mulk_i32 s2, 0xc0
	v_mov_b32_e32 v71, v196
	v_mfma_f32_16x16x32_bf16 v[38:41], v[144:147], v[84:87], v[38:41]
	s_add_u32 s16, s6, s2
	s_mov_b32 s2, 0xfffffc0
	s_addc_u32 s17, s7, s11
	v_mfma_f32_16x16x32_bf16 v[34:37], v[148:151], v[84:87], v[34:37]
	ds_read_b128 v[80:83], v143 offset:2048
	ds_read_b128 v[84:87], v143 offset:3072
	s_waitcnt vmcnt(0) lgkmcnt(0)
	s_barrier
	s_waitcnt lgkmcnt(0)
	v_mfma_f32_16x16x32_bf16 v[30:33], v[72:75], v[80:83], v[30:33]
	v_mfma_f32_16x16x32_bf16 v[26:29], v[76:79], v[80:83], v[26:29]
	v_mfma_f32_16x16x32_bf16 v[22:25], v[144:147], v[80:83], v[22:25]
	v_mfma_f32_16x16x32_bf16 v[18:21], v[148:151], v[80:83], v[18:21]
	v_mfma_f32_16x16x32_bf16 v[14:17], v[72:75], v[84:87], v[14:17]
	v_mfma_f32_16x16x32_bf16 v[10:13], v[76:79], v[84:87], v[10:13]
	ds_read_b128 v[72:75], v141 offset:8192
	ds_read_b128 v[76:79], v141 offset:9216
	v_mfma_f32_16x16x32_bf16 v[6:9], v[144:147], v[84:87], v[6:9]
	v_mfma_f32_16x16x32_bf16 v[2:5], v[148:151], v[84:87], v[2:5]
	ds_read_b128 v[80:83], v0
	ds_read_b128 v[84:87], v0 offset:1024
	ds_read_b128 v[142:145], v141 offset:10240
	ds_read_b128 v[146:149], v141 offset:11264
	ds_read_b128 v[150:153], v0 offset:2048
	ds_read_b128 v[154:157], v0 offset:3072
	s_waitcnt lgkmcnt(0)
	v_mfma_f32_16x16x32_bf16 v[62:65], v[72:75], v[80:83], v[62:65]
	s_waitcnt vmcnt(0)
	s_barrier
	v_mfma_f32_16x16x32_bf16 v[58:61], v[76:79], v[80:83], v[58:61]
	v_mfma_f32_16x16x32_bf16 v[54:57], v[142:145], v[80:83], v[54:57]
	v_mfma_f32_16x16x32_bf16 v[50:53], v[146:149], v[80:83], v[50:53]
	ds_read2_b32 v[80:81], v140 offset1:16
	s_waitcnt lgkmcnt(0)
	s_nop 0
	v_pk_mul_f32 v[64:65], v[64:65], v[80:81] op_sel_hi:[1,0]
	v_pk_mul_f32 v[62:63], v[62:63], v[80:81] op_sel_hi:[1,0]
	s_nop 0
	v_pk_mul_f32 v[60:61], v[60:61], v[80:81] op_sel_hi:[1,0]
	v_pk_mul_f32 v[58:59], v[58:59], v[80:81] op_sel_hi:[1,0]
	v_pk_mul_f32 v[56:57], v[56:57], v[80:81] op_sel_hi:[1,0]
	v_pk_mul_f32 v[54:55], v[54:55], v[80:81] op_sel_hi:[1,0]
	v_pk_mul_f32 v[52:53], v[52:53], v[80:81] op_sel_hi:[1,0]
	v_pk_mul_f32 v[50:51], v[50:51], v[80:81] op_sel_hi:[1,0]
	v_mov_b32_e32 v0, v81
	ds_read2_b32 v[80:81], v140 offset0:32 offset1:48
	v_mfma_f32_16x16x32_bf16 v[46:49], v[72:75], v[84:87], v[46:49]
	v_cvt_pk_bf16_f32 v62, v62, v63
	v_cvt_pk_bf16_f32 v63, v64, v65
	v_mfma_f32_16x16x32_bf16 v[42:45], v[76:79], v[84:87], v[42:45]
	v_cvt_pk_bf16_f32 v58, v58, v59
	s_nop 3
	v_pk_mul_f32 v[48:49], v[48:49], v[0:1] op_sel_hi:[1,0]
	v_pk_mul_f32 v[46:47], v[46:47], v[0:1] op_sel_hi:[1,0]
	v_mfma_f32_16x16x32_bf16 v[38:41], v[142:145], v[84:87], v[38:41]
	v_cvt_pk_bf16_f32 v59, v60, v61
	v_pk_mul_f32 v[44:45], v[44:45], v[0:1] op_sel_hi:[1,0]
	v_pk_mul_f32 v[42:43], v[42:43], v[0:1] op_sel_hi:[1,0]
	v_mfma_f32_16x16x32_bf16 v[34:37], v[146:149], v[84:87], v[34:37]
	v_cvt_pk_bf16_f32 v54, v54, v55
	s_nop 2
	v_pk_mul_f32 v[40:41], v[40:41], v[0:1] op_sel_hi:[1,0]
	v_pk_mul_f32 v[38:39], v[38:39], v[0:1] op_sel_hi:[1,0]
	v_mfma_f32_16x16x32_bf16 v[14:17], v[72:75], v[154:157], v[14:17]
	v_cvt_pk_bf16_f32 v55, v56, v57
	v_pk_mul_f32 v[36:37], v[36:37], v[0:1] op_sel_hi:[1,0]
	v_pk_mul_f32 v[34:35], v[34:35], v[0:1] op_sel_hi:[1,0]
	v_mfma_f32_16x16x32_bf16 v[10:13], v[76:79], v[154:157], v[10:13]
	s_waitcnt lgkmcnt(0)
	v_mov_b32_e32 v0, v81
	s_nop 1
	v_pk_mul_f32 v[16:17], v[16:17], v[0:1] op_sel_hi:[1,0]
	v_pk_mul_f32 v[14:15], v[14:15], v[0:1] op_sel_hi:[1,0]
	v_mfma_f32_16x16x32_bf16 v[6:9], v[142:145], v[154:157], v[6:9]
	v_cvt_pk_bf16_f32 v50, v50, v51
	v_pk_mul_f32 v[12:13], v[12:13], v[0:1] op_sel_hi:[1,0]
	v_pk_mul_f32 v[10:11], v[10:11], v[0:1] op_sel_hi:[1,0]
	v_mfma_f32_16x16x32_bf16 v[2:5], v[146:149], v[154:157], v[2:5]
	v_cvt_pk_bf16_f32 v51, v52, v53
	s_nop 2
	v_pk_mul_f32 v[8:9], v[8:9], v[0:1] op_sel_hi:[1,0]
	v_pk_mul_f32 v[6:7], v[6:7], v[0:1] op_sel_hi:[1,0]
	v_mfma_f32_16x16x32_bf16 v[26:29], v[76:79], v[150:153], v[26:29]
	v_cvt_pk_bf16_f32 v42, v42, v43
	v_pk_mul_f32 v[4:5], v[4:5], v[0:1] op_sel_hi:[1,0]
	v_pk_mul_f32 v[2:3], v[2:3], v[0:1] op_sel_hi:[1,0]
	v_mfma_f32_16x16x32_bf16 v[30:33], v[72:75], v[150:153], v[30:33]
	v_and_b32_e32 v72, 15, v71
	v_lshrrev_b32_e32 v73, 1, v71
	v_and_b32_e32 v0, 64, v71
	v_and_or_b32 v74, v73, s2, v72
	v_lshl_add_u32 v0, v0, 1, 0
	v_and_b32_e32 v73, 24, v73
	v_mul_lo_u32 v74, v74, s30
	v_pk_mul_f32 v[28:29], v[28:29], v[80:81] op_sel_hi:[1,0]
	v_pk_mul_f32 v[26:27], v[26:27], v[80:81] op_sel_hi:[1,0]
	v_add3_u32 v0, v0, v73, v74
	ds_write2_b64 v0, v[62:63], v[58:59] offset1:4
	ds_write2_b64 v0, v[54:55], v[50:51] offset0:8 offset1:12
	v_cvt_pk_bf16_f32 v43, v44, v45
	v_add_u32_e32 v44, 0x1000, v0
	v_cvt_pk_bf16_f32 v26, v26, v27
	v_cvt_pk_bf16_f32 v27, v28, v29
	v_add_u32_e32 v28, 0x2000, v0
	v_cvt_pk_bf16_f32 v14, v14, v15
	v_cvt_pk_bf16_f32 v15, v16, v17
	v_cvt_pk_bf16_f32 v10, v10, v11
	v_cvt_pk_bf16_f32 v11, v12, v13
	v_add_u32_e32 v0, 0x3000, v0
	v_cvt_pk_bf16_f32 v6, v6, v7
	v_cvt_pk_bf16_f32 v7, v8, v9
	v_cvt_pk_bf16_f32 v2, v2, v3
	v_cvt_pk_bf16_f32 v3, v4, v5
	v_mfma_f32_16x16x32_bf16 v[22:25], v[142:145], v[150:153], v[22:25]
	ds_write2_b64 v0, v[14:15], v[10:11] offset0:96 offset1:100
	ds_write2_b64 v0, v[6:7], v[2:3] offset0:104 offset1:108
	v_lshlrev_b32_e32 v0, 4, v71
	v_mfma_f32_16x16x32_bf16 v[18:21], v[146:149], v[150:153], v[18:21]
	v_and_b32_e32 v0, 0x70, v0
	v_lshl_add_u64 v[10:11], s[16:17], 0, v[0:1]
	v_bfe_u32 v0, v71, 3, 1
	v_ashrrev_i32_e32 v2, 4, v71
	v_mul_u32_u24_e32 v0, 0x2100, v0
	v_lshl_add_u32 v12, v72, 4, 0
	v_ashrrev_i32_e32 v3, 31, v2
	v_pk_mul_f32 v[32:33], v[32:33], v[80:81] op_sel_hi:[1,0]
	v_pk_mul_f32 v[30:31], v[30:31], v[80:81] op_sel_hi:[1,0]
	v_pk_mul_f32 v[24:25], v[24:25], v[80:81] op_sel_hi:[1,0]
	v_pk_mul_f32 v[22:23], v[22:23], v[80:81] op_sel_hi:[1,0]
	v_pk_mul_f32 v[20:21], v[20:21], v[80:81] op_sel_hi:[1,0]
	v_pk_mul_f32 v[18:19], v[18:19], v[80:81] op_sel_hi:[1,0]
	v_mad_u64_u32 v[4:5], s[16:17], v2, s30, v[12:13]
	v_lshl_add_u64 v[2:3], v[0:1], 0, v[2:3]
	v_cvt_pk_bf16_f32 v46, v46, v47
	v_cvt_pk_bf16_f32 v47, v48, v49
	v_cvt_pk_bf16_f32 v38, v38, v39
	v_cvt_pk_bf16_f32 v39, v40, v41
	v_cvt_pk_bf16_f32 v34, v34, v35
	v_cvt_pk_bf16_f32 v35, v36, v37
	v_cvt_pk_bf16_f32 v30, v30, v31
	v_cvt_pk_bf16_f32 v31, v32, v33
	v_cvt_pk_bf16_f32 v22, v22, v23
	v_cvt_pk_bf16_f32 v23, v24, v25
	v_cvt_pk_bf16_f32 v18, v18, v19
	v_cvt_pk_bf16_f32 v19, v20, v21
	v_mad_u64_u32 v[14:15], s[16:17], v2, s31, v[10:11]
	ds_write2_b64 v44, v[46:47], v[42:43] offset0:32 offset1:36
	ds_write2_b64 v44, v[38:39], v[34:35] offset0:40 offset1:44
	ds_write2_b64 v28, v[30:31], v[26:27] offset0:64 offset1:68
	ds_write2_b64 v28, v[22:23], v[18:19] offset0:72 offset1:76
	s_waitcnt lgkmcnt(0)
	s_barrier
	v_mad_i32_i24 v15, v3, s31, v15
	ds_read_b128 v[2:5], v4
	v_add_u32_e32 v6, 0x100, v71
	v_ashrrev_i32_e32 v16, 4, v6
	v_mad_u64_u32 v[6:7], s[16:17], v16, s30, v[12:13]
	ds_read_b128 v[6:9], v6
	v_ashrrev_i32_e32 v17, 31, v16
	s_waitcnt lgkmcnt(1)
	global_store_dwordx4 v[14:15], v[2:5], off
	s_nop 1
	v_lshl_add_u64 v[2:3], v[0:1], 0, v[16:17]
	v_mad_u64_u32 v[4:5], s[16:17], v2, s31, v[10:11]
	v_add_u32_e32 v2, 0x200, v71
	v_ashrrev_i32_e32 v2, 4, v2
	v_mad_i32_i24 v5, v3, s31, v5
	v_ashrrev_i32_e32 v3, 31, v2
	s_waitcnt lgkmcnt(0)
	global_store_dwordx4 v[4:5], v[6:9], off
	v_mad_u64_u32 v[4:5], s[16:17], v2, s30, v[12:13]
	v_lshl_add_u64 v[2:3], v[0:1], 0, v[2:3]
	v_mad_u64_u32 v[14:15], s[16:17], v2, s31, v[10:11]
	v_mad_i32_i24 v15, v3, s31, v15
	ds_read_b128 v[2:5], v4
	v_add_u32_e32 v6, 0x300, v71
	v_ashrrev_i32_e32 v16, 4, v6
	v_mad_u64_u32 v[6:7], s[16:17], v16, s30, v[12:13]
	ds_read_b128 v[6:9], v6
	v_ashrrev_i32_e32 v17, 31, v16
	s_waitcnt lgkmcnt(1)
	global_store_dwordx4 v[14:15], v[2:5], off
	s_nop 1
	v_lshl_add_u64 v[2:3], v[0:1], 0, v[16:17]
	v_mad_u64_u32 v[4:5], s[16:17], v2, s31, v[10:11]
	v_add_u32_e32 v2, 0x400, v71
	v_ashrrev_i32_e32 v2, 4, v2
	v_mad_i32_i24 v5, v3, s31, v5
	v_ashrrev_i32_e32 v3, 31, v2
	s_waitcnt lgkmcnt(0)
	global_store_dwordx4 v[4:5], v[6:9], off
	v_mad_u64_u32 v[4:5], s[16:17], v2, s30, v[12:13]
	v_lshl_add_u64 v[2:3], v[0:1], 0, v[2:3]
	v_mad_u64_u32 v[14:15], s[16:17], v2, s31, v[10:11]
	v_mad_i32_i24 v15, v3, s31, v15
	ds_read_b128 v[2:5], v4
	v_add_u32_e32 v6, 0x500, v71
	v_ashrrev_i32_e32 v16, 4, v6
	v_mad_u64_u32 v[6:7], s[16:17], v16, s30, v[12:13]
	ds_read_b128 v[6:9], v6
	v_ashrrev_i32_e32 v17, 31, v16
	s_waitcnt lgkmcnt(1)
	global_store_dwordx4 v[14:15], v[2:5], off
	s_nop 1
	v_lshl_add_u64 v[2:3], v[0:1], 0, v[16:17]
	v_mad_u64_u32 v[4:5], s[16:17], v2, s31, v[10:11]
	v_add_u32_e32 v2, 0x600, v71
	v_ashrrev_i32_e32 v2, 4, v2
	v_mad_i32_i24 v5, v3, s31, v5
	v_ashrrev_i32_e32 v3, 31, v2
	s_waitcnt lgkmcnt(0)
	global_store_dwordx4 v[4:5], v[6:9], off
	v_mad_u64_u32 v[4:5], s[16:17], v2, s30, v[12:13]
	v_lshl_add_u64 v[2:3], v[0:1], 0, v[2:3]
	v_mad_u64_u32 v[14:15], s[16:17], v2, s31, v[10:11]
	v_mad_i32_i24 v15, v3, s31, v15
	ds_read_b128 v[2:5], v4
	v_add_u32_e32 v6, 0x700, v71
	v_ashrrev_i32_e32 v16, 4, v6
	v_mad_u64_u32 v[6:7], s[16:17], v16, s30, v[12:13]
	ds_read_b128 v[6:9], v6
	v_ashrrev_i32_e32 v17, 31, v16
	s_waitcnt lgkmcnt(1)
	global_store_dwordx4 v[14:15], v[2:5], off
	s_nop 1
	v_lshl_add_u64 v[2:3], v[0:1], 0, v[16:17]
	v_mad_u64_u32 v[4:5], s[16:17], v2, s31, v[10:11]
	v_mad_i32_i24 v5, v3, s31, v5
	s_waitcnt lgkmcnt(0)
	global_store_dwordx4 v[4:5], v[6:9], off
	s_barrier

.LBB0_367:
	v_lshl_add_u32 v143, s2, 14, v141
	v_add_u32_e32 v146, 0x1000, v143
	v_readfirstlane_b32 s14, v143
	s_waitcnt vmcnt(4) lgkmcnt(0)
	s_barrier
	v_add_u32_e32 v145, 0x2000, v143
	s_mov_b32 m0, s14
	v_readfirstlane_b32 s14, v146
	v_add_u32_e32 v144, 0x3000, v143
	global_load_lds_dwordx4 v[84:85], off
	s_mov_b32 m0, s14
	v_readfirstlane_b32 s14, v145
	global_load_lds_dwordx4 v[86:87], off
	s_mov_b32 m0, s14
	v_readfirstlane_b32 s14, v144
	global_load_lds_dwordx4 v[74:75], off
	s_mov_b32 m0, s14
	s_lshl_b32 s14, s0, 14
	global_load_lds_dwordx4 v[72:73], off
	s_add_i32 s14, s14, 0
	v_add3_u32 v143, s14, v142, v0
	v_lshl_add_u64 v[80:81], v[72:73], 0, 64
	v_lshl_add_u64 v[82:83], v[74:75], 0, 64
	v_lshl_add_u64 v[78:79], v[84:85], 0, 64
	v_lshl_add_u64 v[76:77], v[86:87], 0, 64
	ds_read_b128 v[72:75], v143 offset:8192
	ds_read_b128 v[84:87], v143 offset:9216
	ds_read_b128 v[144:147], v143 offset:10240
	ds_read_b128 v[148:151], v143 offset:11264
	v_add3_u32 v143, s14, v71, v0
	ds_read_b128 v[152:155], v143
	ds_read_b128 v[156:159], v143 offset:1024
	ds_read_b128 v[160:163], v143 offset:2048
	ds_read_b128 v[164:167], v143 offset:3072
	s_add_i32 s14, s0, 1
	s_cmp_lg_u32 s0, 2
	s_waitcnt lgkmcnt(0)
	s_setprio 1
	v_mfma_f32_16x16x32_bf16 v[62:65], v[72:75], v[152:155], v[62:65]
	s_cselect_b32 s0, s14, 0
	s_add_i32 s14, s2, 1
	s_cmp_lg_u32 s2, 2
	v_mfma_f32_16x16x32_bf16 v[58:61], v[84:87], v[152:155], v[58:61]
	s_cselect_b32 s2, s14, 0
	s_add_i32 s1, s1, -1
	s_cmp_eq_u32 s1, 0
	v_mfma_f32_16x16x32_bf16 v[54:57], v[144:147], v[152:155], v[54:57]
	v_mfma_f32_16x16x32_bf16 v[50:53], v[148:151], v[152:155], v[50:53]
	v_mfma_f32_16x16x32_bf16 v[46:49], v[72:75], v[156:159], v[46:49]
	v_mfma_f32_16x16x32_bf16 v[42:45], v[84:87], v[156:159], v[42:45]
	v_mfma_f32_16x16x32_bf16 v[38:41], v[144:147], v[156:159], v[38:41]
	v_mfma_f32_16x16x32_bf16 v[34:37], v[148:151], v[156:159], v[34:37]
	v_mfma_f32_16x16x32_bf16 v[30:33], v[72:75], v[160:163], v[30:33]
	v_mfma_f32_16x16x32_bf16 v[26:29], v[84:87], v[160:163], v[26:29]
	v_mfma_f32_16x16x32_bf16 v[22:25], v[144:147], v[160:163], v[22:25]
	v_mfma_f32_16x16x32_bf16 v[18:21], v[148:151], v[160:163], v[18:21]
	v_mfma_f32_16x16x32_bf16 v[14:17], v[72:75], v[164:167], v[14:17]
	v_mov_b64_e32 v[74:75], v[82:83]
	v_mov_b64_e32 v[72:73], v[80:81]
	v_mfma_f32_16x16x32_bf16 v[10:13], v[84:87], v[164:167], v[10:13]
	v_mov_b64_e32 v[84:85], v[78:79]
	v_mov_b64_e32 v[86:87], v[76:77]
	v_mfma_f32_16x16x32_bf16 v[6:9], v[144:147], v[164:167], v[6:9]
	v_mfma_f32_16x16x32_bf16 v[2:5], v[148:151], v[164:167], v[2:5]
	s_setprio 0
	s_cbranch_scc0 .LBB0_367
	s_lshl_b32 s1, s0, 14
	s_add_i32 s2, s1, 0
	s_waitcnt vmcnt(4) lgkmcnt(0)
	s_barrier
	v_add3_u32 v141, s2, v142, v0
	v_add3_u32 v143, s2, v71, v0
	ds_read_b128 v[72:75], v141 offset:8192
	ds_read_b128 v[76:79], v141 offset:9216
	ds_read_b128 v[80:83], v143
	ds_read_b128 v[84:87], v143 offset:1024
	ds_read_b128 v[144:147], v141 offset:10240
	ds_read_b128 v[148:151], v141 offset:11264
	s_waitcnt lgkmcnt(0)
	v_mfma_f32_16x16x32_bf16 v[62:65], v[72:75], v[80:83], v[62:65]
	s_addk_i32 s1, 0x4000
	s_cmp_lg_u32 s0, 2
	s_cselect_b32 s0, s1, 0
	v_mfma_f32_16x16x32_bf16 v[58:61], v[76:79], v[80:83], v[58:61]
	s_add_i32 s0, s0, 0
	v_cmp_lt_i32_e32 vcc, v201, v200
	s_xor_b64 s[16:17], s[12:13], -1
	v_mfma_f32_16x16x32_bf16 v[54:57], v[144:147], v[80:83], v[54:57]
	v_mfma_f32_16x16x32_bf16 v[50:53], v[148:151], v[80:83], v[50:53]
	v_mfma_f32_16x16x32_bf16 v[46:49], v[72:75], v[84:87], v[46:49]
	v_mfma_f32_16x16x32_bf16 v[42:45], v[76:79], v[84:87], v[42:45]
	v_mfma_f32_16x16x32_bf16 v[38:41], v[144:147], v[84:87], v[38:41]
	v_mfma_f32_16x16x32_bf16 v[34:37], v[148:151], v[84:87], v[34:37]
	ds_read_b128 v[80:83], v143 offset:2048
	ds_read_b128 v[84:87], v143 offset:3072
	s_waitcnt vmcnt(0) lgkmcnt(0)
	s_barrier
	s_waitcnt lgkmcnt(0)
	v_mfma_f32_16x16x32_bf16 v[26:29], v[76:79], v[80:83], v[26:29]
	v_mfma_f32_16x16x32_bf16 v[10:13], v[76:79], v[84:87], v[10:13]
	v_add3_u32 v76, s0, v142, v0
	v_add3_u32 v0, s0, v71, v0
	s_mov_b32 s0, 0x2aaaaaab
	v_mfma_f32_16x16x32_bf16 v[30:33], v[72:75], v[80:83], v[30:33]
	v_cndmask_b32_e32 v71, v199, v201, vcc
	v_lshlrev_b32_e32 v71, 2, v71
	v_mfma_f32_16x16x32_bf16 v[22:25], v[144:147], v[80:83], v[22:25]
	v_mfma_f32_16x16x32_bf16 v[18:21], v[148:151], v[80:83], v[18:21]
	ds_read_b128 v[78:81], v76 offset:8192
	v_mfma_f32_16x16x32_bf16 v[14:17], v[72:75], v[84:87], v[14:17]
	v_mfma_f32_16x16x32_bf16 v[6:9], v[144:147], v[84:87], v[6:9]
	v_mfma_f32_16x16x32_bf16 v[2:5], v[148:151], v[84:87], v[2:5]
	ds_read_b128 v[84:87], v76 offset:9216
	ds_read_b128 v[72:75], v0
	ds_read_b128 v[142:145], v0 offset:1024
	ds_read_b128 v[146:149], v76 offset:10240
	ds_read_b128 v[150:153], v76 offset:11264
	s_waitcnt lgkmcnt(0)
	v_mfma_f32_16x16x32_bf16 v[46:49], v[78:81], v[142:145], v[46:49]
	ds_read_b128 v[154:157], v0 offset:2048
	v_mfma_f32_16x16x32_bf16 v[42:45], v[84:87], v[142:145], v[42:45]
	v_mfma_f32_16x16x32_bf16 v[38:41], v[146:149], v[142:145], v[38:41]
	v_mfma_f32_16x16x32_bf16 v[34:37], v[150:153], v[142:145], v[34:37]
	ds_read_b128 v[142:145], v0 offset:3072
	s_waitcnt vmcnt(0) lgkmcnt(0)
	s_barrier
	ds_read_b32 v0, v96
	v_mfma_f32_16x16x32_bf16 v[62:65], v[78:81], v[72:75], v[62:65]
	s_waitcnt lgkmcnt(0)
	v_mul_f32_e32 v82, 0x3e16c740, v0
	v_mfma_f32_16x16x32_bf16 v[58:61], v[84:87], v[72:75], v[58:61]
	v_mfma_f32_16x16x32_bf16 v[54:57], v[146:149], v[72:75], v[54:57]
	v_mfma_f32_16x16x32_bf16 v[50:53], v[150:153], v[72:75], v[50:53]
	v_or_b32_e32 v72, s10, v89
	v_add_u32_e32 v73, s26, v95
	v_mul_hi_i32 v0, v72, s0
	v_ashrrev_i32_e32 v77, 6, v73
	v_lshrrev_b32_e32 v73, 31, v0
	v_lshrrev_b32_e32 v0, 4, v0
	v_add_u32_e32 v0, v0, v73
	s_movk_i32 s0, 0x60
	v_mul_lo_u32 v0, v0, s0
	v_sub_u32_e32 v0, v72, v0
	v_cmp_lt_i32_e32 vcc, 63, v0
	s_and_b64 s[14:15], s[16:17], vcc
	v_cmp_eq_u32_e32 vcc, 64, v0
	v_mfma_f32_16x16x32_bf16 v[30:33], v[78:81], v[154:157], v[30:33]
	s_nop 0
	v_cndmask_b32_e32 v0, v90, v77, vcc
	v_cvt_f32_i32_e32 v73, v0
	v_mul_f32_e32 v0, v62, v82
	ds_bpermute_b32 v62, v71, v0
	v_mfma_f32_16x16x32_bf16 v[26:29], v[84:87], v[154:157], v[26:29]
	v_mfma_f32_16x16x32_bf16 v[22:25], v[146:149], v[154:157], v[22:25]
	v_mfma_f32_16x16x32_bf16 v[18:21], v[150:153], v[154:157], v[18:21]
	v_mfma_f32_16x16x32_bf16 v[14:17], v[78:81], v[142:145], v[14:17]
	v_mfma_f32_16x16x32_bf16 v[10:13], v[84:87], v[142:145], v[10:13]
	v_mfma_f32_16x16x32_bf16 v[6:9], v[146:149], v[142:145], v[6:9]
	v_mfma_f32_16x16x32_bf16 v[2:5], v[150:153], v[142:145], v[2:5]
	s_and_saveexec_b64 s[0:1], s[14:15]
	s_cbranch_execz .LBB0_370
	v_mul_f32_e32 v74, v97, v73
	v_mul_f32_e32 v74, 0.15915494, v74
	v_sin_f32_e32 v75, v74
	v_cos_f32_e32 v74, v74
	s_waitcnt lgkmcnt(0)
	v_mul_f32_e32 v62, v75, v62
	v_cndmask_b32_e64 v62, v62, -v62, s[44:45]
	v_fmac_f32_e32 v62, v74, v0
	v_mov_b32_e32 v0, v62

.LBB0_450:
	s_nop 0
	v_lshl_add_u32 v30, s21, 14, v122
	v_add_u32_e32 v33, 0x1000, v30
	v_readfirstlane_b32 s22, v30
	s_waitcnt vmcnt(4) lgkmcnt(0)
	s_barrier
	v_add_u32_e32 v31, 0x2000, v30
	s_mov_b32 m0, s22
	v_readfirstlane_b32 s22, v33
	v_add_u32_e32 v32, 0x3000, v30
	global_load_lds_dwordx4 v[116:117], off
	s_mov_b32 m0, s22
	v_readfirstlane_b32 s22, v31
	v_lshl_add_u64 v[120:121], v[118:119], 0, s[18:19]
	global_load_lds_dwordx4 v[114:115], off
	s_mov_b32 m0, s22
	v_readfirstlane_b32 s22, v32
	global_load_lds_dwordx4 v[120:121], off
	s_mov_b32 m0, s22
	s_lshl_b32 s22, s2, 14
	v_lshl_add_u64 v[30:31], v[120:121], 0, s[26:27]
	s_add_i32 s22, s22, 0
	global_load_lds_dwordx4 v[30:31], off
	v_add3_u32 v30, s22, v124, v0
	ds_read_b128 v[98:101], v30 offset:8192
	ds_read_b128 v[102:105], v30 offset:9216
	ds_read_b128 v[106:109], v30 offset:10240
	ds_read_b128 v[110:113], v30 offset:11264
	v_add3_u32 v30, s22, v123, v0
	ds_read_b128 v[78:81], v30
	ds_read_b128 v[82:85], v30 offset:1024
	ds_read_b128 v[94:97], v30 offset:2048
	ds_read_b128 v[126:129], v30 offset:3072
	s_add_i32 s22, s2, 1
	s_cmp_lg_u32 s2, 2
	s_cselect_b32 s2, s22, 0
	s_add_i32 s22, s21, 1
	s_cmp_lg_u32 s21, 2
	s_cselect_b32 s21, s22, 0
	s_waitcnt lgkmcnt(0)
	s_setprio 1
	v_mfma_f32_16x16x32_bf16 v[30:33], v[78:81], v[98:101], v[74:77]
	v_lshl_add_u64 v[130:131], v[116:117], 0, 64
	s_setprio 0
	s_waitcnt vmcnt(4) lgkmcnt(0)
	s_barrier
	s_setprio 1
	v_mfma_f32_16x16x32_bf16 v[34:37], v[78:81], v[102:105], v[70:73]
	s_setprio 0
	v_lshl_add_u64 v[132:133], v[114:115], 0, 64
	v_lshl_add_u64 v[142:143], v[116:117], 0, s[78:79]
	s_setprio 1
	v_mfma_f32_16x16x32_bf16 v[38:41], v[78:81], v[106:109], v[66:69]
	v_lshl_add_u64 v[144:145], v[114:115], 0, s[78:79]
	v_lshl_add_u64 v[116:117], v[116:117], 0, s[84:85]
	v_lshl_add_u64 v[114:115], v[114:115], 0, s[84:85]
	v_mfma_f32_16x16x32_bf16 v[66:69], v[78:81], v[110:113], v[62:65]
	v_mfma_f32_16x16x32_bf16 v[70:73], v[82:85], v[98:101], v[58:61]
	v_mfma_f32_16x16x32_bf16 v[74:77], v[82:85], v[102:105], v[54:57]
	v_mfma_f32_16x16x32_bf16 v[78:81], v[82:85], v[106:109], v[50:53]
	v_mfma_f32_16x16x32_bf16 v[46:49], v[82:85], v[110:113], v[46:49]
	v_mfma_f32_16x16x32_bf16 v[82:85], v[94:97], v[98:101], v[42:45]
	v_mfma_f32_16x16x32_bf16 v[86:89], v[94:97], v[102:105], v[26:29]
	v_mfma_f32_16x16x32_bf16 v[90:93], v[94:97], v[106:109], v[22:25]
	v_mfma_f32_16x16x32_bf16 v[94:97], v[94:97], v[110:113], v[18:21]
	v_mfma_f32_16x16x32_bf16 v[110:113], v[126:129], v[110:113], v[2:5]
	s_nop 2
	v_lshl_add_u32 v2, s21, 14, v122
	v_add_u32_e32 v3, 0x1000, v2
	v_readfirstlane_b32 s22, v2
	v_add_u32_e32 v5, 0x2000, v2
	s_mov_b32 m0, s22
	v_readfirstlane_b32 s22, v3
	v_add_u32_e32 v4, 0x3000, v2
	global_load_lds_dwordx4 v[130:131], off
	s_mov_b32 m0, s22
	v_readfirstlane_b32 s22, v5
	global_load_lds_dwordx4 v[132:133], off
	v_lshl_add_u64 v[2:3], v[120:121], 0, 64
	s_mov_b32 m0, s22
	v_readfirstlane_b32 s22, v4
	global_load_lds_dwordx4 v[2:3], off
	s_mov_b32 m0, s22
	s_lshl_b32 s22, s2, 14
	v_lshl_add_u64 v[2:3], v[120:121], 0, s[76:77]
	s_add_i32 s22, s22, 0
	v_mfma_f32_16x16x32_bf16 v[102:105], v[126:129], v[102:105], v[10:13]
	global_load_lds_dwordx4 v[2:3], off
	v_add3_u32 v18, s22, v123, v0
	s_nop 0
	v_add3_u32 v10, s22, v124, v0
	v_mfma_f32_16x16x32_bf16 v[98:101], v[126:129], v[98:101], v[14:17]
	s_add_i32 s22, s2, 1
	s_cmp_lg_u32 s2, 2
	s_cselect_b32 s2, s22, 0
	v_mfma_f32_16x16x32_bf16 v[106:109], v[126:129], v[106:109], v[6:9]
	s_setprio 0
	ds_read_b128 v[2:5], v10 offset:8192
	s_nop 1
	ds_read_b128 v[6:9], v10 offset:9216
	ds_read_b128 v[126:129], v10 offset:10240
	ds_read_b128 v[130:133], v10 offset:11264
	s_add_i32 s22, s21, 1
	ds_read_b128 v[10:13], v18
	ds_read_b128 v[14:17], v18 offset:1024
	ds_read_b128 v[134:137], v18 offset:2048
	ds_read_b128 v[138:141], v18 offset:3072
	s_cmp_lg_u32 s21, 2
	s_cselect_b32 s21, s22, 0
	s_waitcnt lgkmcnt(0)
	s_setprio 1
	v_mfma_f32_16x16x32_bf16 v[50:53], v[10:13], v[130:133], v[66:69]
	s_setprio 0
	s_waitcnt vmcnt(4) lgkmcnt(0)
	s_barrier
	s_setprio 1
	v_mfma_f32_16x16x32_bf16 v[62:65], v[10:13], v[2:5], v[30:33]
	s_nop 0
	v_lshl_add_u32 v66, s21, 14, v122
	v_add_u32_e32 v67, 0x1000, v66
	v_readfirstlane_b32 s22, v66
	v_add_u32_e32 v69, 0x2000, v66
	s_mov_b32 m0, s22
	v_readfirstlane_b32 s22, v67
	v_add_u32_e32 v68, 0x3000, v66
	global_load_lds_dwordx4 v[142:143], off
	s_mov_b32 m0, s22
	v_readfirstlane_b32 s22, v69
	global_load_lds_dwordx4 v[144:145], off
	v_lshl_add_u64 v[66:67], v[120:121], 0, s[78:79]
	s_mov_b32 m0, s22
	v_readfirstlane_b32 s22, v68
	global_load_lds_dwordx4 v[66:67], off
	v_lshl_add_u64 v[66:67], v[120:121], 0, s[96:97]
	s_mov_b32 m0, s22
	s_lshl_b32 s22, s2, 14
	global_load_lds_dwordx4 v[66:67], off
	s_add_i32 s22, s22, 0
	v_add3_u32 v66, s22, v124, v0
	v_mfma_f32_16x16x32_bf16 v[58:61], v[10:13], v[6:9], v[34:37]
	v_mfma_f32_16x16x32_bf16 v[54:57], v[10:13], v[126:129], v[38:41]
	v_mfma_f32_16x16x32_bf16 v[22:25], v[14:17], v[2:5], v[70:73]
	v_mfma_f32_16x16x32_bf16 v[26:29], v[14:17], v[6:9], v[74:77]
	v_mfma_f32_16x16x32_bf16 v[42:45], v[14:17], v[126:129], v[78:81]
	v_mfma_f32_16x16x32_bf16 v[46:49], v[14:17], v[130:133], v[46:49]
	v_mfma_f32_16x16x32_bf16 v[10:13], v[134:137], v[2:5], v[82:85]
	v_mfma_f32_16x16x32_bf16 v[14:17], v[134:137], v[6:9], v[86:89]
	v_mfma_f32_16x16x32_bf16 v[18:21], v[134:137], v[126:129], v[90:93]
	s_setprio 0
	ds_read_b128 v[78:81], v66 offset:8192
	ds_read_b128 v[82:85], v66 offset:9216
	ds_read_b128 v[86:89], v66 offset:10240
	ds_read_b128 v[90:93], v66 offset:11264
	v_add3_u32 v66, s22, v123, v0
	s_add_i32 s22, s2, 1
	s_setprio 1
	v_mfma_f32_16x16x32_bf16 v[38:41], v[134:137], v[130:133], v[94:97]
	s_cmp_lg_u32 s2, 2
	s_cselect_b32 s2, s22, 0
	s_add_i32 s22, s21, 1
	v_mfma_f32_16x16x32_bf16 v[2:5], v[138:141], v[2:5], v[98:101]
	s_cmp_lg_u32 s21, 2
	s_cselect_b32 s21, s22, 0
	s_add_u32 s18, s18, 0xc0
	v_mfma_f32_16x16x32_bf16 v[6:9], v[138:141], v[6:9], v[102:105]
	s_addc_u32 s19, s19, 0
	s_cmpk_eq_i32 s18, 0x780
	v_mfma_f32_16x16x32_bf16 v[30:33], v[138:141], v[126:129], v[106:109]
	s_setprio 0
	ds_read_b128 v[94:97], v66
	ds_read_b128 v[98:101], v66 offset:1024
	ds_read_b128 v[102:105], v66 offset:2048
	ds_read_b128 v[106:109], v66 offset:3072
	s_setprio 1
	v_mfma_f32_16x16x32_bf16 v[34:37], v[138:141], v[130:133], v[110:113]
	s_setprio 0
	s_waitcnt lgkmcnt(0)
	s_setprio 1
	v_mfma_f32_16x16x32_bf16 v[74:77], v[94:97], v[78:81], v[62:65]
	v_mfma_f32_16x16x32_bf16 v[70:73], v[94:97], v[82:85], v[58:61]
	v_mfma_f32_16x16x32_bf16 v[66:69], v[94:97], v[86:89], v[54:57]
	v_mfma_f32_16x16x32_bf16 v[62:65], v[94:97], v[90:93], v[50:53]
	v_mfma_f32_16x16x32_bf16 v[58:61], v[98:101], v[78:81], v[22:25]
	v_mfma_f32_16x16x32_bf16 v[54:57], v[98:101], v[82:85], v[26:29]
	v_mfma_f32_16x16x32_bf16 v[50:53], v[98:101], v[86:89], v[42:45]
	v_mfma_f32_16x16x32_bf16 v[46:49], v[98:101], v[90:93], v[46:49]
	v_mfma_f32_16x16x32_bf16 v[42:45], v[102:105], v[78:81], v[10:13]
	v_mfma_f32_16x16x32_bf16 v[26:29], v[102:105], v[82:85], v[14:17]
	v_mfma_f32_16x16x32_bf16 v[22:25], v[102:105], v[86:89], v[18:21]
	v_mfma_f32_16x16x32_bf16 v[18:21], v[102:105], v[90:93], v[38:41]
	v_mfma_f32_16x16x32_bf16 v[14:17], v[106:109], v[78:81], v[2:5]
	v_mfma_f32_16x16x32_bf16 v[10:13], v[106:109], v[82:85], v[6:9]
	v_mfma_f32_16x16x32_bf16 v[6:9], v[106:109], v[86:89], v[30:33]
	v_mfma_f32_16x16x32_bf16 v[2:5], v[106:109], v[90:93], v[34:37]
	s_setprio 0
	s_cbranch_scc0 .LBB0_450
	s_waitcnt vmcnt(4) lgkmcnt(0)
	s_barrier
	v_add3_u32 v98, 0, v124, v0
	v_add3_u32 v0, 0, v123, v0
	ds_read_b128 v[30:33], v98 offset:8192
	ds_read_b128 v[34:37], v98 offset:9216
	ds_read_b128 v[38:41], v98 offset:10240
	ds_read_b128 v[78:81], v98 offset:11264
	ds_read_b128 v[82:85], v0
	ds_read_b128 v[86:89], v0 offset:1024
	ds_read_b128 v[90:93], v0 offset:2048
	ds_read_b128 v[94:97], v0 offset:3072
	s_waitcnt vmcnt(0) lgkmcnt(0)
	s_barrier
	s_waitcnt lgkmcnt(0)
	v_mfma_f32_16x16x32_bf16 v[74:77], v[82:85], v[30:33], v[74:77]
	s_mul_hi_u32 s2, s17, 0x840000
	s_mul_i32 s17, s17, 0x840000
	s_add_u32 s18, s40, s17
	v_mfma_f32_16x16x32_bf16 v[70:73], v[82:85], v[34:37], v[70:73]
	s_mov_b32 s17, s3
	s_addc_u32 s2, s41, s2
	s_lshl_b64 s[16:17], s[16:17], 1
	v_mfma_f32_16x16x32_bf16 v[66:69], v[82:85], v[38:41], v[66:69]
	s_add_u32 s16, s18, s16
	s_addc_u32 s17, s2, s17
	s_movk_i32 s2, 0x4200
	v_mfma_f32_16x16x32_bf16 v[62:65], v[82:85], v[78:81], v[62:65]
	v_mfma_f32_16x16x32_bf16 v[58:61], v[86:89], v[30:33], v[58:61]
	v_mfma_f32_16x16x32_bf16 v[54:57], v[86:89], v[34:37], v[54:57]
	v_mfma_f32_16x16x32_bf16 v[50:53], v[86:89], v[38:41], v[50:53]
	v_mfma_f32_16x16x32_bf16 v[46:49], v[86:89], v[78:81], v[46:49]
	v_mfma_f32_16x16x32_bf16 v[42:45], v[90:93], v[30:33], v[42:45]
	v_mfma_f32_16x16x32_bf16 v[26:29], v[90:93], v[34:37], v[26:29]
	v_mfma_f32_16x16x32_bf16 v[22:25], v[90:93], v[38:41], v[22:25]
	v_mfma_f32_16x16x32_bf16 v[18:21], v[90:93], v[78:81], v[18:21]
	v_mfma_f32_16x16x32_bf16 v[14:17], v[94:97], v[30:33], v[14:17]
	v_mfma_f32_16x16x32_bf16 v[10:13], v[94:97], v[34:37], v[10:13]
	v_mfma_f32_16x16x32_bf16 v[6:9], v[94:97], v[38:41], v[6:9]
	v_mfma_f32_16x16x32_bf16 v[2:5], v[94:97], v[78:81], v[2:5]
	ds_read_b128 v[30:33], v98 offset:24576
	ds_read_b128 v[34:37], v98 offset:25600
	ds_read_b128 v[38:41], v98 offset:26624
	ds_read_b128 v[78:81], v98 offset:27648
	ds_read_b128 v[82:85], v0 offset:16384
	ds_read_b128 v[86:89], v0 offset:17408
	ds_read_b128 v[90:93], v0 offset:18432
	ds_read_b128 v[94:97], v0 offset:19456
	s_waitcnt vmcnt(0) lgkmcnt(0)
	s_barrier
	v_mfma_f32_16x16x32_bf16 v[74:77], v[82:85], v[30:33], v[74:77]
	v_mfma_f32_16x16x32_bf16 v[58:61], v[86:89], v[30:33], v[58:61]
	v_mfma_f32_16x16x32_bf16 v[70:73], v[82:85], v[34:37], v[70:73]
	v_mfma_f32_16x16x32_bf16 v[66:69], v[82:85], v[38:41], v[66:69]
	v_mfma_f32_16x16x32_bf16 v[54:57], v[86:89], v[34:37], v[54:57]
	v_mfma_f32_16x16x32_bf16 v[50:53], v[86:89], v[38:41], v[50:53]
	v_mfma_f32_16x16x32_bf16 v[22:25], v[90:93], v[38:41], v[22:25]
	v_mfma_f32_16x16x32_bf16 v[6:9], v[94:97], v[38:41], v[6:9]
	v_mov_b32_e32 v40, v196
	s_nop 0
	v_cvt_pk_bf16_f32 v38, v58, v59
	v_mfma_f32_16x16x32_bf16 v[42:45], v[90:93], v[30:33], v[42:45]
	v_and_b32_e32 v0, 0x4f, v40
	v_mul_u32_u24_e32 v0, 0x110, v0
	v_cvt_pk_bf16_f32 v39, v60, v61
	v_mfma_f32_16x16x32_bf16 v[14:17], v[94:97], v[30:33], v[14:17]
	v_lshrrev_b32_e32 v30, 1, v40
	v_and_b32_e32 v31, 0xffffff80, v40
	v_add_u32_e32 v32, 0, v31
	v_mfma_f32_16x16x32_bf16 v[62:65], v[82:85], v[78:81], v[62:65]
	v_and_b32_e32 v33, 24, v30
	v_cvt_pk_bf16_f32 v30, v74, v75
	v_cvt_pk_bf16_f32 v31, v76, v77
	v_mfma_f32_16x16x32_bf16 v[46:49], v[86:89], v[78:81], v[46:49]
	v_add3_u32 v0, v32, v33, v0
	v_cvt_pk_bf16_f32 v32, v70, v71
	v_cvt_pk_bf16_f32 v33, v72, v73
	ds_write2_b64 v0, v[30:31], v[38:39] offset1:4
	v_cvt_pk_bf16_f32 v30, v54, v55
	v_cvt_pk_bf16_f32 v31, v56, v57
	v_add_u32_e32 v38, 0x1000, v0
	v_mfma_f32_16x16x32_bf16 v[26:29], v[90:93], v[34:37], v[26:29]
	ds_write2_b64 v38, v[32:33], v[30:31] offset0:32 offset1:36
	v_cvt_pk_bf16_f32 v30, v50, v51
	v_cvt_pk_bf16_f32 v31, v52, v53
	v_mfma_f32_16x16x32_bf16 v[10:13], v[94:97], v[34:37], v[10:13]
	v_cvt_pk_bf16_f32 v34, v66, v67
	v_cvt_pk_bf16_f32 v35, v68, v69
	v_add_u32_e32 v32, 0x2000, v0
	v_mfma_f32_16x16x32_bf16 v[18:21], v[90:93], v[78:81], v[18:21]
	v_cvt_pk_bf16_f32 v36, v62, v63
	v_cvt_pk_bf16_f32 v37, v64, v65
	ds_write2_b64 v32, v[34:35], v[30:31] offset0:64 offset1:68
	v_mfma_f32_16x16x32_bf16 v[2:5], v[94:97], v[78:81], v[2:5]
	v_cvt_pk_bf16_f32 v30, v46, v47
	v_cvt_pk_bf16_f32 v31, v48, v49
	v_add_u32_e32 v33, 0x3000, v0
	ds_write2_b64 v33, v[36:37], v[30:31] offset0:96 offset1:100
	v_cvt_pk_bf16_f32 v30, v42, v43
	v_cvt_pk_bf16_f32 v31, v44, v45
	v_cvt_pk_bf16_f32 v14, v14, v15
	v_cvt_pk_bf16_f32 v15, v16, v17
	ds_write2_b64 v0, v[30:31], v[14:15] offset0:8 offset1:12
	v_lshlrev_b32_e32 v0, 4, v40
	v_cvt_pk_bf16_f32 v22, v22, v23
	v_cvt_pk_bf16_f32 v23, v24, v25
	v_cvt_pk_bf16_f32 v6, v6, v7
	v_cvt_pk_bf16_f32 v7, v8, v9
	v_and_b32_e32 v0, 0xf0, v0
	v_cvt_pk_bf16_f32 v18, v18, v19
	v_cvt_pk_bf16_f32 v19, v20, v21
	ds_write2_b64 v32, v[22:23], v[6:7] offset0:72 offset1:76
	v_cvt_pk_bf16_f32 v2, v2, v3
	v_cvt_pk_bf16_f32 v3, v4, v5
	v_lshl_add_u64 v[6:7], s[16:17], 0, v[0:1]
	v_add_u32_e32 v0, 0, v0
	v_ashrrev_i32_e32 v4, 4, v40
	ds_write2_b64 v33, v[18:19], v[2:3] offset0:104 offset1:108
	v_mad_u64_u32 v[2:3], s[16:17], v4, s30, v[0:1]
	v_cvt_pk_bf16_f32 v26, v26, v27
	v_cvt_pk_bf16_f32 v27, v28, v29
	v_cvt_pk_bf16_f32 v10, v10, v11
	v_cvt_pk_bf16_f32 v11, v12, v13
	v_add_u32_e32 v3, s20, v4
	ds_write2_b64 v38, v[26:27], v[10:11] offset0:40 offset1:44
	s_waitcnt lgkmcnt(0)
	s_barrier
	v_mad_i64_i32 v[8:9], s[16:17], v3, s2, v[6:7]
	ds_read_b128 v[2:5], v2
	s_waitcnt lgkmcnt(0)
	global_store_dwordx4 v[8:9], v[2:5], off
	s_nop 1
	v_add_u32_e32 v2, 0x100, v40
	v_ashrrev_i32_e32 v4, 4, v2
	v_mad_u64_u32 v[2:3], s[16:17], v4, s30, v[0:1]
	v_add_u32_e32 v3, s20, v4
	v_mad_i64_i32 v[8:9], s[16:17], v3, s2, v[6:7]
	ds_read_b128 v[2:5], v2
	s_waitcnt lgkmcnt(0)
	global_store_dwordx4 v[8:9], v[2:5], off
	s_nop 1
	v_add_u32_e32 v2, 0x200, v40
	v_ashrrev_i32_e32 v4, 4, v2
	v_mad_u64_u32 v[2:3], s[16:17], v4, s30, v[0:1]
	v_add_u32_e32 v3, s20, v4
	v_mad_i64_i32 v[8:9], s[16:17], v3, s2, v[6:7]
	ds_read_b128 v[2:5], v2
	s_waitcnt lgkmcnt(0)
	global_store_dwordx4 v[8:9], v[2:5], off
	s_nop 1
	v_add_u32_e32 v2, 0x300, v40
	v_ashrrev_i32_e32 v4, 4, v2
	v_mad_u64_u32 v[2:3], s[16:17], v4, s30, v[0:1]
	v_add_u32_e32 v3, s20, v4
	v_mad_i64_i32 v[8:9], s[16:17], v3, s2, v[6:7]
	ds_read_b128 v[2:5], v2
	s_waitcnt lgkmcnt(0)
	global_store_dwordx4 v[8:9], v[2:5], off
	s_nop 1
	v_add_u32_e32 v2, 0x400, v40
	v_ashrrev_i32_e32 v4, 4, v2
	v_mad_u64_u32 v[2:3], s[16:17], v4, s30, v[0:1]
	v_add_u32_e32 v3, s20, v4
	v_mad_i64_i32 v[8:9], s[16:17], v3, s2, v[6:7]
	ds_read_b128 v[2:5], v2
	s_waitcnt lgkmcnt(0)
	global_store_dwordx4 v[8:9], v[2:5], off
	s_nop 1
	v_add_u32_e32 v2, 0x500, v40
	v_ashrrev_i32_e32 v4, 4, v2
	v_mad_u64_u32 v[2:3], s[16:17], v4, s30, v[0:1]
	v_add_u32_e32 v3, s20, v4
	v_mad_i64_i32 v[8:9], s[16:17], v3, s2, v[6:7]
	ds_read_b128 v[2:5], v2
	s_waitcnt lgkmcnt(0)
	global_store_dwordx4 v[8:9], v[2:5], off
	s_nop 1
	v_add_u32_e32 v2, 0x600, v40
	v_ashrrev_i32_e32 v4, 4, v2
	v_mad_u64_u32 v[2:3], s[16:17], v4, s30, v[0:1]
	v_add_u32_e32 v3, s20, v4
	v_mad_i64_i32 v[8:9], s[16:17], v3, s2, v[6:7]
	ds_read_b128 v[2:5], v2
	s_waitcnt lgkmcnt(0)
	global_store_dwordx4 v[8:9], v[2:5], off
	s_nop 1
	v_add_u32_e32 v2, 0x700, v40
	v_ashrrev_i32_e32 v4, 4, v2
	v_mad_u64_u32 v[2:3], s[16:17], v4, s30, v[0:1]
	v_add_u32_e32 v0, s20, v4
	ds_read_b128 v[2:5], v2
	v_mad_i64_i32 v[6:7], s[16:17], v0, s2, v[6:7]
	s_mov_b64 s[16:17], 0
	s_waitcnt lgkmcnt(0)
	global_store_dwordx4 v[6:7], v[2:5], off
	s_barrier

.LBB0_458:
	s_mul_i32 s23, s19, 0x6000
	v_add_u32_e32 v136, s23, v156
	v_add_u32_e32 v137, 0x1000, v136
	v_readfirstlane_b32 s23, v136
	s_waitcnt vmcnt(6) lgkmcnt(0)
	s_barrier
	s_mov_b32 m0, s23
	v_readfirstlane_b32 s23, v137
	v_add_u32_e32 v137, 0x2000, v136
	global_load_lds_dwordx4 v[148:149], off
	s_mov_b32 m0, s23
	v_readfirstlane_b32 s23, v137
	v_add_u32_e32 v137, 0x3000, v136
	global_load_lds_dwordx4 v[150:151], off
	s_mov_b32 m0, s23
	v_readfirstlane_b32 s23, v137
	v_add_u32_e32 v137, 0x4000, v136
	v_lshl_add_u64 v[130:131], v[154:155], 0, s[20:21]
	global_load_lds_dwordx4 v[152:153], off
	s_mov_b32 m0, s23
	v_readfirstlane_b32 s23, v137
	v_lshl_add_u64 v[134:135], v[130:131], 0, s[78:79]
	global_load_lds_dwordx4 v[146:147], off
	s_mov_b32 m0, s23
	v_lshl_add_u64 v[132:133], v[130:131], 0, s[96:97]
	global_load_lds_dwordx4 v[134:135], off
	v_add_u32_e32 v134, 0x5000, v136
	v_lshl_add_u64 v[140:141], v[148:149], 0, 64
	v_readfirstlane_b32 s23, v134
	s_mov_b32 m0, s23
	s_mul_i32 s23, s22, 0x6000
	s_add_i32 s23, s23, 0
	global_load_lds_dwordx4 v[132:133], off
	v_add3_u32 v159, s23, v157, v0
	ds_read_b128 v[142:145], v159 offset:16384
	ds_read_b128 v[160:163], v159 offset:17408
	ds_read_b128 v[164:167], v159 offset:18432
	ds_read_b128 v[168:171], v159 offset:19456
	v_add3_u32 v159, s23, v158, v0
	ds_read_b128 v[172:175], v159
	ds_read_b128 v[176:179], v159 offset:1024
	ds_read_b128 v[180:183], v159 offset:2048
	ds_read_b128 v[184:187], v159 offset:3072
	s_add_i32 s23, s22, 1
	s_waitcnt lgkmcnt(0)
	s_setprio 1
	v_mfma_f32_16x16x32_bf16 v[126:129], v[142:145], v[172:175], v[126:129]
	s_cmp_lg_u32 s22, 2
	s_cselect_b32 s22, s23, 0
	s_add_i32 s23, s19, 1
	v_mfma_f32_16x16x32_bf16 v[122:125], v[160:163], v[172:175], v[122:125]
	s_cmp_lg_u32 s19, 2
	s_cselect_b32 s19, s23, 0
	s_mul_i32 s23, s19, 0x6000
	v_mfma_f32_16x16x32_bf16 v[118:121], v[164:167], v[172:175], v[118:121]
	v_lshl_add_u64 v[138:139], v[150:151], 0, 64
	v_lshl_add_u64 v[136:137], v[152:153], 0, 64
	v_lshl_add_u64 v[134:135], v[146:147], 0, 64
	v_mfma_f32_16x16x32_bf16 v[114:117], v[168:171], v[172:175], v[114:117]
	v_lshl_add_u64 v[132:133], v[130:131], 0, s[84:85]
	v_lshl_add_u64 v[130:131], v[130:131], 0, s[24:25]
	v_lshl_add_u64 v[148:149], v[148:149], 0, s[78:79]
	v_mfma_f32_16x16x32_bf16 v[110:113], v[142:145], v[176:179], v[110:113]
	v_lshl_add_u64 v[150:151], v[150:151], 0, s[78:79]
	v_lshl_add_u64 v[152:153], v[152:153], 0, s[78:79]
	v_lshl_add_u64 v[146:147], v[146:147], 0, s[78:79]
	v_mfma_f32_16x16x32_bf16 v[106:109], v[160:163], v[176:179], v[106:109]
	v_mfma_f32_16x16x32_bf16 v[102:105], v[164:167], v[176:179], v[102:105]
	v_mfma_f32_16x16x32_bf16 v[98:101], v[168:171], v[176:179], v[98:101]
	v_mfma_f32_16x16x32_bf16 v[94:97], v[142:145], v[180:183], v[94:97]
	v_mfma_f32_16x16x32_bf16 v[90:93], v[160:163], v[180:183], v[90:93]
	v_mfma_f32_16x16x32_bf16 v[86:89], v[164:167], v[180:183], v[86:89]
	v_mfma_f32_16x16x32_bf16 v[82:85], v[168:171], v[180:183], v[82:85]
	v_mfma_f32_16x16x32_bf16 v[78:81], v[142:145], v[184:187], v[78:81]
	v_mfma_f32_16x16x32_bf16 v[74:77], v[160:163], v[184:187], v[74:77]
	v_mfma_f32_16x16x32_bf16 v[70:73], v[164:167], v[184:187], v[70:73]
	v_mfma_f32_16x16x32_bf16 v[62:65], v[168:171], v[184:187], v[62:65]
	s_setprio 0
	ds_read_b128 v[172:175], v159 offset:4096
	ds_read_b128 v[176:179], v159 offset:5120
	ds_read_b128 v[180:183], v159 offset:6144
	ds_read_b128 v[184:187], v159 offset:7168
	s_waitcnt vmcnt(6) lgkmcnt(0)
	s_barrier
	s_waitcnt lgkmcnt(0)
	s_setprio 1
	v_mfma_f32_16x16x32_bf16 v[66:69], v[142:145], v[172:175], v[66:69]
	s_setprio 0
	s_setprio 1
	v_mfma_f32_16x16x32_bf16 v[46:49], v[142:145], v[176:179], v[46:49]
	v_mfma_f32_16x16x32_bf16 v[34:37], v[142:145], v[180:183], v[34:37]
	v_mfma_f32_16x16x32_bf16 v[14:17], v[142:145], v[184:187], v[14:17]
	v_add_u32_e32 v142, s23, v156
	s_nop 0
	v_readfirstlane_b32 s23, v142
	s_mov_b32 m0, s23
	v_mfma_f32_16x16x32_bf16 v[58:61], v[160:163], v[172:175], v[58:61]
	global_load_lds_dwordx4 v[140:141], off
	v_add_u32_e32 v140, 0x1000, v142
	v_mfma_f32_16x16x32_bf16 v[54:57], v[164:167], v[172:175], v[54:57]
	v_readfirstlane_b32 s23, v140
	s_mov_b32 m0, s23
	s_nop 0
	global_load_lds_dwordx4 v[138:139], off
	v_add_u32_e32 v138, 0x2000, v142
	v_mfma_f32_16x16x32_bf16 v[50:53], v[168:171], v[172:175], v[50:53]
	v_readfirstlane_b32 s23, v138
	s_mov_b32 m0, s23
	s_nop 0
	global_load_lds_dwordx4 v[136:137], off
	v_add_u32_e32 v136, 0x3000, v142
	v_mfma_f32_16x16x32_bf16 v[42:45], v[160:163], v[176:179], v[42:45]
	v_readfirstlane_b32 s23, v136
	s_mov_b32 m0, s23
	s_nop 0
	global_load_lds_dwordx4 v[134:135], off
	v_add_u32_e32 v134, 0x4000, v142
	v_mfma_f32_16x16x32_bf16 v[38:41], v[164:167], v[176:179], v[38:41]
	v_readfirstlane_b32 s23, v134
	s_mov_b32 m0, s23
	s_nop 0
	global_load_lds_dwordx4 v[132:133], off
	v_add_u32_e32 v132, 0x5000, v142
	v_mfma_f32_16x16x32_bf16 v[30:33], v[168:171], v[176:179], v[30:33]
	v_readfirstlane_b32 s23, v132
	s_mov_b32 m0, s23
	s_mul_i32 s23, s22, 0x6000
	global_load_lds_dwordx4 v[130:131], off
	s_add_i32 s23, s23, 0
	v_add3_u32 v142, s23, v157, v0
	v_add3_u32 v159, s23, v158, v0
	v_mfma_f32_16x16x32_bf16 v[26:29], v[160:163], v[180:183], v[26:29]
	s_setprio 0
	ds_read_b128 v[130:133], v142 offset:16384
	ds_read_b128 v[134:137], v142 offset:17408
	ds_read_b128 v[138:141], v142 offset:18432
	ds_read_b128 v[142:145], v142 offset:19456
	s_add_i32 s23, s22, 1
	s_cmp_lg_u32 s22, 2
	s_setprio 1
	v_mfma_f32_16x16x32_bf16 v[22:25], v[164:167], v[180:183], v[22:25]
	s_cselect_b32 s22, s23, 0
	s_add_i32 s23, s19, 1
	s_cmp_lg_u32 s19, 2
	v_mfma_f32_16x16x32_bf16 v[18:21], v[168:171], v[180:183], v[18:21]
	s_cselect_b32 s19, s23, 0
	s_add_u32 s20, s20, 0x80
	s_addc_u32 s21, s21, 0
	v_mfma_f32_16x16x32_bf16 v[10:13], v[160:163], v[184:187], v[10:13]
	s_cmpk_eq_i32 s20, 0x780
	v_mfma_f32_16x16x32_bf16 v[6:9], v[164:167], v[184:187], v[6:9]
	v_mfma_f32_16x16x32_bf16 v[2:5], v[168:171], v[184:187], v[2:5]
	s_setprio 0
	ds_read_b128 v[160:163], v159
	ds_read_b128 v[164:167], v159 offset:1024
	ds_read_b128 v[168:171], v159 offset:2048
	ds_read_b128 v[172:175], v159 offset:3072
	s_waitcnt lgkmcnt(0)
	s_setprio 1
	v_mfma_f32_16x16x32_bf16 v[126:129], v[130:133], v[160:163], v[126:129]
	v_mfma_f32_16x16x32_bf16 v[122:125], v[134:137], v[160:163], v[122:125]
	v_mfma_f32_16x16x32_bf16 v[118:121], v[138:141], v[160:163], v[118:121]
	v_mfma_f32_16x16x32_bf16 v[114:117], v[142:145], v[160:163], v[114:117]
	v_mfma_f32_16x16x32_bf16 v[110:113], v[130:133], v[164:167], v[110:113]
	v_mfma_f32_16x16x32_bf16 v[106:109], v[134:137], v[164:167], v[106:109]
	v_mfma_f32_16x16x32_bf16 v[102:105], v[138:141], v[164:167], v[102:105]
	v_mfma_f32_16x16x32_bf16 v[98:101], v[142:145], v[164:167], v[98:101]
	v_mfma_f32_16x16x32_bf16 v[94:97], v[130:133], v[168:171], v[94:97]
	v_mfma_f32_16x16x32_bf16 v[90:93], v[134:137], v[168:171], v[90:93]
	v_mfma_f32_16x16x32_bf16 v[86:89], v[138:141], v[168:171], v[86:89]
	v_mfma_f32_16x16x32_bf16 v[82:85], v[142:145], v[168:171], v[82:85]
	v_mfma_f32_16x16x32_bf16 v[78:81], v[130:133], v[172:175], v[78:81]
	v_mfma_f32_16x16x32_bf16 v[74:77], v[134:137], v[172:175], v[74:77]
	v_mfma_f32_16x16x32_bf16 v[70:73], v[138:141], v[172:175], v[70:73]
	v_mfma_f32_16x16x32_bf16 v[62:65], v[142:145], v[172:175], v[62:65]
	s_setprio 0
	ds_read_b128 v[160:163], v159 offset:4096
	ds_read_b128 v[164:167], v159 offset:5120
	ds_read_b128 v[168:171], v159 offset:6144
	ds_read_b128 v[172:175], v159 offset:7168
	s_waitcnt lgkmcnt(0)
	s_setprio 1
	v_mfma_f32_16x16x32_bf16 v[66:69], v[130:133], v[160:163], v[66:69]
	v_mfma_f32_16x16x32_bf16 v[58:61], v[134:137], v[160:163], v[58:61]
	v_mfma_f32_16x16x32_bf16 v[54:57], v[138:141], v[160:163], v[54:57]
	v_mfma_f32_16x16x32_bf16 v[50:53], v[142:145], v[160:163], v[50:53]
	v_mfma_f32_16x16x32_bf16 v[46:49], v[130:133], v[164:167], v[46:49]
	v_mfma_f32_16x16x32_bf16 v[42:45], v[134:137], v[164:167], v[42:45]
	v_mfma_f32_16x16x32_bf16 v[38:41], v[138:141], v[164:167], v[38:41]
	v_mfma_f32_16x16x32_bf16 v[30:33], v[142:145], v[164:167], v[30:33]
	v_mfma_f32_16x16x32_bf16 v[34:37], v[130:133], v[168:171], v[34:37]
	v_mfma_f32_16x16x32_bf16 v[26:29], v[134:137], v[168:171], v[26:29]
	v_mfma_f32_16x16x32_bf16 v[22:25], v[138:141], v[168:171], v[22:25]
	v_mfma_f32_16x16x32_bf16 v[18:21], v[142:145], v[168:171], v[18:21]
	v_mfma_f32_16x16x32_bf16 v[14:17], v[130:133], v[172:175], v[14:17]
	v_mfma_f32_16x16x32_bf16 v[10:13], v[134:137], v[172:175], v[10:13]
	v_mfma_f32_16x16x32_bf16 v[6:9], v[138:141], v[172:175], v[6:9]
	v_mfma_f32_16x16x32_bf16 v[2:5], v[142:145], v[172:175], v[2:5]
	s_setprio 0
	s_cbranch_scc0 .LBB0_458
	s_waitcnt vmcnt(6) lgkmcnt(0)
	s_barrier
	v_add3_u32 v190, 0, v157, v0
	ds_read_b128 v[130:133], v190 offset:16384
	ds_read_b128 v[138:141], v190 offset:17408
	ds_read_b128 v[142:145], v190 offset:18432
	ds_read_b128 v[146:149], v190 offset:19456
	v_add3_u32 v0, 0, v158, v0
	ds_read_b128 v[134:137], v0
	s_waitcnt lgkmcnt(0)
	v_mfma_f32_16x16x32_bf16 v[126:129], v[130:133], v[134:137], v[126:129]
	s_mov_b64 s[20:21], -1
	s_cmp_lg_u32 s2, 22
	v_mfma_f32_16x16x32_bf16 v[122:125], v[138:141], v[134:137], v[122:125]
	v_mfma_f32_16x16x32_bf16 v[118:121], v[142:145], v[134:137], v[118:121]
	v_mfma_f32_16x16x32_bf16 v[134:137], v[146:149], v[134:137], v[114:117]
	s_nop 2
	ds_read_b128 v[114:117], v0 offset:1024
	s_waitcnt lgkmcnt(0)
	v_mfma_f32_16x16x32_bf16 v[150:153], v[142:145], v[114:117], v[102:105]
	s_nop 2
	ds_read_b128 v[102:105], v0 offset:2048
	s_waitcnt lgkmcnt(0)
	v_mfma_f32_16x16x32_bf16 v[94:97], v[130:133], v[102:105], v[94:97]
	v_mfma_f32_16x16x32_bf16 v[90:93], v[138:141], v[102:105], v[90:93]
	v_mfma_f32_16x16x32_bf16 v[86:89], v[142:145], v[102:105], v[86:89]
	v_mfma_f32_16x16x32_bf16 v[82:85], v[146:149], v[102:105], v[82:85]
	ds_read_b128 v[102:105], v0 offset:3072
	s_waitcnt lgkmcnt(0)
	v_mfma_f32_16x16x32_bf16 v[78:81], v[130:133], v[102:105], v[78:81]
	v_mfma_f32_16x16x32_bf16 v[74:77], v[138:141], v[102:105], v[74:77]
	v_mfma_f32_16x16x32_bf16 v[70:73], v[142:145], v[102:105], v[70:73]
	v_mfma_f32_16x16x32_bf16 v[62:65], v[146:149], v[102:105], v[62:65]
	ds_read_b128 v[102:105], v0 offset:4096
	s_waitcnt lgkmcnt(0)
	v_mfma_f32_16x16x32_bf16 v[66:69], v[130:133], v[102:105], v[66:69]
	v_mfma_f32_16x16x32_bf16 v[58:61], v[138:141], v[102:105], v[58:61]
	v_mfma_f32_16x16x32_bf16 v[54:57], v[142:145], v[102:105], v[54:57]
	v_mfma_f32_16x16x32_bf16 v[50:53], v[146:149], v[102:105], v[50:53]
	ds_read_b128 v[102:105], v0 offset:5120
	s_waitcnt lgkmcnt(0)
	v_mfma_f32_16x16x32_bf16 v[158:161], v[146:149], v[102:105], v[30:33]
	s_nop 2
	ds_read_b128 v[30:33], v0 offset:6144
	s_waitcnt lgkmcnt(0)
	v_mfma_f32_16x16x32_bf16 v[174:177], v[146:149], v[30:33], v[18:21]
	s_nop 2
	ds_read_b128 v[18:21], v0 offset:7168
	s_waitcnt vmcnt(0) lgkmcnt(0)
	s_barrier
	ds_read_b128 v[178:181], v190 offset:40960
	ds_read_b128 v[182:185], v190 offset:41984
	ds_read_b128 v[186:189], v190 offset:43008
	ds_read_b128 v[190:193], v190 offset:44032
	v_mfma_f32_16x16x32_bf16 v[106:109], v[138:141], v[114:117], v[106:109]
	v_mfma_f32_16x16x32_bf16 v[42:45], v[138:141], v[102:105], v[42:45]
	v_mfma_f32_16x16x32_bf16 v[166:169], v[138:141], v[30:33], v[26:29]
	s_waitcnt lgkmcnt(0)
	v_mfma_f32_16x16x32_bf16 v[138:141], v[138:141], v[18:21], v[10:13]
	s_nop 0
	ds_read_b128 v[26:29], v0 offset:26624
	s_nop 0
	ds_read_b128 v[10:13], v0 offset:24576
	v_mfma_f32_16x16x32_bf16 v[110:113], v[130:133], v[114:117], v[110:113]
	v_mfma_f32_16x16x32_bf16 v[98:101], v[146:149], v[114:117], v[98:101]
	v_mfma_f32_16x16x32_bf16 v[46:49], v[130:133], v[102:105], v[46:49]
	v_mfma_f32_16x16x32_bf16 v[154:157], v[142:145], v[102:105], v[38:41]
	v_mfma_f32_16x16x32_bf16 v[170:173], v[142:145], v[30:33], v[22:25]
	v_mfma_f32_16x16x32_bf16 v[142:145], v[142:145], v[18:21], v[6:9]
	v_mfma_f32_16x16x32_bf16 v[146:149], v[146:149], v[18:21], v[2:5]
	s_waitcnt lgkmcnt(0)
	v_mfma_f32_16x16x32_bf16 v[2:5], v[178:181], v[10:13], v[126:129]
	v_mfma_f32_16x16x32_bf16 v[6:9], v[182:185], v[10:13], v[122:125]
	v_mfma_f32_16x16x32_bf16 v[114:117], v[186:189], v[10:13], v[118:121]
	v_mfma_f32_16x16x32_bf16 v[102:105], v[190:193], v[10:13], v[134:137]
	ds_read_b128 v[10:13], v0 offset:25600
	v_mfma_f32_16x16x32_bf16 v[162:165], v[130:133], v[30:33], v[34:37]
	v_mfma_f32_16x16x32_bf16 v[130:133], v[130:133], v[18:21], v[14:17]
	s_waitcnt lgkmcnt(0)
	v_mfma_f32_16x16x32_bf16 v[18:21], v[178:181], v[10:13], v[110:113]
	v_mfma_f32_16x16x32_bf16 v[22:25], v[182:185], v[10:13], v[106:109]
	v_mfma_f32_16x16x32_bf16 v[126:129], v[186:189], v[10:13], v[150:153]
	v_mfma_f32_16x16x32_bf16 v[122:125], v[190:193], v[10:13], v[98:101]
	v_mfma_f32_16x16x32_bf16 v[10:13], v[178:181], v[26:29], v[94:97]
	v_mfma_f32_16x16x32_bf16 v[14:17], v[182:185], v[26:29], v[90:93]
	v_mfma_f32_16x16x32_bf16 v[106:109], v[186:189], v[26:29], v[86:89]
	v_mfma_f32_16x16x32_bf16 v[98:101], v[190:193], v[26:29], v[82:85]
	ds_read_b128 v[26:29], v0 offset:27648
	s_nop 1
	ds_read_b128 v[82:85], v0 offset:31744
	s_waitcnt lgkmcnt(0)
	v_mfma_f32_16x16x32_bf16 v[110:113], v[190:193], v[26:29], v[62:65]
	s_nop 2
	ds_read_b128 v[62:65], v0 offset:28672
	s_waitcnt lgkmcnt(0)
	v_mfma_f32_16x16x32_bf16 v[30:33], v[182:185], v[62:65], v[58:61]
	s_nop 2
	ds_read_b128 v[58:61], v0 offset:29696
	v_mfma_f32_16x16x32_bf16 v[34:37], v[178:181], v[26:29], v[78:81]
	v_mfma_f32_16x16x32_bf16 v[86:89], v[186:189], v[62:65], v[54:57]
	v_mfma_f32_16x16x32_bf16 v[78:81], v[190:193], v[62:65], v[50:53]
	s_waitcnt lgkmcnt(0)
	v_mfma_f32_16x16x32_bf16 v[50:53], v[178:181], v[58:61], v[46:49]
	v_mfma_f32_16x16x32_bf16 v[54:57], v[182:185], v[58:61], v[42:45]
	v_mfma_f32_16x16x32_bf16 v[94:97], v[186:189], v[58:61], v[154:157]
	v_mfma_f32_16x16x32_bf16 v[90:93], v[190:193], v[58:61], v[158:161]
	ds_read_b128 v[58:61], v0 offset:30720
	s_waitcnt vmcnt(0) lgkmcnt(0)
	s_barrier
	v_mfma_f32_16x16x32_bf16 v[38:41], v[182:185], v[26:29], v[74:77]
	v_mfma_f32_16x16x32_bf16 v[118:121], v[186:189], v[26:29], v[70:73]
	v_mfma_f32_16x16x32_bf16 v[26:29], v[178:181], v[62:65], v[66:69]
	v_mfma_f32_16x16x32_bf16 v[42:45], v[178:181], v[58:61], v[162:165]
	v_mfma_f32_16x16x32_bf16 v[46:49], v[182:185], v[58:61], v[166:169]
	v_mfma_f32_16x16x32_bf16 v[70:73], v[186:189], v[58:61], v[170:173]
	v_mfma_f32_16x16x32_bf16 v[66:69], v[190:193], v[58:61], v[174:177]
	v_mfma_f32_16x16x32_bf16 v[58:61], v[178:181], v[82:85], v[130:133]
	v_mfma_f32_16x16x32_bf16 v[62:65], v[182:185], v[82:85], v[138:141]
	v_mfma_f32_16x16x32_bf16 v[74:77], v[186:189], v[82:85], v[142:145]
	v_mfma_f32_16x16x32_bf16 v[82:85], v[190:193], v[82:85], v[146:149]
	s_cbranch_scc0 .LBB0_470
	s_and_b32 s22, s18, 0x180
	s_cmp_gt_i32 s2, 3
	s_mov_b64 s[26:27], -1
	s_cbranch_scc0 .LBB0_466
	s_mov_b64 s[20:21], 0x200
	s_cmp_lt_u32 s2, 8
	s_mov_b64 s[24:25], s[4:5]
	s_mov_b32 s19, s22
	s_cbranch_scc1 .LBB0_465
	s_cmp_lt_u32 s2, 16
	s_mov_b64 s[24:25], s[6:7]
	s_mov_b32 s19, s22
	s_cbranch_scc1 .LBB0_465
	s_cmp_lt_u32 s2, 20
	s_mov_b64 s[24:25], s[8:9]
	s_mov_b32 s19, s22
	s_cbranch_scc1 .LBB0_465
	s_add_i32 s19, s18, 0xfffff600
	s_mov_b64 s[20:21], 0x100
	s_mov_b64 s[24:25], s[10:11]
